# GEMM epilogue rstd: no rsqrt range scaling; GEMM K-loop: first iteration peeled with SrcC=0 instead of 128 zero-fill moves per unit
# speedup vs baseline: 1.0339x; 1.0073x over previous
.LBB0_188:
	s_waitcnt vmcnt(9)
	v_mfma_f32_32x32x16_bf16 v[16:31], v[108:111], v[132:135], 0
	v_mov_b32_e32 v33, v51
	v_mul_f32_e64 v34, v174, v32
	v_mul_f32_e64 v35, v175, v33
	v_add_u32_e32 v148, v200, v150
	v_sub_f32_e32 v33, v34, v35
	v_mov_b32_e32 v34, v51
	v_mov_b32_e32 v35, v32
	v_pk_mul_f32 v[50:51], v[176:177], v[50:51] op_sel_hi:[1,0]
	v_pk_mul_f32 v[52:53], v[174:175], v[34:35]
	v_pk_fma_f32 v[188:189], v[172:173], v[48:49], v[50:51] neg_lo:[0,0,1] neg_hi:[0,0,1]
	v_pk_fma_f32 v[48:49], v[172:173], v[48:49], v[50:51] op_sel_hi:[1,0,1]
	v_mfma_f32_32x32x16_bf16 v[0:15], v[108:111], v[128:131], 0
	v_add_f32_e32 v186, v33, v16
	v_add_f32_e32 v16, v52, v53
	v_mov_b32_e32 v189, v49
	ds_write_b128 v148, v[108:111] offset:8192
	s_cmp_gt_i32 s24, 0
	s_cselect_b64 s[2:3], -1, 0
	s_or_b64 s[14:15], s[2:3], s[50:51]
	v_mfma_f32_32x32x16_bf16 v[48:63], v[108:111], v[136:139], 0
	s_nop 3
	v_mov_b32_e32 v190, v0
	v_mfma_f32_32x32x16_bf16 v[32:47], v[108:111], v[140:143], 0
	s_nop 5
	v_mov_b32_e32 v191, v48
	v_add_f32_e64 v108, v188, v190
	v_add_f32_e64 v109, v189, v191
	v_mul_f32_e64 v110, v172, v108
	v_mul_f32_e64 v111, v173, v109
	v_sub_f32_e32 v0, v110, v111
	v_pk_mul_f32 v[110:111], v[176:177], v[108:109]
	v_add_f32_e32 v16, v16, v32
	v_add_f32_e32 v0, v1, v0
	v_add_f32_e32 v1, v110, v111
	v_add_f32_e32 v110, v49, v1
	v_pk_mul_f32 v[48:49], v[178:179], v[16:17] op_sel_hi:[1,0]
	v_mov_b32_e32 v32, v17
	v_pk_fma_f32 v[188:189], v[174:175], v[186:187], v[48:49] neg_lo:[0,0,1] neg_hi:[0,0,1]
	v_pk_fma_f32 v[48:49], v[174:175], v[186:187], v[48:49] op_sel_hi:[1,0,1]
	s_nop 0
	v_mov_b32_e32 v189, v49
	v_pk_add_f32 v[32:33], v[32:33], v[188:189]
	s_nop 0
	v_pk_mul_f32 v[48:49], v[174:175], v[32:33]
	s_nop 0
	v_sub_f32_e32 v1, v48, v49
	v_pk_mul_f32 v[48:49], v[178:179], v[32:33]
	v_add_f32_e32 v189, v18, v1
	v_add_f32_e32 v1, v48, v49
	v_pk_mul_f32 v[48:49], v[176:177], v[110:111] op_sel_hi:[1,0]
	v_add_f32_e32 v191, v34, v1
	v_pk_fma_f32 v[192:193], v[172:173], v[0:1], v[48:49] neg_lo:[0,0,1] neg_hi:[0,0,1]
	v_pk_fma_f32 v[48:49], v[172:173], v[0:1], v[48:49] op_sel_hi:[1,0,1]
	v_mul_f32_e32 v213, v174, v189
	v_mov_b32_e32 v193, v49
	v_mov_b32_e32 v48, v2
	v_mov_b32_e32 v49, v50
	v_pk_add_f32 v[192:193], v[48:49], v[192:193]
	v_mul_f32_e32 v215, v175, v191
	v_pk_mul_f32 v[48:49], v[172:173], v[192:193]
	v_mov_b32_e32 v18, v3
	v_mov_b32_e32 v212, v48
	v_mov_b32_e32 v214, v49
	v_pk_add_f32 v[48:49], v[212:213], v[214:215] neg_lo:[0,1] neg_hi:[0,1]
	v_mov_b32_e32 v190, v193
	v_pk_add_f32 v[2:3], v[18:19], v[48:49]
	v_pk_mul_f32 v[18:19], v[180:181], v[190:191]
	v_mov_b32_e32 v188, v192
	v_pk_fma_f32 v[18:19], v[182:183], v[188:189], v[18:19]
	v_mov_b32_e32 v34, v51
	v_pk_add_f32 v[18:19], v[34:35], v[18:19]
	v_mov_b32_e32 v48, v4
	v_pk_mul_f32 v[34:35], v[182:183], v[18:19]
	v_mov_b32_e32 v49, v20
	v_pk_fma_f32 v[34:35], v[180:181], v[2:3], v[34:35] neg_lo:[0,0,1] neg_hi:[0,0,1]
	v_mov_b32_e32 v50, v52
	v_pk_add_f32 v[34:35], v[48:49], v[34:35]
	v_pk_mul_f32 v[48:49], v[180:181], v[18:19]
	v_mov_b32_e32 v51, v36
	v_pk_fma_f32 v[48:49], v[182:183], v[2:3], v[48:49]
	v_mov_b32_e32 v20, v5
	v_pk_add_f32 v[212:213], v[50:51], v[48:49]
	v_mov_b32_e32 v36, v53
	v_pk_mul_f32 v[48:49], v[182:183], v[212:213]
	v_pk_mul_f32 v[50:51], v[180:181], v[212:213]
	v_pk_fma_f32 v[48:49], v[180:181], v[34:35], v[48:49] neg_lo:[0,0,1] neg_hi:[0,0,1]
	v_pk_fma_f32 v[50:51], v[182:183], v[34:35], v[50:51]
	v_pk_add_f32 v[4:5], v[20:21], v[48:49]
	v_pk_add_f32 v[20:21], v[36:37], v[50:51]
	v_mov_b32_e32 v48, v6
	v_pk_mul_f32 v[36:37], v[182:183], v[20:21]
	v_mov_b32_e32 v49, v22
	v_pk_fma_f32 v[36:37], v[180:181], v[4:5], v[36:37] neg_lo:[0,0,1] neg_hi:[0,0,1]
	v_mov_b32_e32 v50, v54
	v_pk_add_f32 v[36:37], v[48:49], v[36:37]
	v_pk_mul_f32 v[48:49], v[180:181], v[20:21]
	v_mov_b32_e32 v51, v38
	v_pk_fma_f32 v[48:49], v[182:183], v[4:5], v[48:49]
	v_mov_b32_e32 v22, v7
	v_pk_add_f32 v[52:53], v[50:51], v[48:49]
	v_mov_b32_e32 v38, v55
	v_pk_mul_f32 v[48:49], v[182:183], v[52:53]
	v_mov_b32_e32 v214, v8
	v_pk_fma_f32 v[48:49], v[180:181], v[36:37], v[48:49] neg_lo:[0,0,1] neg_hi:[0,0,1]
	v_mov_b32_e32 v215, v24
	v_pk_add_f32 v[6:7], v[22:23], v[48:49]
	v_pk_mul_f32 v[22:23], v[180:181], v[52:53]
	v_mov_b32_e32 v48, v56
	v_pk_fma_f32 v[22:23], v[182:183], v[36:37], v[22:23]
	v_mov_b32_e32 v49, v40
	v_pk_add_f32 v[22:23], v[38:39], v[22:23]
	v_mov_b32_e32 v24, v9
	v_pk_mul_f32 v[38:39], v[180:181], v[22:23]
	v_pk_mul_f32 v[54:55], v[182:183], v[22:23]
	v_pk_fma_f32 v[38:39], v[182:183], v[6:7], v[38:39]
	v_pk_fma_f32 v[54:55], v[180:181], v[6:7], v[54:55] neg_lo:[0,0,1] neg_hi:[0,0,1]
	v_pk_add_f32 v[38:39], v[48:49], v[38:39]
	v_pk_add_f32 v[54:55], v[214:215], v[54:55]
	v_pk_mul_f32 v[48:49], v[182:183], v[38:39]
	v_pk_mul_f32 v[50:51], v[180:181], v[38:39]
	v_pk_fma_f32 v[48:49], v[180:181], v[54:55], v[48:49] neg_lo:[0,0,1] neg_hi:[0,0,1]
	v_mov_b32_e32 v40, v57
	v_pk_add_f32 v[8:9], v[24:25], v[48:49]
	v_pk_fma_f32 v[24:25], v[182:183], v[54:55], v[50:51]
	v_mov_b32_e32 v48, v10
	v_pk_add_f32 v[24:25], v[40:41], v[24:25]
	v_mov_b32_e32 v49, v26
	v_pk_mul_f32 v[40:41], v[182:183], v[24:25]
	v_mov_b32_e32 v50, v58
	v_pk_fma_f32 v[40:41], v[180:181], v[8:9], v[40:41] neg_lo:[0,0,1] neg_hi:[0,0,1]
	v_mov_b32_e32 v51, v42
	v_pk_add_f32 v[40:41], v[48:49], v[40:41]
	v_pk_mul_f32 v[48:49], v[180:181], v[24:25]
	v_mov_b32_e32 v26, v11
	v_pk_fma_f32 v[48:49], v[182:183], v[8:9], v[48:49]
	v_mov_b32_e32 v42, v59
	v_pk_add_f32 v[56:57], v[50:51], v[48:49]
	v_mov_b32_e32 v50, v60
	v_pk_mul_f32 v[48:49], v[182:183], v[56:57]
	v_mov_b32_e32 v51, v44
	v_pk_fma_f32 v[48:49], v[180:181], v[40:41], v[48:49] neg_lo:[0,0,1] neg_hi:[0,0,1]
	v_mov_b32_e32 v44, v61
	v_pk_add_f32 v[10:11], v[26:27], v[48:49]
	v_pk_mul_f32 v[26:27], v[180:181], v[56:57]
	v_mov_b32_e32 v48, v12
	v_pk_fma_f32 v[26:27], v[182:183], v[40:41], v[26:27]
	v_mov_b32_e32 v49, v28
	v_pk_add_f32 v[26:27], v[42:43], v[26:27]
	v_mov_b32_e32 v28, v13
	v_pk_mul_f32 v[42:43], v[182:183], v[26:27]
	v_cvt_pk_bf16_f32 v0, v108, v0
	v_pk_fma_f32 v[42:43], v[180:181], v[10:11], v[42:43] neg_lo:[0,0,1] neg_hi:[0,0,1]
	v_cvt_pk_bf16_f32 v1, v192, v2
	v_pk_add_f32 v[42:43], v[48:49], v[42:43]
	v_pk_mul_f32 v[48:49], v[180:181], v[26:27]
	v_cvt_pk_bf16_f32 v2, v186, v32
	v_pk_fma_f32 v[48:49], v[182:183], v[10:11], v[48:49]
	v_cvt_pk_bf16_f32 v3, v189, v3
	v_pk_add_f32 v[58:59], v[50:51], v[48:49]
	v_mov_b32_e32 v50, v62
	v_pk_mul_f32 v[48:49], v[182:183], v[58:59]
	v_mov_b32_e32 v51, v46
	v_pk_fma_f32 v[48:49], v[180:181], v[42:43], v[48:49] neg_lo:[0,0,1] neg_hi:[0,0,1]
	v_mov_b32_e32 v46, v63
	v_pk_add_f32 v[12:13], v[28:29], v[48:49]
	v_pk_mul_f32 v[28:29], v[180:181], v[58:59]
	v_mov_b32_e32 v48, v14
	v_pk_fma_f32 v[28:29], v[182:183], v[42:43], v[28:29]
	v_mov_b32_e32 v49, v30
	v_pk_add_f32 v[28:29], v[44:45], v[28:29]
	v_mov_b32_e32 v30, v15
	v_pk_mul_f32 v[44:45], v[182:183], v[28:29]
	ds_write2st64_b64 v207, v[0:1], v[2:3] offset1:4
	v_pk_fma_f32 v[44:45], v[180:181], v[12:13], v[44:45] neg_lo:[0,0,1] neg_hi:[0,0,1]
	v_cvt_pk_bf16_f32 v0, v35, v5
	v_pk_add_f32 v[44:45], v[48:49], v[44:45]
	v_pk_mul_f32 v[48:49], v[180:181], v[28:29]
	v_cvt_pk_bf16_f32 v1, v37, v7
	v_pk_fma_f32 v[48:49], v[182:183], v[12:13], v[48:49]
	v_pk_mov_b32 v[2:3], v[192:193], v[18:19] op_sel:[1,0]
	v_pk_add_f32 v[60:61], v[50:51], v[48:49]
	v_cvt_pk_bf16_f32 v5, v56, v26
	v_pk_mul_f32 v[14:15], v[180:181], v[60:61]
	v_pk_mul_f32 v[48:49], v[182:183], v[60:61]
	v_pk_fma_f32 v[14:15], v[182:183], v[44:45], v[14:15]
	v_pk_fma_f32 v[48:49], v[180:181], v[44:45], v[48:49] neg_lo:[0,0,1] neg_hi:[0,0,1]
	v_pk_add_f32 v[50:51], v[46:47], v[14:15]
	v_cvt_pk_bf16_f32 v14, v34, v4
	v_cvt_pk_bf16_f32 v15, v36, v6
	v_pk_add_f32 v[48:49], v[30:31], v[48:49]
	v_cvt_pk_bf16_f32 v30, v54, v8
	v_cvt_pk_bf16_f32 v31, v40, v10
	ds_write2st64_b64 v208, v[14:15], v[0:1] offset1:4
	v_cvt_pk_bf16_f32 v0, v55, v9
	v_cvt_pk_bf16_f32 v1, v41, v11
	v_cvt_pk_bf16_f32 v46, v42, v12
	v_cvt_pk_bf16_f32 v47, v44, v48
	ds_write2st64_b64 v209, v[30:31], v[0:1] offset1:4
	v_cvt_pk_bf16_f32 v0, v43, v13
	v_cvt_pk_bf16_f32 v1, v45, v49
	ds_write2st64_b64 v210, v[46:47], v[0:1] offset1:4
	v_cvt_pk_bf16_f32 v0, v109, v110
	v_cvt_pk_bf16_f32 v1, v2, v3
	v_cvt_pk_bf16_f32 v8, v16, v33
	v_cvt_pk_bf16_f32 v9, v191, v19
	v_cvt_pk_bf16_f32 v2, v212, v20
	v_cvt_pk_bf16_f32 v3, v52, v22
	ds_write2st64_b64 v207, v[0:1], v[8:9] offset0:8 offset1:12
	v_cvt_pk_bf16_f32 v0, v213, v21
	v_cvt_pk_bf16_f32 v1, v53, v23
	v_cvt_pk_bf16_f32 v4, v38, v24
	ds_write2st64_b64 v208, v[2:3], v[0:1] offset0:8 offset1:12
	v_cvt_pk_bf16_f32 v0, v39, v25
	v_cvt_pk_bf16_f32 v1, v57, v27
	v_cvt_pk_bf16_f32 v6, v58, v28
	v_cvt_pk_bf16_f32 v7, v60, v50
	ds_write2st64_b64 v209, v[4:5], v[0:1] offset0:8 offset1:12
	v_cvt_pk_bf16_f32 v0, v59, v29
	v_cvt_pk_bf16_f32 v1, v61, v51
	ds_write2st64_b64 v210, v[6:7], v[0:1] offset0:8 offset1:12
	s_waitcnt lgkmcnt(0)
	ds_read_b64_tr_b16 v[0:1], v151 offset:0
	ds_read_b64_tr_b16 v[2:3], v199 offset:0
	ds_read_b64_tr_b16 v[28:29], v151 offset:1024
	ds_read_b64_tr_b16 v[30:31], v199 offset:1024
	ds_read_b64_tr_b16 v[24:25], v151 offset:2048
	ds_read_b64_tr_b16 v[26:27], v199 offset:2048
	ds_read_b64_tr_b16 v[20:21], v151 offset:3072
	ds_read_b64_tr_b16 v[22:23], v199 offset:3072
	ds_read_b64_tr_b16 v[16:17], v151 offset:4096
	ds_read_b64_tr_b16 v[18:19], v199 offset:4096
	ds_read_b64_tr_b16 v[44:45], v151 offset:5120
	ds_read_b64_tr_b16 v[46:47], v199 offset:5120
	ds_read_b64_tr_b16 v[40:41], v151 offset:6144
	ds_read_b64_tr_b16 v[42:43], v199 offset:6144
	ds_read_b64_tr_b16 v[52:53], v151 offset:7168
	ds_read_b64_tr_b16 v[54:55], v199 offset:7168
	s_waitcnt lgkmcnt(0)
	s_nop 0
	v_mfma_f32_32x32x16_bf16 v[0:15], v[68:71], v[0:3], 0
	v_mfma_f32_32x32x16_bf16 v[0:15], v[64:67], v[28:31], v[0:15]
	v_mfma_f32_32x32x16_bf16 v[0:15], v[76:79], v[24:27], v[0:15]
	v_mfma_f32_32x32x16_bf16 v[0:15], v[72:75], v[20:23], v[0:15]
	v_mfma_f32_32x32x16_bf16 v[0:15], v[84:87], v[16:19], v[0:15]
	v_mfma_f32_32x32x16_bf16 v[0:15], v[80:83], v[44:47], v[0:15]
	v_mfma_f32_32x32x16_bf16 v[0:15], v[92:95], v[40:43], v[0:15]
	v_mfma_f32_32x32x16_bf16 v[0:15], v[88:91], v[52:55], v[0:15]
	s_and_saveexec_b64 s[2:3], s[14:15]
	s_cbranch_execz .LBB0_190
	s_nop 7
	v_add_u32_e32 v16, v200, v146
	v_add_u32_e32 v16, 0x2000, v16
	ds_read2_b64 v[16:19], v16 offset1:2
	s_waitcnt lgkmcnt(0)
	v_lshlrev_b32_e32 v10, 16, v19
	v_and_b32_e32 v11, 0xffff0000, v19
	v_pk_fma_f32 v[6:7], v[102:103], v[10:11], v[6:7]
	s_nop 0
	v_mul_f32_e32 v10, v7, v7
	v_fmaak_f32 v10, v240, v10, 0xc0135761
	v_mul_f32_e32 v11, v6, v6
	v_mul_f32_e32 v10, v7, v10
	v_fmaak_f32 v11, v240, v11, 0xc0135761
	v_mul_f32_e32 v11, v6, v11
	v_exp_f32_e32 v10, v10
	v_exp_f32_e32 v11, v11
	v_add_f32_e32 v8, 1.0, v10
	v_rcp_f32_e32 v9, v8
	v_add_f32_e32 v8, 1.0, v11
	v_lshlrev_b32_e32 v10, 16, v18
	v_and_b32_e32 v11, 0xffff0000, v18
	v_pk_fma_f32 v[4:5], v[100:101], v[10:11], v[4:5]
	v_and_b32_e32 v13, 0xffff0000, v17
	v_mul_f32_e32 v10, v5, v5
	v_fmaak_f32 v10, v240, v10, 0xc0135761
	v_mul_f32_e32 v11, v4, v4
	v_mul_f32_e32 v10, v5, v10
	v_fmaak_f32 v11, v240, v11, 0xc0135761
	v_mul_f32_e32 v11, v4, v11
	v_exp_f32_e32 v10, v10
	v_exp_f32_e32 v12, v11
	v_and_b32_e32 v15, 0xffff0000, v16
	v_add_f32_e32 v10, 1.0, v10
	v_rcp_f32_e32 v11, v10
	v_add_f32_e32 v10, 1.0, v12
	v_lshlrev_b32_e32 v12, 16, v17
	v_pk_fma_f32 v[2:3], v[98:99], v[12:13], v[2:3]
	v_rcp_f32_e32 v8, v8
	v_mul_f32_e32 v12, v3, v3
	v_fmaak_f32 v12, v240, v12, 0xc0135761
	v_mul_f32_e32 v13, v2, v2
	v_mul_f32_e32 v12, v3, v12
	v_fmaak_f32 v13, v240, v13, 0xc0135761
	v_mul_f32_e32 v13, v2, v13
	v_exp_f32_e32 v12, v12
	v_exp_f32_e32 v14, v13
	v_rcp_f32_e32 v10, v10
	v_add_f32_e32 v12, 1.0, v12
	v_rcp_f32_e32 v13, v12
	v_add_f32_e32 v12, 1.0, v14
	v_lshlrev_b32_e32 v14, 16, v16
	v_pk_fma_f32 v[0:1], v[96:97], v[14:15], v[0:1]
	v_rcp_f32_e32 v12, v12
	v_mul_f32_e32 v14, v1, v1
	v_fmaak_f32 v14, v240, v14, 0xc0135761
	v_mul_f32_e32 v15, v0, v0
	v_mul_f32_e32 v14, v1, v14
	v_fmaak_f32 v15, v240, v15, 0xc0135761
	v_mul_f32_e32 v15, v0, v15
	v_exp_f32_e32 v14, v14
	v_exp_f32_e32 v16, v15
	s_cmp_eq_u32 s24, 0
	v_add_f32_e32 v14, 1.0, v14
	v_rcp_f32_e32 v15, v14
	v_add_f32_e32 v14, 1.0, v16
	v_rcp_f32_e32 v14, v14
	s_cselect_b64 vcc, -1, 0
	v_pk_mul_f32 v[6:7], v[6:7], v[8:9]
	v_cndmask_b32_e64 v9, v123, 0, vcc
	v_cndmask_b32_e32 v8, v122, v154, vcc
	v_pk_mul_f32 v[2:3], v[2:3], v[12:13]
	v_pk_mul_f32 v[0:1], v[0:1], v[14:15]
	v_lshlrev_b64 v[8:9], 11, v[8:9]
	v_pk_mul_f32 v[4:5], v[4:5], v[10:11]
	v_lshl_add_u64 v[8:9], v[126:127], 0, v[8:9]
	v_cvt_pk_bf16_f32 v0, v0, v1
	v_cvt_pk_bf16_f32 v1, v2, v3
	v_cvt_pk_bf16_f32 v2, v4, v5
	v_cvt_pk_bf16_f32 v3, v6, v7
	global_store_dwordx2 v[8:9], v[0:1], off
	global_store_dwordx2 v[8:9], v[2:3], off offset:16
.LBB0_190:
	s_or_b64 exec, exec, s[2:3]
	s_add_i32 s67, s24, 4
	s_min_i32 s2, s67, s23
	s_nop 0
	v_sub_co_u32_e64 v0, vcc, s2, 1
	v_ashrrev_i32_e32 v1, 31, v0
	v_lshl_add_u64 v[0:1], v[0:1], 4, v[120:121]
	v_cndmask_b32_e64 v1, v1, 0, vcc
	v_cndmask_b32_e32 v0, v0, v154, vcc
	v_lshlrev_b64 v[0:1], 11, v[0:1]
	v_lshl_add_u64 v[0:1], v[184:185], 0, v[0:1]
	global_load_dwordx4 v[108:111], v[0:1], off
	s_add_i32 s52, s24, 1
	s_cmp_ge_i32 s52, s22
	s_cbranch_scc1 .LBB0_195
	s_waitcnt vmcnt(9)
	v_mfma_f32_32x32x16_bf16 v[16:31], v[104:107], v[132:135], 0
	v_mov_b32_e32 v32, v49
	v_mov_b32_e32 v33, v51
	v_mul_f32_e64 v32, v174, v32
	v_mul_f32_e64 v33, v175, v33
	ds_write_b128 v148, v[104:107] offset:8192
	v_sub_f32_e32 v32, v32, v33
	v_mov_b32_e32 v33, v49
	s_cmp_gt_i32 s24, -1
	s_nop 3
	v_add_f32_e32 v186, v32, v16
	v_mov_b32_e32 v32, v51
	v_pk_mul_f32 v[50:51], v[176:177], v[50:51] op_sel_hi:[1,0]
	v_pk_mul_f32 v[52:53], v[174:175], v[32:33]
	v_pk_fma_f32 v[188:189], v[172:173], v[48:49], v[50:51] neg_lo:[0,0,1] neg_hi:[0,0,1]
	v_pk_fma_f32 v[48:49], v[172:173], v[48:49], v[50:51] op_sel_hi:[1,0,1]
	v_mfma_f32_32x32x16_bf16 v[0:15], v[104:107], v[128:131], 0
	v_add_f32_e32 v16, v53, v52
	v_mov_b32_e32 v189, v49
	s_cselect_b64 s[2:3], -1, 0
	s_or_b64 s[14:15], s[2:3], s[50:51]
	v_mfma_f32_32x32x16_bf16 v[48:63], v[104:107], v[136:139], 0
	s_nop 6
	v_mov_b32_e32 v190, v0
	v_mfma_f32_32x32x16_bf16 v[32:47], v[104:107], v[140:143], 0
	s_nop 2
	v_mov_b32_e32 v191, v48
	v_add_f32_e64 v104, v188, v190
	v_add_f32_e64 v105, v189, v191
	v_mul_f32_e64 v106, v172, v104
	v_mul_f32_e64 v107, v173, v105
	v_sub_f32_e32 v0, v106, v107
	v_pk_mul_f32 v[106:107], v[176:177], v[104:105]
	s_nop 1
	v_add_f32_e32 v16, v16, v32
	v_add_f32_e32 v0, v1, v0
	v_add_f32_e32 v1, v106, v107
	v_add_f32_e32 v106, v49, v1
	v_pk_mul_f32 v[48:49], v[178:179], v[16:17] op_sel_hi:[1,0]
	v_mov_b32_e32 v32, v17
	v_pk_fma_f32 v[188:189], v[174:175], v[186:187], v[48:49] neg_lo:[0,0,1] neg_hi:[0,0,1]
	v_pk_fma_f32 v[48:49], v[174:175], v[186:187], v[48:49] op_sel_hi:[1,0,1]
	s_nop 0
	v_mov_b32_e32 v189, v49
	v_pk_add_f32 v[32:33], v[32:33], v[188:189]
	s_nop 0
	v_pk_mul_f32 v[48:49], v[174:175], v[32:33]
	s_nop 0
	v_sub_f32_e32 v1, v48, v49
	v_pk_mul_f32 v[48:49], v[178:179], v[32:33]
	v_add_f32_e32 v189, v18, v1
	v_add_f32_e32 v1, v48, v49
	v_pk_mul_f32 v[48:49], v[176:177], v[106:107] op_sel_hi:[1,0]
	v_add_f32_e32 v191, v34, v1
	v_pk_fma_f32 v[192:193], v[172:173], v[0:1], v[48:49] neg_lo:[0,0,1] neg_hi:[0,0,1]
	v_pk_fma_f32 v[48:49], v[172:173], v[0:1], v[48:49] op_sel_hi:[1,0,1]
	v_mul_f32_e32 v213, v174, v189
	v_mov_b32_e32 v193, v49
	v_mov_b32_e32 v48, v2
	v_mov_b32_e32 v49, v50
	v_pk_add_f32 v[192:193], v[48:49], v[192:193]
	v_mul_f32_e32 v215, v175, v191
	v_pk_mul_f32 v[48:49], v[172:173], v[192:193]
	v_mov_b32_e32 v18, v3
	v_mov_b32_e32 v212, v48
	v_mov_b32_e32 v214, v49
	v_pk_add_f32 v[48:49], v[212:213], v[214:215] neg_lo:[0,1] neg_hi:[0,1]
	v_mov_b32_e32 v190, v193
	v_pk_add_f32 v[2:3], v[18:19], v[48:49]
	v_pk_mul_f32 v[18:19], v[180:181], v[190:191]
	v_mov_b32_e32 v188, v192
	v_pk_fma_f32 v[18:19], v[182:183], v[188:189], v[18:19]
	v_mov_b32_e32 v34, v51
	v_pk_add_f32 v[18:19], v[34:35], v[18:19]
	v_mov_b32_e32 v48, v4
	v_pk_mul_f32 v[34:35], v[182:183], v[18:19]
	v_mov_b32_e32 v49, v20
	v_pk_fma_f32 v[34:35], v[180:181], v[2:3], v[34:35] neg_lo:[0,0,1] neg_hi:[0,0,1]
	v_mov_b32_e32 v50, v52
	v_pk_add_f32 v[34:35], v[48:49], v[34:35]
	v_pk_mul_f32 v[48:49], v[180:181], v[18:19]
	v_mov_b32_e32 v51, v36
	v_pk_fma_f32 v[48:49], v[182:183], v[2:3], v[48:49]
	v_mov_b32_e32 v20, v5
	v_pk_add_f32 v[212:213], v[50:51], v[48:49]
	v_mov_b32_e32 v36, v53
	v_pk_mul_f32 v[48:49], v[182:183], v[212:213]
	v_pk_mul_f32 v[50:51], v[180:181], v[212:213]
	v_pk_fma_f32 v[48:49], v[180:181], v[34:35], v[48:49] neg_lo:[0,0,1] neg_hi:[0,0,1]
	v_pk_fma_f32 v[50:51], v[182:183], v[34:35], v[50:51]
	v_pk_add_f32 v[4:5], v[20:21], v[48:49]
	v_pk_add_f32 v[20:21], v[36:37], v[50:51]
	v_mov_b32_e32 v48, v6
	v_pk_mul_f32 v[36:37], v[182:183], v[20:21]
	v_mov_b32_e32 v49, v22
	v_pk_fma_f32 v[36:37], v[180:181], v[4:5], v[36:37] neg_lo:[0,0,1] neg_hi:[0,0,1]
	v_mov_b32_e32 v50, v54
	v_pk_add_f32 v[36:37], v[48:49], v[36:37]
	v_pk_mul_f32 v[48:49], v[180:181], v[20:21]
	v_mov_b32_e32 v51, v38
	v_pk_fma_f32 v[48:49], v[182:183], v[4:5], v[48:49]
	v_mov_b32_e32 v22, v7
	v_pk_add_f32 v[52:53], v[50:51], v[48:49]
	v_mov_b32_e32 v38, v55
	v_pk_mul_f32 v[48:49], v[182:183], v[52:53]
	v_mov_b32_e32 v214, v8
	v_pk_fma_f32 v[48:49], v[180:181], v[36:37], v[48:49] neg_lo:[0,0,1] neg_hi:[0,0,1]
	v_mov_b32_e32 v215, v24
	v_pk_add_f32 v[6:7], v[22:23], v[48:49]
	v_pk_mul_f32 v[22:23], v[180:181], v[52:53]
	v_mov_b32_e32 v48, v56
	v_pk_fma_f32 v[22:23], v[182:183], v[36:37], v[22:23]
	v_mov_b32_e32 v49, v40
	v_pk_add_f32 v[22:23], v[38:39], v[22:23]
	v_mov_b32_e32 v24, v9
	v_pk_mul_f32 v[38:39], v[180:181], v[22:23]
	v_pk_mul_f32 v[54:55], v[182:183], v[22:23]
	v_pk_fma_f32 v[38:39], v[182:183], v[6:7], v[38:39]
	v_pk_fma_f32 v[54:55], v[180:181], v[6:7], v[54:55] neg_lo:[0,0,1] neg_hi:[0,0,1]
	v_pk_add_f32 v[38:39], v[48:49], v[38:39]
	v_pk_add_f32 v[54:55], v[214:215], v[54:55]
	v_pk_mul_f32 v[48:49], v[182:183], v[38:39]
	v_pk_mul_f32 v[50:51], v[180:181], v[38:39]
	v_pk_fma_f32 v[48:49], v[180:181], v[54:55], v[48:49] neg_lo:[0,0,1] neg_hi:[0,0,1]
	v_mov_b32_e32 v40, v57
	v_pk_add_f32 v[8:9], v[24:25], v[48:49]
	v_pk_fma_f32 v[24:25], v[182:183], v[54:55], v[50:51]
	v_mov_b32_e32 v48, v10
	v_pk_add_f32 v[24:25], v[40:41], v[24:25]
	v_mov_b32_e32 v49, v26
	v_pk_mul_f32 v[40:41], v[182:183], v[24:25]
	v_mov_b32_e32 v50, v58
	v_pk_fma_f32 v[40:41], v[180:181], v[8:9], v[40:41] neg_lo:[0,0,1] neg_hi:[0,0,1]
	v_mov_b32_e32 v51, v42
	v_pk_add_f32 v[40:41], v[48:49], v[40:41]
	v_pk_mul_f32 v[48:49], v[180:181], v[24:25]
	v_mov_b32_e32 v26, v11
	v_pk_fma_f32 v[48:49], v[182:183], v[8:9], v[48:49]
	v_mov_b32_e32 v42, v59
	v_pk_add_f32 v[56:57], v[50:51], v[48:49]
	v_mov_b32_e32 v50, v60
	v_pk_mul_f32 v[48:49], v[182:183], v[56:57]
	v_mov_b32_e32 v51, v44
	v_pk_fma_f32 v[48:49], v[180:181], v[40:41], v[48:49] neg_lo:[0,0,1] neg_hi:[0,0,1]
	v_mov_b32_e32 v44, v61
	v_pk_add_f32 v[10:11], v[26:27], v[48:49]
	v_pk_mul_f32 v[26:27], v[180:181], v[56:57]
	v_mov_b32_e32 v48, v12
	v_pk_fma_f32 v[26:27], v[182:183], v[40:41], v[26:27]
	v_mov_b32_e32 v49, v28
	v_pk_add_f32 v[26:27], v[42:43], v[26:27]
	v_mov_b32_e32 v28, v13
	v_pk_mul_f32 v[42:43], v[182:183], v[26:27]
	v_cvt_pk_bf16_f32 v0, v104, v0
	v_pk_fma_f32 v[42:43], v[180:181], v[10:11], v[42:43] neg_lo:[0,0,1] neg_hi:[0,0,1]
	v_cvt_pk_bf16_f32 v1, v192, v2
	v_pk_add_f32 v[42:43], v[48:49], v[42:43]
	v_pk_mul_f32 v[48:49], v[180:181], v[26:27]
	v_cvt_pk_bf16_f32 v2, v186, v32
	v_pk_fma_f32 v[48:49], v[182:183], v[10:11], v[48:49]
	v_cvt_pk_bf16_f32 v3, v189, v3
	v_pk_add_f32 v[58:59], v[50:51], v[48:49]
	v_mov_b32_e32 v50, v62
	v_pk_mul_f32 v[48:49], v[182:183], v[58:59]
	v_mov_b32_e32 v51, v46
	v_pk_fma_f32 v[48:49], v[180:181], v[42:43], v[48:49] neg_lo:[0,0,1] neg_hi:[0,0,1]
	v_mov_b32_e32 v46, v63
	v_pk_add_f32 v[12:13], v[28:29], v[48:49]
	v_pk_mul_f32 v[28:29], v[180:181], v[58:59]
	v_mov_b32_e32 v48, v14
	v_pk_fma_f32 v[28:29], v[182:183], v[42:43], v[28:29]
	v_mov_b32_e32 v49, v30
	v_pk_add_f32 v[28:29], v[44:45], v[28:29]
	v_mov_b32_e32 v30, v15
	v_pk_mul_f32 v[44:45], v[182:183], v[28:29]
	ds_write2st64_b64 v207, v[0:1], v[2:3] offset1:4
	v_pk_fma_f32 v[44:45], v[180:181], v[12:13], v[44:45] neg_lo:[0,0,1] neg_hi:[0,0,1]
	v_cvt_pk_bf16_f32 v0, v35, v5
	v_pk_add_f32 v[44:45], v[48:49], v[44:45]
	v_pk_mul_f32 v[48:49], v[180:181], v[28:29]
	v_cvt_pk_bf16_f32 v1, v37, v7
	v_pk_fma_f32 v[48:49], v[182:183], v[12:13], v[48:49]
	v_pk_mov_b32 v[2:3], v[192:193], v[18:19] op_sel:[1,0]
	v_pk_add_f32 v[60:61], v[50:51], v[48:49]
	v_cvt_pk_bf16_f32 v5, v56, v26
	v_pk_mul_f32 v[14:15], v[180:181], v[60:61]
	v_pk_mul_f32 v[48:49], v[182:183], v[60:61]
	v_pk_fma_f32 v[14:15], v[182:183], v[44:45], v[14:15]
	v_pk_fma_f32 v[48:49], v[180:181], v[44:45], v[48:49] neg_lo:[0,0,1] neg_hi:[0,0,1]
	v_pk_add_f32 v[50:51], v[46:47], v[14:15]
	v_cvt_pk_bf16_f32 v14, v34, v4
	v_cvt_pk_bf16_f32 v15, v36, v6
	v_pk_add_f32 v[48:49], v[30:31], v[48:49]
	v_cvt_pk_bf16_f32 v30, v54, v8
	v_cvt_pk_bf16_f32 v31, v40, v10
	ds_write2st64_b64 v208, v[14:15], v[0:1] offset1:4
	v_cvt_pk_bf16_f32 v0, v55, v9
	v_cvt_pk_bf16_f32 v1, v41, v11
	v_cvt_pk_bf16_f32 v46, v42, v12
	v_cvt_pk_bf16_f32 v47, v44, v48
	ds_write2st64_b64 v209, v[30:31], v[0:1] offset1:4
	v_cvt_pk_bf16_f32 v0, v43, v13
	v_cvt_pk_bf16_f32 v1, v45, v49
	ds_write2st64_b64 v210, v[46:47], v[0:1] offset1:4
	v_cvt_pk_bf16_f32 v0, v105, v106
	v_cvt_pk_bf16_f32 v1, v2, v3
	v_cvt_pk_bf16_f32 v8, v16, v33
	v_cvt_pk_bf16_f32 v9, v191, v19
	v_cvt_pk_bf16_f32 v2, v212, v20
	v_cvt_pk_bf16_f32 v3, v52, v22
	ds_write2st64_b64 v207, v[0:1], v[8:9] offset0:8 offset1:12
	v_cvt_pk_bf16_f32 v0, v213, v21
	v_cvt_pk_bf16_f32 v1, v53, v23
	v_cvt_pk_bf16_f32 v4, v38, v24
	ds_write2st64_b64 v208, v[2:3], v[0:1] offset0:8 offset1:12
	v_cvt_pk_bf16_f32 v0, v39, v25
	v_cvt_pk_bf16_f32 v1, v57, v27
	v_cvt_pk_bf16_f32 v6, v58, v28
	v_cvt_pk_bf16_f32 v7, v60, v50
	ds_write2st64_b64 v209, v[4:5], v[0:1] offset0:8 offset1:12
	v_cvt_pk_bf16_f32 v0, v59, v29
	v_cvt_pk_bf16_f32 v1, v61, v51
	ds_write2st64_b64 v210, v[6:7], v[0:1] offset0:8 offset1:12
	s_waitcnt lgkmcnt(0)
	ds_read_b64_tr_b16 v[0:1], v151 offset:0
	ds_read_b64_tr_b16 v[2:3], v199 offset:0
	ds_read_b64_tr_b16 v[28:29], v151 offset:1024
	ds_read_b64_tr_b16 v[30:31], v199 offset:1024
	ds_read_b64_tr_b16 v[24:25], v151 offset:2048
	ds_read_b64_tr_b16 v[26:27], v199 offset:2048
	ds_read_b64_tr_b16 v[20:21], v151 offset:3072
	ds_read_b64_tr_b16 v[22:23], v199 offset:3072
	ds_read_b64_tr_b16 v[16:17], v151 offset:4096
	ds_read_b64_tr_b16 v[18:19], v199 offset:4096
	ds_read_b64_tr_b16 v[44:45], v151 offset:5120
	ds_read_b64_tr_b16 v[46:47], v199 offset:5120
	ds_read_b64_tr_b16 v[40:41], v151 offset:6144
	ds_read_b64_tr_b16 v[42:43], v199 offset:6144
	ds_read_b64_tr_b16 v[52:53], v151 offset:7168
	ds_read_b64_tr_b16 v[54:55], v199 offset:7168
	s_waitcnt lgkmcnt(0)
	s_nop 0
	v_mfma_f32_32x32x16_bf16 v[0:15], v[68:71], v[0:3], 0
	v_mfma_f32_32x32x16_bf16 v[0:15], v[64:67], v[28:31], v[0:15]
	v_mfma_f32_32x32x16_bf16 v[0:15], v[76:79], v[24:27], v[0:15]
	v_mfma_f32_32x32x16_bf16 v[0:15], v[72:75], v[20:23], v[0:15]
	v_mfma_f32_32x32x16_bf16 v[0:15], v[84:87], v[16:19], v[0:15]
	v_mfma_f32_32x32x16_bf16 v[0:15], v[80:83], v[44:47], v[0:15]
	v_mfma_f32_32x32x16_bf16 v[0:15], v[92:95], v[40:43], v[0:15]
	v_mfma_f32_32x32x16_bf16 v[0:15], v[88:91], v[52:55], v[0:15]
	s_and_saveexec_b64 s[2:3], s[14:15]
	s_cbranch_execz .LBB0_193
	s_nop 7
	v_add_u32_e32 v16, v200, v146
	v_add_u32_e32 v16, 0x2000, v16
	ds_read2_b64 v[16:19], v16 offset1:2
	s_waitcnt lgkmcnt(0)
	v_lshlrev_b32_e32 v10, 16, v19
	v_and_b32_e32 v11, 0xffff0000, v19
	v_pk_fma_f32 v[6:7], v[102:103], v[10:11], v[6:7]
	s_nop 0
	v_mul_f32_e32 v10, v7, v7
	v_fmaak_f32 v10, v240, v10, 0xc0135761
	v_mul_f32_e32 v11, v6, v6
	v_mul_f32_e32 v10, v7, v10
	v_fmaak_f32 v11, v240, v11, 0xc0135761
	v_mul_f32_e32 v11, v6, v11
	v_exp_f32_e32 v10, v10
	v_exp_f32_e32 v11, v11
	v_add_f32_e32 v8, 1.0, v10
	v_rcp_f32_e32 v9, v8
	v_add_f32_e32 v8, 1.0, v11
	v_lshlrev_b32_e32 v10, 16, v18
	v_and_b32_e32 v11, 0xffff0000, v18
	v_pk_fma_f32 v[4:5], v[100:101], v[10:11], v[4:5]
	v_and_b32_e32 v13, 0xffff0000, v17
	v_mul_f32_e32 v10, v5, v5
	v_fmaak_f32 v10, v240, v10, 0xc0135761
	v_mul_f32_e32 v11, v4, v4
	v_mul_f32_e32 v10, v5, v10
	v_fmaak_f32 v11, v240, v11, 0xc0135761
	v_mul_f32_e32 v11, v4, v11
	v_exp_f32_e32 v10, v10
	v_exp_f32_e32 v12, v11
	v_and_b32_e32 v15, 0xffff0000, v16
	v_add_f32_e32 v10, 1.0, v10
	v_rcp_f32_e32 v11, v10
	v_add_f32_e32 v10, 1.0, v12
	v_lshlrev_b32_e32 v12, 16, v17
	v_pk_fma_f32 v[2:3], v[98:99], v[12:13], v[2:3]
	v_rcp_f32_e32 v8, v8
	v_mul_f32_e32 v12, v3, v3
	v_fmaak_f32 v12, v240, v12, 0xc0135761
	v_mul_f32_e32 v13, v2, v2
	v_mul_f32_e32 v12, v3, v12
	v_fmaak_f32 v13, v240, v13, 0xc0135761
	v_mul_f32_e32 v13, v2, v13
	v_exp_f32_e32 v12, v12
	v_exp_f32_e32 v14, v13
	v_rcp_f32_e32 v10, v10
	v_add_f32_e32 v12, 1.0, v12
	v_rcp_f32_e32 v13, v12
	v_add_f32_e32 v12, 1.0, v14
	v_lshlrev_b32_e32 v14, 16, v16
	v_pk_fma_f32 v[0:1], v[96:97], v[14:15], v[0:1]
	v_rcp_f32_e32 v12, v12
	v_mul_f32_e32 v14, v1, v1
	v_fmaak_f32 v14, v240, v14, 0xc0135761
	v_mul_f32_e32 v15, v0, v0
	v_mul_f32_e32 v14, v1, v14
	v_fmaak_f32 v15, v240, v15, 0xc0135761
	v_mul_f32_e32 v15, v0, v15
	v_exp_f32_e32 v14, v14
	v_exp_f32_e32 v16, v15
	s_cmp_eq_u32 s24, -1
	v_add_f32_e32 v14, 1.0, v14
	v_rcp_f32_e32 v15, v14
	v_add_f32_e32 v14, 1.0, v16
	v_rcp_f32_e32 v14, v14
	s_cselect_b64 vcc, -1, 0
	v_pk_mul_f32 v[6:7], v[6:7], v[8:9]
	v_cndmask_b32_e64 v9, v125, 0, vcc
	v_cndmask_b32_e32 v8, v124, v154, vcc
	v_pk_mul_f32 v[2:3], v[2:3], v[12:13]
	v_pk_mul_f32 v[0:1], v[0:1], v[14:15]
	v_lshlrev_b64 v[8:9], 11, v[8:9]
	v_pk_mul_f32 v[4:5], v[4:5], v[10:11]
	v_lshl_add_u64 v[8:9], v[126:127], 0, v[8:9]
	v_cvt_pk_bf16_f32 v0, v0, v1
	v_cvt_pk_bf16_f32 v1, v2, v3
	v_cvt_pk_bf16_f32 v2, v4, v5
	v_cvt_pk_bf16_f32 v3, v6, v7
	global_store_dwordx2 v[8:9], v[0:1], off
	global_store_dwordx2 v[8:9], v[2:3], off offset:16

.LBB0_196:
	s_waitcnt vmcnt(9)
	v_mfma_f32_32x32x16_bf16 v[16:31], v[116:119], v[132:135], 0
	v_mov_b32_e32 v32, v49
	v_mov_b32_e32 v33, v51
	v_mul_f32_e64 v32, v174, v32
	v_mul_f32_e64 v33, v175, v33
	ds_write_b128 v148, v[116:119] offset:8192
	v_sub_f32_e32 v32, v32, v33
	v_mov_b32_e32 v33, v49
	s_cmp_gt_i32 s24, -2
	s_nop 3
	v_add_f32_e32 v186, v32, v16
	v_mov_b32_e32 v32, v51
	v_pk_mul_f32 v[50:51], v[176:177], v[50:51] op_sel_hi:[1,0]
	v_pk_mul_f32 v[52:53], v[174:175], v[32:33]
	v_pk_fma_f32 v[188:189], v[172:173], v[48:49], v[50:51] neg_lo:[0,0,1] neg_hi:[0,0,1]
	v_pk_fma_f32 v[48:49], v[172:173], v[48:49], v[50:51] op_sel_hi:[1,0,1]
	v_mfma_f32_32x32x16_bf16 v[0:15], v[116:119], v[128:131], 0
	v_add_f32_e32 v16, v52, v53
	v_mov_b32_e32 v189, v49
	s_cselect_b64 s[2:3], -1, 0
	s_or_b64 s[68:69], s[2:3], s[50:51]
	v_mfma_f32_32x32x16_bf16 v[48:63], v[116:119], v[136:139], 0
	s_nop 6
	v_mov_b32_e32 v190, v0
	v_mfma_f32_32x32x16_bf16 v[32:47], v[116:119], v[140:143], 0
	s_nop 2
	v_mov_b32_e32 v191, v48
	v_add_f32_e64 v116, v188, v190
	v_add_f32_e64 v117, v189, v191
	v_mul_f32_e64 v118, v172, v116
	v_mul_f32_e64 v119, v173, v117
	v_sub_f32_e32 v0, v118, v119
	v_pk_mul_f32 v[118:119], v[176:177], v[116:117]
	s_nop 1
	v_add_f32_e32 v16, v16, v32
	v_add_f32_e32 v0, v1, v0
	v_add_f32_e32 v1, v118, v119
	v_add_f32_e32 v118, v49, v1
	v_pk_mul_f32 v[48:49], v[178:179], v[16:17] op_sel_hi:[1,0]
	v_mov_b32_e32 v32, v17
	v_pk_fma_f32 v[188:189], v[174:175], v[186:187], v[48:49] neg_lo:[0,0,1] neg_hi:[0,0,1]
	v_pk_fma_f32 v[48:49], v[174:175], v[186:187], v[48:49] op_sel_hi:[1,0,1]
	s_nop 0
	v_mov_b32_e32 v189, v49
	v_pk_add_f32 v[32:33], v[32:33], v[188:189]
	s_nop 0
	v_pk_mul_f32 v[48:49], v[174:175], v[32:33]
	s_nop 0
	v_sub_f32_e32 v1, v48, v49
	v_pk_mul_f32 v[48:49], v[178:179], v[32:33]
	v_add_f32_e32 v189, v18, v1
	v_add_f32_e32 v1, v48, v49
	v_pk_mul_f32 v[48:49], v[176:177], v[118:119] op_sel_hi:[1,0]
	v_add_f32_e32 v191, v34, v1
	v_pk_fma_f32 v[192:193], v[172:173], v[0:1], v[48:49] neg_lo:[0,0,1] neg_hi:[0,0,1]
	v_pk_fma_f32 v[48:49], v[172:173], v[0:1], v[48:49] op_sel_hi:[1,0,1]
	v_mul_f32_e32 v213, v174, v189
	v_mov_b32_e32 v193, v49
	v_mov_b32_e32 v48, v2
	v_mov_b32_e32 v49, v50
	v_pk_add_f32 v[192:193], v[48:49], v[192:193]
	v_mul_f32_e32 v215, v175, v191
	v_pk_mul_f32 v[48:49], v[172:173], v[192:193]
	v_mov_b32_e32 v18, v3
	v_mov_b32_e32 v212, v48
	v_mov_b32_e32 v214, v49
	v_pk_add_f32 v[48:49], v[212:213], v[214:215] neg_lo:[0,1] neg_hi:[0,1]
	v_mov_b32_e32 v190, v193
	v_pk_add_f32 v[2:3], v[18:19], v[48:49]
	v_pk_mul_f32 v[18:19], v[180:181], v[190:191]
	v_mov_b32_e32 v188, v192
	v_pk_fma_f32 v[18:19], v[182:183], v[188:189], v[18:19]
	v_mov_b32_e32 v34, v51
	v_pk_add_f32 v[18:19], v[34:35], v[18:19]
	v_mov_b32_e32 v48, v52
	v_pk_mul_f32 v[34:35], v[180:181], v[18:19]
	v_mov_b32_e32 v49, v36
	v_pk_fma_f32 v[34:35], v[182:183], v[2:3], v[34:35]
	v_pk_mul_f32 v[212:213], v[182:183], v[18:19]
	v_pk_add_f32 v[34:35], v[48:49], v[34:35]
	v_pk_fma_f32 v[212:213], v[180:181], v[2:3], v[212:213] neg_lo:[0,0,1] neg_hi:[0,0,1]
	v_mov_b32_e32 v214, v4
	v_mov_b32_e32 v215, v20
	v_pk_mul_f32 v[48:49], v[182:183], v[34:35]
	v_pk_add_f32 v[212:213], v[214:215], v[212:213]
	v_pk_mul_f32 v[50:51], v[180:181], v[34:35]
	v_pk_fma_f32 v[48:49], v[180:181], v[212:213], v[48:49] neg_lo:[0,0,1] neg_hi:[0,0,1]
	v_mov_b32_e32 v20, v5
	v_pk_add_f32 v[4:5], v[20:21], v[48:49]
	v_pk_fma_f32 v[20:21], v[182:183], v[212:213], v[50:51]
	v_mov_b32_e32 v36, v53
	v_pk_add_f32 v[20:21], v[36:37], v[20:21]
	v_mov_b32_e32 v48, v6
	v_pk_mul_f32 v[36:37], v[182:183], v[20:21]
	v_mov_b32_e32 v49, v22
	v_pk_fma_f32 v[36:37], v[180:181], v[4:5], v[36:37] neg_lo:[0,0,1] neg_hi:[0,0,1]
	v_mov_b32_e32 v50, v54
	v_pk_add_f32 v[36:37], v[48:49], v[36:37]
	v_pk_mul_f32 v[48:49], v[180:181], v[20:21]
	v_mov_b32_e32 v51, v38
	v_pk_fma_f32 v[48:49], v[182:183], v[4:5], v[48:49]
	v_mov_b32_e32 v22, v7
	v_pk_add_f32 v[52:53], v[50:51], v[48:49]
	v_mov_b32_e32 v38, v55
	v_pk_mul_f32 v[48:49], v[182:183], v[52:53]
	v_mov_b32_e32 v50, v56
	v_pk_fma_f32 v[48:49], v[180:181], v[36:37], v[48:49] neg_lo:[0,0,1] neg_hi:[0,0,1]
	v_mov_b32_e32 v51, v40
	v_pk_add_f32 v[6:7], v[22:23], v[48:49]
	v_pk_mul_f32 v[22:23], v[180:181], v[52:53]
	v_mov_b32_e32 v48, v8
	v_pk_fma_f32 v[22:23], v[182:183], v[36:37], v[22:23]
	v_mov_b32_e32 v49, v24
	v_pk_add_f32 v[22:23], v[38:39], v[22:23]
	v_mov_b32_e32 v24, v9
	v_pk_mul_f32 v[38:39], v[182:183], v[22:23]
	v_mov_b32_e32 v40, v57
	v_pk_fma_f32 v[38:39], v[180:181], v[6:7], v[38:39] neg_lo:[0,0,1] neg_hi:[0,0,1]
	v_cvt_pk_bf16_f32 v0, v116, v0
	v_pk_add_f32 v[38:39], v[48:49], v[38:39]
	v_pk_mul_f32 v[48:49], v[180:181], v[22:23]
	v_cvt_pk_bf16_f32 v1, v192, v2
	v_pk_fma_f32 v[48:49], v[182:183], v[6:7], v[48:49]
	v_cvt_pk_bf16_f32 v2, v186, v32
	v_pk_add_f32 v[54:55], v[50:51], v[48:49]
	v_mov_b32_e32 v50, v58
	v_pk_mul_f32 v[48:49], v[182:183], v[54:55]
	v_mov_b32_e32 v51, v42
	v_pk_fma_f32 v[48:49], v[180:181], v[38:39], v[48:49] neg_lo:[0,0,1] neg_hi:[0,0,1]
	v_mov_b32_e32 v42, v59
	v_pk_add_f32 v[8:9], v[24:25], v[48:49]
	v_pk_mul_f32 v[24:25], v[180:181], v[54:55]
	v_mov_b32_e32 v48, v10
	v_pk_fma_f32 v[24:25], v[182:183], v[38:39], v[24:25]
	v_mov_b32_e32 v49, v26
	v_pk_add_f32 v[24:25], v[40:41], v[24:25]
	v_mov_b32_e32 v26, v11
	v_pk_mul_f32 v[40:41], v[182:183], v[24:25]
	v_cvt_pk_bf16_f32 v3, v189, v3
	v_pk_fma_f32 v[40:41], v[180:181], v[8:9], v[40:41] neg_lo:[0,0,1] neg_hi:[0,0,1]
	ds_write2st64_b64 v207, v[0:1], v[2:3] offset1:4
	v_pk_add_f32 v[40:41], v[48:49], v[40:41]
	v_pk_mul_f32 v[48:49], v[180:181], v[24:25]
	v_cvt_pk_bf16_f32 v0, v213, v5
	v_pk_fma_f32 v[48:49], v[182:183], v[8:9], v[48:49]
	v_cvt_pk_bf16_f32 v1, v37, v7
	v_pk_add_f32 v[56:57], v[50:51], v[48:49]
	v_mov_b32_e32 v50, v12
	v_pk_mul_f32 v[48:49], v[182:183], v[56:57]
	v_mov_b32_e32 v51, v28
	v_pk_fma_f32 v[48:49], v[180:181], v[40:41], v[48:49] neg_lo:[0,0,1] neg_hi:[0,0,1]
	v_mov_b32_e32 v28, v13
	v_pk_add_f32 v[10:11], v[26:27], v[48:49]
	v_pk_mul_f32 v[26:27], v[180:181], v[56:57]
	v_pk_mov_b32 v[2:3], v[192:193], v[18:19] op_sel:[1,0]
	v_pk_fma_f32 v[26:27], v[182:183], v[40:41], v[26:27]
	s_nop 0
	v_pk_add_f32 v[26:27], v[42:43], v[26:27]
	s_nop 0
	v_pk_mul_f32 v[42:43], v[182:183], v[26:27]
	v_pk_mul_f32 v[48:49], v[180:181], v[26:27]
	v_pk_fma_f32 v[42:43], v[180:181], v[10:11], v[42:43] neg_lo:[0,0,1] neg_hi:[0,0,1]
	v_pk_fma_f32 v[48:49], v[182:183], v[10:11], v[48:49]
	v_pk_add_f32 v[42:43], v[50:51], v[42:43]
	v_mov_b32_e32 v50, v60
	v_mov_b32_e32 v51, v44
	v_pk_add_f32 v[58:59], v[50:51], v[48:49]
	v_mov_b32_e32 v44, v61
	v_pk_mul_f32 v[48:49], v[182:183], v[58:59]
	v_mov_b32_e32 v50, v62
	v_pk_fma_f32 v[48:49], v[180:181], v[42:43], v[48:49] neg_lo:[0,0,1] neg_hi:[0,0,1]
	v_mov_b32_e32 v51, v46
	v_pk_add_f32 v[12:13], v[28:29], v[48:49]
	v_pk_mul_f32 v[28:29], v[180:181], v[58:59]
	v_mov_b32_e32 v48, v14
	v_pk_fma_f32 v[28:29], v[182:183], v[42:43], v[28:29]
	v_mov_b32_e32 v49, v30
	v_pk_add_f32 v[28:29], v[44:45], v[28:29]
	v_mov_b32_e32 v30, v15
	v_pk_mul_f32 v[44:45], v[182:183], v[28:29]
	v_mov_b32_e32 v46, v63
	v_pk_fma_f32 v[44:45], v[180:181], v[12:13], v[44:45] neg_lo:[0,0,1] neg_hi:[0,0,1]
	v_cvt_pk_bf16_f32 v5, v56, v26
	v_pk_add_f32 v[44:45], v[48:49], v[44:45]
	v_pk_mul_f32 v[48:49], v[180:181], v[28:29]
	s_nop 0
	v_pk_fma_f32 v[48:49], v[182:183], v[12:13], v[48:49]
	s_nop 0
	v_pk_add_f32 v[60:61], v[50:51], v[48:49]
	s_nop 0
	v_pk_mul_f32 v[14:15], v[180:181], v[60:61]
	v_pk_mul_f32 v[48:49], v[182:183], v[60:61]
	v_pk_fma_f32 v[14:15], v[182:183], v[44:45], v[14:15]
	v_pk_fma_f32 v[48:49], v[180:181], v[44:45], v[48:49] neg_lo:[0,0,1] neg_hi:[0,0,1]
	v_pk_add_f32 v[50:51], v[46:47], v[14:15]
	v_cvt_pk_bf16_f32 v14, v212, v4
	v_cvt_pk_bf16_f32 v15, v36, v6
	v_pk_add_f32 v[48:49], v[30:31], v[48:49]
	v_cvt_pk_bf16_f32 v30, v38, v8
	v_cvt_pk_bf16_f32 v31, v40, v10
	ds_write2st64_b64 v208, v[14:15], v[0:1] offset1:4
	v_cvt_pk_bf16_f32 v0, v39, v9
	v_cvt_pk_bf16_f32 v1, v41, v11
	v_cvt_pk_bf16_f32 v46, v42, v12
	v_cvt_pk_bf16_f32 v47, v44, v48
	ds_write2st64_b64 v209, v[30:31], v[0:1] offset1:4
	v_cvt_pk_bf16_f32 v0, v43, v13
	v_cvt_pk_bf16_f32 v1, v45, v49
	ds_write2st64_b64 v210, v[46:47], v[0:1] offset1:4
	v_cvt_pk_bf16_f32 v0, v117, v118
	v_cvt_pk_bf16_f32 v1, v2, v3
	v_cvt_pk_bf16_f32 v8, v16, v33
	v_cvt_pk_bf16_f32 v9, v191, v19
	v_cvt_pk_bf16_f32 v2, v34, v20
	v_cvt_pk_bf16_f32 v3, v52, v22
	ds_write2st64_b64 v207, v[0:1], v[8:9] offset0:8 offset1:12
	v_cvt_pk_bf16_f32 v0, v35, v21
	v_cvt_pk_bf16_f32 v1, v53, v23
	v_cvt_pk_bf16_f32 v4, v54, v24
	ds_write2st64_b64 v208, v[2:3], v[0:1] offset0:8 offset1:12
	v_cvt_pk_bf16_f32 v0, v55, v25
	v_cvt_pk_bf16_f32 v1, v57, v27
	v_cvt_pk_bf16_f32 v6, v58, v28
	v_cvt_pk_bf16_f32 v7, v60, v50
	ds_write2st64_b64 v209, v[4:5], v[0:1] offset0:8 offset1:12
	v_cvt_pk_bf16_f32 v0, v59, v29
	v_cvt_pk_bf16_f32 v1, v61, v51
	ds_write2st64_b64 v210, v[6:7], v[0:1] offset0:8 offset1:12
	s_waitcnt lgkmcnt(0)
	ds_read_b64_tr_b16 v[0:1], v151 offset:0
	ds_read_b64_tr_b16 v[2:3], v199 offset:0
	ds_read_b64_tr_b16 v[28:29], v151 offset:1024
	ds_read_b64_tr_b16 v[30:31], v199 offset:1024
	ds_read_b64_tr_b16 v[24:25], v151 offset:2048
	ds_read_b64_tr_b16 v[26:27], v199 offset:2048
	ds_read_b64_tr_b16 v[20:21], v151 offset:3072
	ds_read_b64_tr_b16 v[22:23], v199 offset:3072
	ds_read_b64_tr_b16 v[16:17], v151 offset:4096
	ds_read_b64_tr_b16 v[18:19], v199 offset:4096
	ds_read_b64_tr_b16 v[44:45], v151 offset:5120
	ds_read_b64_tr_b16 v[46:47], v199 offset:5120
	ds_read_b64_tr_b16 v[40:41], v151 offset:6144
	ds_read_b64_tr_b16 v[42:43], v199 offset:6144
	ds_read_b64_tr_b16 v[52:53], v151 offset:7168
	ds_read_b64_tr_b16 v[54:55], v199 offset:7168
	s_waitcnt lgkmcnt(0)
	s_nop 0
	v_mfma_f32_32x32x16_bf16 v[0:15], v[68:71], v[0:3], 0
	v_mfma_f32_32x32x16_bf16 v[0:15], v[64:67], v[28:31], v[0:15]
	v_mfma_f32_32x32x16_bf16 v[0:15], v[76:79], v[24:27], v[0:15]
	v_mfma_f32_32x32x16_bf16 v[0:15], v[72:75], v[20:23], v[0:15]
	v_mfma_f32_32x32x16_bf16 v[0:15], v[84:87], v[16:19], v[0:15]
	v_mfma_f32_32x32x16_bf16 v[0:15], v[80:83], v[44:47], v[0:15]
	v_mfma_f32_32x32x16_bf16 v[0:15], v[92:95], v[40:43], v[0:15]
	v_mfma_f32_32x32x16_bf16 v[0:15], v[88:91], v[52:55], v[0:15]
	s_and_saveexec_b64 s[2:3], s[68:69]
	s_cbranch_execz .LBB0_198
	s_nop 7
	v_add_u32_e32 v16, v200, v146
	v_add_u32_e32 v16, 0x2000, v16
	ds_read2_b64 v[16:19], v16 offset1:2
	s_waitcnt lgkmcnt(0)
	v_lshlrev_b32_e32 v10, 16, v19
	v_and_b32_e32 v11, 0xffff0000, v19
	v_pk_fma_f32 v[6:7], v[102:103], v[10:11], v[6:7]
	s_nop 0
	v_mul_f32_e32 v10, v7, v7
	v_fmaak_f32 v10, v240, v10, 0xc0135761
	v_mul_f32_e32 v11, v6, v6
	v_mul_f32_e32 v10, v7, v10
	v_fmaak_f32 v11, v240, v11, 0xc0135761
	v_mul_f32_e32 v11, v6, v11
	v_exp_f32_e32 v10, v10
	v_exp_f32_e32 v11, v11
	v_add_f32_e32 v8, 1.0, v10
	v_rcp_f32_e32 v9, v8
	v_add_f32_e32 v8, 1.0, v11
	v_lshlrev_b32_e32 v10, 16, v18
	v_and_b32_e32 v11, 0xffff0000, v18
	v_pk_fma_f32 v[4:5], v[100:101], v[10:11], v[4:5]
	v_and_b32_e32 v13, 0xffff0000, v17
	v_mul_f32_e32 v10, v5, v5
	v_fmaak_f32 v10, v240, v10, 0xc0135761
	v_mul_f32_e32 v11, v4, v4
	v_mul_f32_e32 v10, v5, v10
	v_fmaak_f32 v11, v240, v11, 0xc0135761
	v_mul_f32_e32 v11, v4, v11
	v_exp_f32_e32 v10, v10
	v_exp_f32_e32 v12, v11
	v_and_b32_e32 v15, 0xffff0000, v16
	v_add_f32_e32 v10, 1.0, v10
	v_rcp_f32_e32 v11, v10
	v_add_f32_e32 v10, 1.0, v12
	v_lshlrev_b32_e32 v12, 16, v17
	v_pk_fma_f32 v[2:3], v[98:99], v[12:13], v[2:3]
	v_rcp_f32_e32 v8, v8
	v_mul_f32_e32 v12, v3, v3
	v_fmaak_f32 v12, v240, v12, 0xc0135761
	v_mul_f32_e32 v13, v2, v2
	v_mul_f32_e32 v12, v3, v12
	v_fmaak_f32 v13, v240, v13, 0xc0135761
	v_mul_f32_e32 v13, v2, v13
	v_exp_f32_e32 v12, v12
	v_exp_f32_e32 v14, v13
	s_cmp_eq_u32 s24, -2
	v_add_f32_e32 v12, 1.0, v12
	v_rcp_f32_e32 v13, v12
	v_add_f32_e32 v12, 1.0, v14
	v_lshlrev_b32_e32 v14, 16, v16
	v_pk_fma_f32 v[0:1], v[96:97], v[14:15], v[0:1]
	v_rcp_f32_e32 v12, v12
	v_mul_f32_e32 v14, v1, v1
	v_fmaak_f32 v14, v240, v14, 0xc0135761
	v_mul_f32_e32 v15, v0, v0
	v_mul_f32_e32 v14, v1, v14
	v_fmaak_f32 v15, v240, v15, 0xc0135761
	v_mul_f32_e32 v15, v0, v15
	v_exp_f32_e32 v14, v14
	v_exp_f32_e32 v16, v15
	v_rcp_f32_e32 v10, v10
	v_add_f32_e32 v14, 1.0, v14
	v_rcp_f32_e32 v15, v14
	v_add_f32_e32 v14, 1.0, v16
	v_rcp_f32_e32 v14, v14
	s_cselect_b64 vcc, -1, 0
	s_ashr_i32 s53, s52, 31
	v_pk_mul_f32 v[6:7], v[6:7], v[8:9]
	v_lshl_add_u64 v[8:9], s[52:53], 4, v[120:121]
	v_cndmask_b32_e64 v9, v9, 0, vcc
	v_cndmask_b32_e32 v8, v8, v154, vcc
	v_pk_mul_f32 v[2:3], v[2:3], v[12:13]
	v_pk_mul_f32 v[0:1], v[0:1], v[14:15]
	v_lshlrev_b64 v[8:9], 11, v[8:9]
	v_pk_mul_f32 v[4:5], v[4:5], v[10:11]
	v_lshl_add_u64 v[8:9], v[126:127], 0, v[8:9]
	v_cvt_pk_bf16_f32 v0, v0, v1
	v_cvt_pk_bf16_f32 v1, v2, v3
	v_cvt_pk_bf16_f32 v2, v4, v5
	v_cvt_pk_bf16_f32 v3, v6, v7
	global_store_dwordx2 v[8:9], v[0:1], off
	global_store_dwordx2 v[8:9], v[2:3], off offset:16

.LBB0_199:
	s_waitcnt vmcnt(9)
	v_mfma_f32_32x32x16_bf16 v[16:31], v[112:115], v[132:135], 0
	v_mov_b32_e32 v32, v49
	v_mov_b32_e32 v33, v51
	v_mul_f32_e64 v32, v174, v32
	v_mul_f32_e64 v33, v175, v33
	ds_write_b128 v148, v[112:115] offset:8192
	v_sub_f32_e32 v32, v32, v33
	v_mov_b32_e32 v33, v49
	s_cmp_gt_i32 s24, -3
	s_nop 3
	v_add_f32_e32 v148, v32, v16
	v_mov_b32_e32 v32, v51
	v_pk_mul_f32 v[50:51], v[176:177], v[50:51] op_sel_hi:[1,0]
	v_pk_mul_f32 v[52:53], v[174:175], v[32:33]
	v_pk_fma_f32 v[186:187], v[172:173], v[48:49], v[50:51] neg_lo:[0,0,1] neg_hi:[0,0,1]
	v_pk_fma_f32 v[48:49], v[172:173], v[48:49], v[50:51] op_sel_hi:[1,0,1]
	v_mfma_f32_32x32x16_bf16 v[0:15], v[112:115], v[128:131], 0
	v_add_f32_e32 v16, v52, v53
	v_mov_b32_e32 v187, v49
	s_cselect_b64 s[2:3], -1, 0
	s_or_b64 s[52:53], s[2:3], s[50:51]
	v_mfma_f32_32x32x16_bf16 v[48:63], v[112:115], v[136:139], 0
	s_nop 6
	v_mov_b32_e32 v188, v0
	v_mfma_f32_32x32x16_bf16 v[32:47], v[112:115], v[140:143], 0
	s_nop 2
	v_mov_b32_e32 v189, v48
	v_add_f32_e64 v112, v186, v188
	v_add_f32_e64 v113, v187, v189
	v_mul_f32_e64 v114, v172, v112
	v_mul_f32_e64 v115, v173, v113
	v_sub_f32_e32 v0, v114, v115
	v_pk_mul_f32 v[114:115], v[176:177], v[112:113]
	s_nop 1
	v_add_f32_e32 v16, v16, v32
	v_add_f32_e32 v0, v1, v0
	v_add_f32_e32 v1, v114, v115
	v_add_f32_e32 v114, v49, v1
	v_pk_mul_f32 v[48:49], v[178:179], v[16:17] op_sel_hi:[1,0]
	v_mov_b32_e32 v32, v17
	v_pk_fma_f32 v[186:187], v[174:175], v[148:149], v[48:49] neg_lo:[0,0,1] neg_hi:[0,0,1]
	v_pk_fma_f32 v[48:49], v[174:175], v[148:149], v[48:49] op_sel_hi:[1,0,1]
	s_nop 0
	v_mov_b32_e32 v187, v49
	v_pk_add_f32 v[32:33], v[32:33], v[186:187]
	s_nop 0
	v_pk_mul_f32 v[48:49], v[174:175], v[32:33]
	s_nop 0
	v_sub_f32_e32 v1, v48, v49
	v_pk_mul_f32 v[48:49], v[178:179], v[32:33]
	v_add_f32_e32 v187, v18, v1
	v_add_f32_e32 v1, v48, v49
	v_pk_mul_f32 v[48:49], v[176:177], v[114:115] op_sel_hi:[1,0]
	v_add_f32_e32 v189, v34, v1
	v_pk_fma_f32 v[190:191], v[172:173], v[0:1], v[48:49] neg_lo:[0,0,1] neg_hi:[0,0,1]
	v_pk_fma_f32 v[48:49], v[172:173], v[0:1], v[48:49] op_sel_hi:[1,0,1]
	v_mul_f32_e32 v193, v174, v187
	v_mov_b32_e32 v191, v49
	v_mov_b32_e32 v48, v2
	v_mov_b32_e32 v49, v50
	v_pk_add_f32 v[190:191], v[48:49], v[190:191]
	v_mul_f32_e32 v213, v175, v189
	v_pk_mul_f32 v[48:49], v[172:173], v[190:191]
	v_mov_b32_e32 v18, v3
	v_mov_b32_e32 v192, v48
	v_mov_b32_e32 v212, v49
	v_pk_add_f32 v[48:49], v[192:193], v[212:213] neg_lo:[0,1] neg_hi:[0,1]
	v_mov_b32_e32 v188, v191
	v_pk_add_f32 v[2:3], v[18:19], v[48:49]
	v_pk_mul_f32 v[18:19], v[180:181], v[188:189]
	v_mov_b32_e32 v186, v190
	v_pk_fma_f32 v[18:19], v[182:183], v[186:187], v[18:19]
	v_mov_b32_e32 v34, v51
	v_pk_add_f32 v[18:19], v[34:35], v[18:19]
	v_mov_b32_e32 v48, v4
	v_pk_mul_f32 v[34:35], v[182:183], v[18:19]
	v_mov_b32_e32 v49, v20
	v_pk_fma_f32 v[34:35], v[180:181], v[2:3], v[34:35] neg_lo:[0,0,1] neg_hi:[0,0,1]
	v_mov_b32_e32 v50, v52
	v_pk_add_f32 v[34:35], v[48:49], v[34:35]
	v_pk_mul_f32 v[48:49], v[180:181], v[18:19]
	v_mov_b32_e32 v51, v36
	v_pk_fma_f32 v[48:49], v[182:183], v[2:3], v[48:49]
	v_mov_b32_e32 v20, v5
	v_pk_add_f32 v[192:193], v[50:51], v[48:49]
	v_mov_b32_e32 v36, v53
	v_pk_mul_f32 v[48:49], v[182:183], v[192:193]
	v_mov_b32_e32 v50, v54
	v_pk_fma_f32 v[48:49], v[180:181], v[34:35], v[48:49] neg_lo:[0,0,1] neg_hi:[0,0,1]
	v_mov_b32_e32 v51, v38
	v_pk_add_f32 v[4:5], v[20:21], v[48:49]
	v_pk_mul_f32 v[20:21], v[180:181], v[192:193]
	v_mov_b32_e32 v48, v6
	v_pk_fma_f32 v[20:21], v[182:183], v[34:35], v[20:21]
	v_mov_b32_e32 v49, v22
	v_pk_add_f32 v[20:21], v[36:37], v[20:21]
	v_mov_b32_e32 v22, v7
	v_pk_mul_f32 v[36:37], v[182:183], v[20:21]
	v_mov_b32_e32 v38, v55
	v_pk_fma_f32 v[36:37], v[180:181], v[4:5], v[36:37] neg_lo:[0,0,1] neg_hi:[0,0,1]
	v_cvt_pk_bf16_f32 v0, v112, v0
	v_pk_add_f32 v[36:37], v[48:49], v[36:37]
	v_pk_mul_f32 v[48:49], v[180:181], v[20:21]
	v_cvt_pk_bf16_f32 v1, v190, v2
	v_pk_fma_f32 v[48:49], v[182:183], v[4:5], v[48:49]
	v_cvt_pk_bf16_f32 v2, v148, v32
	v_pk_add_f32 v[52:53], v[50:51], v[48:49]
	v_mov_b32_e32 v50, v8
	v_pk_mul_f32 v[48:49], v[182:183], v[52:53]
	v_mov_b32_e32 v51, v24
	v_pk_fma_f32 v[48:49], v[180:181], v[36:37], v[48:49] neg_lo:[0,0,1] neg_hi:[0,0,1]
	v_mov_b32_e32 v24, v9
	v_pk_add_f32 v[6:7], v[22:23], v[48:49]
	v_pk_mul_f32 v[22:23], v[180:181], v[52:53]
	v_cvt_pk_bf16_f32 v3, v187, v3
	v_pk_fma_f32 v[22:23], v[182:183], v[36:37], v[22:23]
	ds_write2st64_b64 v207, v[0:1], v[2:3] offset1:4
	v_pk_add_f32 v[22:23], v[38:39], v[22:23]
	v_cvt_pk_bf16_f32 v0, v35, v5
	v_pk_mul_f32 v[38:39], v[182:183], v[22:23]
	v_pk_mul_f32 v[48:49], v[180:181], v[22:23]
	v_pk_fma_f32 v[38:39], v[180:181], v[6:7], v[38:39] neg_lo:[0,0,1] neg_hi:[0,0,1]
	v_pk_fma_f32 v[48:49], v[182:183], v[6:7], v[48:49]
	v_pk_add_f32 v[38:39], v[50:51], v[38:39]
	v_mov_b32_e32 v50, v56
	v_mov_b32_e32 v51, v40
	v_pk_add_f32 v[54:55], v[50:51], v[48:49]
	v_mov_b32_e32 v40, v57
	v_pk_mul_f32 v[48:49], v[182:183], v[54:55]
	v_mov_b32_e32 v50, v58
	v_pk_fma_f32 v[48:49], v[180:181], v[38:39], v[48:49] neg_lo:[0,0,1] neg_hi:[0,0,1]
	v_mov_b32_e32 v51, v42
	v_pk_add_f32 v[8:9], v[24:25], v[48:49]
	v_pk_mul_f32 v[24:25], v[180:181], v[54:55]
	v_mov_b32_e32 v48, v10
	v_pk_fma_f32 v[24:25], v[182:183], v[38:39], v[24:25]
	v_mov_b32_e32 v49, v26
	v_pk_add_f32 v[24:25], v[40:41], v[24:25]
	v_mov_b32_e32 v42, v59
	v_pk_mul_f32 v[40:41], v[182:183], v[24:25]
	v_mov_b32_e32 v26, v11
	v_pk_fma_f32 v[40:41], v[180:181], v[8:9], v[40:41] neg_lo:[0,0,1] neg_hi:[0,0,1]
	v_cvt_pk_bf16_f32 v1, v37, v7
	v_pk_add_f32 v[40:41], v[48:49], v[40:41]
	v_pk_mul_f32 v[48:49], v[180:181], v[24:25]
	v_pk_mov_b32 v[2:3], v[190:191], v[18:19] op_sel:[1,0]
	v_pk_fma_f32 v[48:49], v[182:183], v[8:9], v[48:49]
	s_nop 0
	v_pk_add_f32 v[56:57], v[50:51], v[48:49]
	s_nop 0
	v_pk_mul_f32 v[48:49], v[180:181], v[56:57]
	v_pk_mul_f32 v[58:59], v[182:183], v[56:57]
	v_pk_fma_f32 v[48:49], v[182:183], v[40:41], v[48:49]
	v_pk_fma_f32 v[58:59], v[180:181], v[40:41], v[58:59] neg_lo:[0,0,1] neg_hi:[0,0,1]
	v_pk_add_f32 v[42:43], v[42:43], v[48:49]
	v_pk_add_f32 v[10:11], v[26:27], v[58:59]
	v_pk_mul_f32 v[48:49], v[182:183], v[42:43]
	v_pk_mul_f32 v[50:51], v[180:181], v[42:43]
	v_pk_fma_f32 v[26:27], v[180:181], v[10:11], v[48:49] neg_lo:[0,0,1] neg_hi:[0,0,1]
	v_mov_b32_e32 v48, v12
	v_mov_b32_e32 v49, v28
	v_pk_add_f32 v[26:27], v[48:49], v[26:27]
	v_pk_fma_f32 v[48:49], v[182:183], v[10:11], v[50:51]
	v_mov_b32_e32 v50, v60
	v_mov_b32_e32 v51, v44
	v_pk_add_f32 v[58:59], v[50:51], v[48:49]
	v_mov_b32_e32 v28, v13
	v_pk_mul_f32 v[48:49], v[182:183], v[58:59]
	v_mov_b32_e32 v44, v61
	v_pk_fma_f32 v[48:49], v[180:181], v[26:27], v[48:49] neg_lo:[0,0,1] neg_hi:[0,0,1]
	v_mov_b32_e32 v50, v62
	v_pk_add_f32 v[12:13], v[28:29], v[48:49]
	v_pk_mul_f32 v[28:29], v[180:181], v[58:59]
	v_mov_b32_e32 v48, v14
	v_pk_fma_f32 v[28:29], v[182:183], v[26:27], v[28:29]
	v_mov_b32_e32 v49, v30
	v_pk_add_f32 v[28:29], v[44:45], v[28:29]
	v_mov_b32_e32 v51, v46
	v_pk_mul_f32 v[44:45], v[182:183], v[28:29]
	v_mov_b32_e32 v30, v15
	v_pk_fma_f32 v[44:45], v[180:181], v[12:13], v[44:45] neg_lo:[0,0,1] neg_hi:[0,0,1]
	v_mov_b32_e32 v46, v63
	v_pk_add_f32 v[44:45], v[48:49], v[44:45]
	v_pk_mul_f32 v[48:49], v[180:181], v[28:29]
	v_cvt_pk_bf16_f32 v5, v56, v42
	v_pk_fma_f32 v[48:49], v[182:183], v[12:13], v[48:49]
	s_nop 0
	v_pk_add_f32 v[60:61], v[50:51], v[48:49]
	s_nop 0
	v_pk_mul_f32 v[14:15], v[180:181], v[60:61]
	v_pk_mul_f32 v[48:49], v[182:183], v[60:61]
	v_pk_fma_f32 v[14:15], v[182:183], v[44:45], v[14:15]
	v_pk_fma_f32 v[48:49], v[180:181], v[44:45], v[48:49] neg_lo:[0,0,1] neg_hi:[0,0,1]
	v_pk_add_f32 v[50:51], v[46:47], v[14:15]
	v_cvt_pk_bf16_f32 v14, v34, v4
	v_cvt_pk_bf16_f32 v15, v36, v6
	v_pk_add_f32 v[48:49], v[30:31], v[48:49]
	v_cvt_pk_bf16_f32 v30, v38, v8
	v_cvt_pk_bf16_f32 v31, v40, v10
	ds_write2st64_b64 v208, v[14:15], v[0:1] offset1:4
	v_cvt_pk_bf16_f32 v0, v39, v9
	v_cvt_pk_bf16_f32 v1, v41, v11
	v_cvt_pk_bf16_f32 v46, v26, v12
	v_cvt_pk_bf16_f32 v47, v44, v48
	ds_write2st64_b64 v209, v[30:31], v[0:1] offset1:4
	v_cvt_pk_bf16_f32 v0, v27, v13
	v_cvt_pk_bf16_f32 v1, v45, v49
	ds_write2st64_b64 v210, v[46:47], v[0:1] offset1:4
	v_cvt_pk_bf16_f32 v0, v113, v114
	v_cvt_pk_bf16_f32 v1, v2, v3
	v_cvt_pk_bf16_f32 v8, v16, v33
	v_cvt_pk_bf16_f32 v9, v189, v19
	v_cvt_pk_bf16_f32 v2, v192, v20
	v_cvt_pk_bf16_f32 v3, v52, v22
	ds_write2st64_b64 v207, v[0:1], v[8:9] offset0:8 offset1:12
	v_cvt_pk_bf16_f32 v0, v193, v21
	v_cvt_pk_bf16_f32 v1, v53, v23
	v_cvt_pk_bf16_f32 v4, v54, v24
	ds_write2st64_b64 v208, v[2:3], v[0:1] offset0:8 offset1:12
	v_cvt_pk_bf16_f32 v0, v55, v25
	v_cvt_pk_bf16_f32 v1, v57, v43
	v_cvt_pk_bf16_f32 v6, v58, v28
	v_cvt_pk_bf16_f32 v7, v60, v50
	ds_write2st64_b64 v209, v[4:5], v[0:1] offset0:8 offset1:12
	v_cvt_pk_bf16_f32 v0, v59, v29
	v_cvt_pk_bf16_f32 v1, v61, v51
	ds_write2st64_b64 v210, v[6:7], v[0:1] offset0:8 offset1:12
	s_waitcnt lgkmcnt(0)
	ds_read_b64_tr_b16 v[0:1], v151 offset:0
	ds_read_b64_tr_b16 v[2:3], v199 offset:0
	ds_read_b64_tr_b16 v[28:29], v151 offset:1024
	ds_read_b64_tr_b16 v[30:31], v199 offset:1024
	ds_read_b64_tr_b16 v[24:25], v151 offset:2048
	ds_read_b64_tr_b16 v[26:27], v199 offset:2048
	ds_read_b64_tr_b16 v[20:21], v151 offset:3072
	ds_read_b64_tr_b16 v[22:23], v199 offset:3072
	ds_read_b64_tr_b16 v[16:17], v151 offset:4096
	ds_read_b64_tr_b16 v[18:19], v199 offset:4096
	ds_read_b64_tr_b16 v[44:45], v151 offset:5120
	ds_read_b64_tr_b16 v[46:47], v199 offset:5120
	ds_read_b64_tr_b16 v[40:41], v151 offset:6144
	ds_read_b64_tr_b16 v[42:43], v199 offset:6144
	ds_read_b64_tr_b16 v[52:53], v151 offset:7168
	ds_read_b64_tr_b16 v[54:55], v199 offset:7168
	s_waitcnt lgkmcnt(0)
	s_nop 0
	v_mfma_f32_32x32x16_bf16 v[0:15], v[68:71], v[0:3], 0
	v_mfma_f32_32x32x16_bf16 v[0:15], v[64:67], v[28:31], v[0:15]
	v_mfma_f32_32x32x16_bf16 v[0:15], v[76:79], v[24:27], v[0:15]
	v_mfma_f32_32x32x16_bf16 v[0:15], v[72:75], v[20:23], v[0:15]
	v_mfma_f32_32x32x16_bf16 v[0:15], v[84:87], v[16:19], v[0:15]
	v_mfma_f32_32x32x16_bf16 v[0:15], v[80:83], v[44:47], v[0:15]
	v_mfma_f32_32x32x16_bf16 v[0:15], v[92:95], v[40:43], v[0:15]
	v_mfma_f32_32x32x16_bf16 v[0:15], v[88:91], v[52:55], v[0:15]
	s_and_saveexec_b64 s[2:3], s[52:53]
	s_cbranch_execz .LBB0_186
	s_nop 7
	v_add_u32_e32 v16, v200, v146
	v_add_u32_e32 v16, 0x2000, v16
	ds_read2_b64 v[16:19], v16 offset1:2
	s_waitcnt lgkmcnt(0)
	v_lshlrev_b32_e32 v10, 16, v19
	v_and_b32_e32 v11, 0xffff0000, v19
	v_pk_fma_f32 v[6:7], v[102:103], v[10:11], v[6:7]
	s_nop 0
	v_mul_f32_e32 v10, v7, v7
	v_fmaak_f32 v10, v240, v10, 0xc0135761
	v_mul_f32_e32 v11, v6, v6
	v_mul_f32_e32 v10, v7, v10
	v_fmaak_f32 v11, v240, v11, 0xc0135761
	v_mul_f32_e32 v11, v6, v11
	v_exp_f32_e32 v10, v10
	v_exp_f32_e32 v11, v11
	v_add_f32_e32 v8, 1.0, v10
	v_rcp_f32_e32 v9, v8
	v_add_f32_e32 v8, 1.0, v11
	v_lshlrev_b32_e32 v10, 16, v18
	v_and_b32_e32 v11, 0xffff0000, v18
	v_pk_fma_f32 v[4:5], v[100:101], v[10:11], v[4:5]
	v_and_b32_e32 v13, 0xffff0000, v17
	v_mul_f32_e32 v10, v5, v5
	v_fmaak_f32 v10, v240, v10, 0xc0135761
	v_mul_f32_e32 v11, v4, v4
	v_mul_f32_e32 v10, v5, v10
	v_fmaak_f32 v11, v240, v11, 0xc0135761
	v_mul_f32_e32 v11, v4, v11
	v_exp_f32_e32 v10, v10
	v_exp_f32_e32 v12, v11
	v_and_b32_e32 v15, 0xffff0000, v16
	v_add_f32_e32 v10, 1.0, v10
	v_rcp_f32_e32 v11, v10
	v_add_f32_e32 v10, 1.0, v12
	v_lshlrev_b32_e32 v12, 16, v17
	v_pk_fma_f32 v[2:3], v[98:99], v[12:13], v[2:3]
	v_rcp_f32_e32 v8, v8
	v_mul_f32_e32 v12, v3, v3
	v_fmaak_f32 v12, v240, v12, 0xc0135761
	v_mul_f32_e32 v13, v2, v2
	v_mul_f32_e32 v12, v3, v12
	v_fmaak_f32 v13, v240, v13, 0xc0135761
	v_mul_f32_e32 v13, v2, v13
	v_exp_f32_e32 v12, v12
	v_exp_f32_e32 v14, v13
	s_cmp_eq_u32 s24, -3
	v_add_f32_e32 v12, 1.0, v12
	v_rcp_f32_e32 v13, v12
	v_add_f32_e32 v12, 1.0, v14
	v_lshlrev_b32_e32 v14, 16, v16
	v_pk_fma_f32 v[0:1], v[96:97], v[14:15], v[0:1]
	v_rcp_f32_e32 v12, v12
	v_mul_f32_e32 v14, v1, v1
	v_fmaak_f32 v14, v240, v14, 0xc0135761
	v_mul_f32_e32 v15, v0, v0
	v_mul_f32_e32 v14, v1, v14
	v_fmaak_f32 v15, v240, v15, 0xc0135761
	v_mul_f32_e32 v15, v0, v15
	v_exp_f32_e32 v14, v14
	v_exp_f32_e32 v16, v15
	v_rcp_f32_e32 v10, v10
	v_add_f32_e32 v14, 1.0, v14
	v_rcp_f32_e32 v15, v14
	v_add_f32_e32 v14, 1.0, v16
	v_rcp_f32_e32 v14, v14
	s_cselect_b64 vcc, -1, 0
	s_ashr_i32 s15, s14, 31
	v_pk_mul_f32 v[6:7], v[6:7], v[8:9]
	v_lshl_add_u64 v[8:9], s[14:15], 4, v[120:121]
	v_cndmask_b32_e64 v9, v9, 0, vcc
	v_cndmask_b32_e32 v8, v8, v154, vcc
	v_pk_mul_f32 v[2:3], v[2:3], v[12:13]
	v_pk_mul_f32 v[0:1], v[0:1], v[14:15]
	v_lshlrev_b64 v[8:9], 11, v[8:9]
	v_pk_mul_f32 v[4:5], v[4:5], v[10:11]
	v_lshl_add_u64 v[8:9], v[126:127], 0, v[8:9]
	v_cvt_pk_bf16_f32 v0, v0, v1
	v_cvt_pk_bf16_f32 v1, v2, v3
	v_cvt_pk_bf16_f32 v2, v4, v5
	v_cvt_pk_bf16_f32 v3, v6, v7
	global_store_dwordx2 v[8:9], v[0:1], off
	global_store_dwordx2 v[8:9], v[2:3], off offset:16
	s_branch .LBB0_186

.LBB0_270:
	s_ashr_i32 s25, s24, 31
	s_lshl_b64 s[22:23], s[24:25], 19
	s_add_u32 s26, s16, s22
	s_addc_u32 s27, s17, s23
	s_and_b64 s[22:23], s[4:5], exec
	s_cselect_b32 s25, s27, s15
	s_cselect_b32 s56, s26, s14
	s_ashr_i32 s21, s20, 31
	s_lshl_b64 s[22:23], s[20:21], 19
	s_add_u32 s28, s34, s22
	s_addc_u32 s29, s35, s23
	s_and_b64 s[22:23], s[4:5], exec
	s_cselect_b32 s21, s29, s3
	s_cselect_b32 s57, s28, s2
	s_add_u32 s14, s14, 0x40080
	s_addc_u32 s15, s15, 0
	s_add_u32 s58, s2, 0x100
	s_addc_u32 s59, s3, 0
	s_mov_b32 s64, -2
	s_waitcnt lgkmcnt(0)
	s_waitcnt vmcnt(0)
	ds_read_b128 v[136:139], v159
	ds_read_b128 v[164:167], v159 offset:1024
	ds_read_b128 v[180:183], v159 offset:2048
	ds_read_b128 v[184:187], v159 offset:3072
	ds_read_b128 v[188:191], v160
	ds_read_b128 v[196:199], v160 offset:1024
	ds_read_b128 v[200:203], v160 offset:2048
	ds_read_b128 v[204:207], v160 offset:3072
	s_add_u32 s2, s14, 0xfffc0080
	s_addc_u32 s3, s15, -1
	s_cmp_eq_u32 s64, 12
	s_cselect_b32 s23, s25, s3
	s_cselect_b32 s22, s56, s2
	s_cselect_b32 s3, s21, s59
	s_cselect_b32 s2, s57, s58
	v_lshl_add_u64 v[168:169], s[14:15], 0, v[128:129]
	s_add_i32 m0, s31, 0xc000
	ds_read_b128 v[208:211], v161
	ds_read_b128 v[212:215], v161 offset:1024
	ds_read_b128 v[216:219], v161 offset:2048
	ds_read_b128 v[220:223], v161 offset:3072
	ds_read_b128 v[224:227], v161 offset:4096
	ds_read_b128 v[228:231], v161 offset:5120
	ds_read_b128 v[232:235], v161 offset:6144
	ds_read_b128 v[236:239], v161 offset:7168
	global_load_lds_dwordx4 v[168:169], off
	v_lshl_add_u64 v[168:169], s[14:15], 0, v[130:131]
	s_add_i32 m0, s31, 0xe000
	s_nop 0
	global_load_lds_dwordx4 v[168:169], off
	s_waitcnt vmcnt(8)
	s_waitcnt lgkmcnt(0)
	s_barrier
	s_setprio 1
	s_waitcnt lgkmcnt(0)
	v_mfma_f32_16x16x32_bf16 v[116:119], v[136:139], v[208:211], 0
	v_mfma_f32_16x16x32_bf16 v[112:115], v[180:183], v[208:211], 0
	v_mfma_f32_16x16x32_bf16 v[108:111], v[136:139], v[216:219], 0
	v_mfma_f32_16x16x32_bf16 v[104:107], v[180:183], v[216:219], 0
	v_mfma_f32_16x16x32_bf16 v[92:95], v[136:139], v[224:227], 0
	v_mfma_f32_16x16x32_bf16 v[88:91], v[180:183], v[224:227], 0
	v_mfma_f32_16x16x32_bf16 v[76:79], v[136:139], v[232:235], 0
	v_mfma_f32_16x16x32_bf16 v[72:75], v[180:183], v[232:235], 0
	v_mfma_f32_16x16x32_bf16 v[116:119], v[164:167], v[212:215], v[116:119]
	v_mfma_f32_16x16x32_bf16 v[112:115], v[184:187], v[212:215], v[112:115]
	v_mfma_f32_16x16x32_bf16 v[108:111], v[164:167], v[220:223], v[108:111]
	v_mfma_f32_16x16x32_bf16 v[104:107], v[184:187], v[220:223], v[104:107]
	v_mfma_f32_16x16x32_bf16 v[92:95], v[164:167], v[228:231], v[92:95]
	v_mfma_f32_16x16x32_bf16 v[88:91], v[184:187], v[228:231], v[88:91]
	v_mfma_f32_16x16x32_bf16 v[76:79], v[164:167], v[236:239], v[76:79]
	v_mfma_f32_16x16x32_bf16 v[72:75], v[184:187], v[236:239], v[72:75]
	s_setprio 0
	s_setprio 1
	v_mfma_f32_16x16x32_bf16 v[124:127], v[188:191], v[208:211], 0
	v_mfma_f32_16x16x32_bf16 v[120:123], v[200:203], v[208:211], 0
	v_mfma_f32_16x16x32_bf16 v[100:103], v[188:191], v[216:219], 0
	v_mfma_f32_16x16x32_bf16 v[96:99], v[200:203], v[216:219], 0
	v_mfma_f32_16x16x32_bf16 v[84:87], v[188:191], v[224:227], 0
	v_mfma_f32_16x16x32_bf16 v[80:83], v[200:203], v[224:227], 0
	v_mfma_f32_16x16x32_bf16 v[68:71], v[188:191], v[232:235], 0
	v_mfma_f32_16x16x32_bf16 v[64:67], v[200:203], v[232:235], 0
	v_mfma_f32_16x16x32_bf16 v[124:127], v[196:199], v[212:215], v[124:127]
	v_mfma_f32_16x16x32_bf16 v[120:123], v[204:207], v[212:215], v[120:123]
	v_mfma_f32_16x16x32_bf16 v[100:103], v[196:199], v[220:223], v[100:103]
	v_mfma_f32_16x16x32_bf16 v[96:99], v[204:207], v[220:223], v[96:99]
	v_mfma_f32_16x16x32_bf16 v[84:87], v[196:199], v[228:231], v[84:87]
	v_mfma_f32_16x16x32_bf16 v[80:83], v[204:207], v[228:231], v[80:83]
	v_mfma_f32_16x16x32_bf16 v[68:71], v[196:199], v[236:239], v[68:71]
	v_mfma_f32_16x16x32_bf16 v[64:67], v[204:207], v[236:239], v[64:67]
	s_setprio 0
	s_barrier
	s_add_i32 s65, s49, s37
	v_lshl_add_u64 v[168:169], s[2:3], 0, v[142:143]
	s_mov_b32 m0, s65
	ds_read_b128 v[208:211], v161 offset:16384
	ds_read_b128 v[212:215], v161 offset:17408
	ds_read_b128 v[216:219], v161 offset:18432
	ds_read_b128 v[220:223], v161 offset:19456
	ds_read_b128 v[224:227], v161 offset:20480
	ds_read_b128 v[228:231], v161 offset:21504
	ds_read_b128 v[232:235], v161 offset:22528
	ds_read_b128 v[236:239], v161 offset:23552
	global_load_lds_dwordx4 v[168:169], off
	s_add_i32 m0, s65, 0x2000
	s_add_u32 s66, s2, 0x40000
	v_lshl_add_u64 v[192:193], s[2:3], 0, v[146:147]
	s_addc_u32 s67, s3, 0
	s_add_i32 s65, s50, s37
	global_load_lds_dwordx4 v[192:193], off
	v_lshl_add_u64 v[240:241], s[66:67], 0, v[142:143]
	s_mov_b32 m0, s65
	v_lshl_add_u64 v[242:243], s[22:23], 0, v[144:145]
	global_load_lds_dwordx4 v[240:241], off
	v_lshl_add_u64 v[240:241], s[66:67], 0, v[146:147]
	s_add_i32 m0, s65, 0x2000
	s_nop 0
	global_load_lds_dwordx4 v[240:241], off
	v_lshl_add_u64 v[240:241], s[22:23], 0, v[140:141]
	s_mov_b32 m0, s31
	s_nop 0
	global_load_lds_dwordx4 v[240:241], off
	s_mov_b32 m0, s38
	s_nop 0
	global_load_lds_dwordx4 v[242:243], off
	s_waitcnt vmcnt(8)
	s_waitcnt lgkmcnt(0)
	s_barrier
	s_setprio 1
	s_waitcnt lgkmcnt(0)
	v_mfma_f32_16x16x32_bf16 v[52:55], v[136:139], v[208:211], 0
	v_mfma_f32_16x16x32_bf16 v[48:51], v[180:183], v[208:211], 0
	v_mfma_f32_16x16x32_bf16 v[44:47], v[136:139], v[216:219], 0
	v_mfma_f32_16x16x32_bf16 v[40:43], v[180:183], v[216:219], 0
	v_mfma_f32_16x16x32_bf16 v[28:31], v[136:139], v[224:227], 0
	v_mfma_f32_16x16x32_bf16 v[24:27], v[180:183], v[224:227], 0
	v_mfma_f32_16x16x32_bf16 v[12:15], v[136:139], v[232:235], 0
	v_mfma_f32_16x16x32_bf16 v[8:11], v[180:183], v[232:235], 0
	v_mfma_f32_16x16x32_bf16 v[52:55], v[164:167], v[212:215], v[52:55]
	v_mfma_f32_16x16x32_bf16 v[48:51], v[184:187], v[212:215], v[48:51]
	v_mfma_f32_16x16x32_bf16 v[44:47], v[164:167], v[220:223], v[44:47]
	v_mfma_f32_16x16x32_bf16 v[40:43], v[184:187], v[220:223], v[40:43]
	v_mfma_f32_16x16x32_bf16 v[28:31], v[164:167], v[228:231], v[28:31]
	v_mfma_f32_16x16x32_bf16 v[24:27], v[184:187], v[228:231], v[24:27]
	v_mfma_f32_16x16x32_bf16 v[12:15], v[164:167], v[236:239], v[12:15]
	v_mfma_f32_16x16x32_bf16 v[8:11], v[184:187], v[236:239], v[8:11]
	s_setprio 0
	s_setprio 1
	v_mfma_f32_16x16x32_bf16 v[60:63], v[188:191], v[208:211], 0
	v_mfma_f32_16x16x32_bf16 v[56:59], v[200:203], v[208:211], 0
	v_mfma_f32_16x16x32_bf16 v[36:39], v[188:191], v[216:219], 0
	v_mfma_f32_16x16x32_bf16 v[32:35], v[200:203], v[216:219], 0
	v_mfma_f32_16x16x32_bf16 v[20:23], v[188:191], v[224:227], 0
	v_mfma_f32_16x16x32_bf16 v[16:19], v[200:203], v[224:227], 0
	v_mfma_f32_16x16x32_bf16 v[4:7], v[188:191], v[232:235], 0
	v_mfma_f32_16x16x32_bf16 v[0:3], v[200:203], v[232:235], 0
	v_mfma_f32_16x16x32_bf16 v[60:63], v[196:199], v[212:215], v[60:63]
	v_mfma_f32_16x16x32_bf16 v[56:59], v[204:207], v[212:215], v[56:59]
	v_mfma_f32_16x16x32_bf16 v[36:39], v[196:199], v[220:223], v[36:39]
	v_mfma_f32_16x16x32_bf16 v[32:35], v[204:207], v[220:223], v[32:35]
	v_mfma_f32_16x16x32_bf16 v[20:23], v[196:199], v[228:231], v[20:23]
	v_mfma_f32_16x16x32_bf16 v[16:19], v[204:207], v[228:231], v[16:19]
	v_mfma_f32_16x16x32_bf16 v[4:7], v[196:199], v[236:239], v[4:7]
	v_mfma_f32_16x16x32_bf16 v[0:3], v[204:207], v[236:239], v[0:3]
	s_setprio 0
	s_barrier
	s_add_i32 s65, 0, 0x18000
	v_add_u32_e32 v163, s65, v156
	s_add_i32 s66, 0, 0x1c000
	ds_read_b128 v[136:139], v163
	ds_read_b128 v[164:167], v163 offset:1024
	ds_read_b128 v[180:183], v163 offset:2048
	ds_read_b128 v[184:187], v163 offset:3072
	v_add_u32_e32 v163, s66, v156
	ds_read_b128 v[188:191], v163
	ds_read_b128 v[196:199], v163 offset:1024
	ds_read_b128 v[200:203], v163 offset:2048
	ds_read_b128 v[204:207], v163 offset:3072
	s_add_u32 s22, s22, 0x40000
	s_addc_u32 s23, s23, 0
	s_mov_b32 m0, s39
	v_lshl_add_u64 v[244:245], s[22:23], 0, v[140:141]
	ds_read_b128 v[208:211], v161 offset:32768
	ds_read_b128 v[212:215], v161 offset:33792
	ds_read_b128 v[216:219], v161 offset:34816
	ds_read_b128 v[220:223], v161 offset:35840
	ds_read_b128 v[224:227], v161 offset:36864
	ds_read_b128 v[228:231], v161 offset:37888
	ds_read_b128 v[232:235], v161 offset:38912
	ds_read_b128 v[236:239], v161 offset:39936
	global_load_lds_dwordx4 v[244:245], off
	v_lshl_add_u64 v[244:245], s[22:23], 0, v[144:145]
	s_mov_b32 m0, s40
	s_nop 0
	global_load_lds_dwordx4 v[244:245], off
	s_waitcnt vmcnt(8)
	s_waitcnt lgkmcnt(0)
	s_barrier
	s_setprio 1
	s_waitcnt lgkmcnt(0)
	v_mfma_f32_16x16x32_bf16 v[116:119], v[136:139], v[208:211], v[116:119]
	v_mfma_f32_16x16x32_bf16 v[112:115], v[180:183], v[208:211], v[112:115]
	v_mfma_f32_16x16x32_bf16 v[108:111], v[136:139], v[216:219], v[108:111]
	v_mfma_f32_16x16x32_bf16 v[104:107], v[180:183], v[216:219], v[104:107]
	v_mfma_f32_16x16x32_bf16 v[92:95], v[136:139], v[224:227], v[92:95]
	v_mfma_f32_16x16x32_bf16 v[88:91], v[180:183], v[224:227], v[88:91]
	v_mfma_f32_16x16x32_bf16 v[76:79], v[136:139], v[232:235], v[76:79]
	v_mfma_f32_16x16x32_bf16 v[72:75], v[180:183], v[232:235], v[72:75]
	v_mfma_f32_16x16x32_bf16 v[116:119], v[164:167], v[212:215], v[116:119]
	v_mfma_f32_16x16x32_bf16 v[112:115], v[184:187], v[212:215], v[112:115]
	v_mfma_f32_16x16x32_bf16 v[108:111], v[164:167], v[220:223], v[108:111]
	v_mfma_f32_16x16x32_bf16 v[104:107], v[184:187], v[220:223], v[104:107]
	v_mfma_f32_16x16x32_bf16 v[92:95], v[164:167], v[228:231], v[92:95]
	v_mfma_f32_16x16x32_bf16 v[88:91], v[184:187], v[228:231], v[88:91]
	v_mfma_f32_16x16x32_bf16 v[76:79], v[164:167], v[236:239], v[76:79]
	v_mfma_f32_16x16x32_bf16 v[72:75], v[184:187], v[236:239], v[72:75]
	s_setprio 0
	s_setprio 1
	v_mfma_f32_16x16x32_bf16 v[124:127], v[188:191], v[208:211], v[124:127]
	v_mfma_f32_16x16x32_bf16 v[120:123], v[200:203], v[208:211], v[120:123]
	v_mfma_f32_16x16x32_bf16 v[100:103], v[188:191], v[216:219], v[100:103]
	v_mfma_f32_16x16x32_bf16 v[96:99], v[200:203], v[216:219], v[96:99]
	v_mfma_f32_16x16x32_bf16 v[84:87], v[188:191], v[224:227], v[84:87]
	v_mfma_f32_16x16x32_bf16 v[80:83], v[200:203], v[224:227], v[80:83]
	v_mfma_f32_16x16x32_bf16 v[68:71], v[188:191], v[232:235], v[68:71]
	v_mfma_f32_16x16x32_bf16 v[64:67], v[200:203], v[232:235], v[64:67]
	v_mfma_f32_16x16x32_bf16 v[124:127], v[196:199], v[212:215], v[124:127]
	v_mfma_f32_16x16x32_bf16 v[120:123], v[204:207], v[212:215], v[120:123]
	v_mfma_f32_16x16x32_bf16 v[100:103], v[196:199], v[220:223], v[100:103]
	v_mfma_f32_16x16x32_bf16 v[96:99], v[204:207], v[220:223], v[96:99]
	v_mfma_f32_16x16x32_bf16 v[84:87], v[196:199], v[228:231], v[84:87]
	v_mfma_f32_16x16x32_bf16 v[80:83], v[204:207], v[228:231], v[80:83]
	v_mfma_f32_16x16x32_bf16 v[68:71], v[196:199], v[236:239], v[68:71]
	v_mfma_f32_16x16x32_bf16 v[64:67], v[204:207], v[236:239], v[64:67]
	s_setprio 0
	s_barrier
	s_add_i32 s22, s65, s37
	v_lshl_add_u64 v[168:169], v[168:169], 0, s[10:11]
	s_mov_b32 m0, s22
	ds_read_b128 v[208:211], v161 offset:49152
	ds_read_b128 v[212:215], v161 offset:50176
	ds_read_b128 v[216:219], v161 offset:51200
	ds_read_b128 v[220:223], v161 offset:52224
	ds_read_b128 v[224:227], v161 offset:53248
	ds_read_b128 v[228:231], v161 offset:54272
	ds_read_b128 v[232:235], v161 offset:55296
	ds_read_b128 v[236:239], v161 offset:56320
	global_load_lds_dwordx4 v[168:169], off
	s_add_i32 m0, s22, 0x2000
	s_add_u32 s2, s2, 0x40080
	v_lshl_add_u64 v[168:169], v[192:193], 0, s[10:11]
	s_addc_u32 s3, s3, 0
	s_add_i32 s22, s66, s37
	global_load_lds_dwordx4 v[168:169], off
	v_lshl_add_u64 v[168:169], s[2:3], 0, v[142:143]
	s_mov_b32 m0, s22
	s_nop 0
	global_load_lds_dwordx4 v[168:169], off
	v_lshl_add_u64 v[168:169], s[2:3], 0, v[146:147]
	s_add_i32 m0, s22, 0x2000
	s_nop 0
	global_load_lds_dwordx4 v[168:169], off
	v_lshl_add_u64 v[168:169], v[240:241], 0, s[10:11]
	s_mov_b32 m0, s43
	s_nop 0
	global_load_lds_dwordx4 v[168:169], off
	v_lshl_add_u64 v[168:169], v[242:243], 0, s[10:11]
	s_mov_b32 m0, s44
	s_nop 0
	global_load_lds_dwordx4 v[168:169], off
	s_waitcnt vmcnt(8)
	s_waitcnt lgkmcnt(0)
	s_barrier
	s_setprio 1
	s_waitcnt lgkmcnt(0)
	v_mfma_f32_16x16x32_bf16 v[52:55], v[136:139], v[208:211], v[52:55]
	v_mfma_f32_16x16x32_bf16 v[48:51], v[180:183], v[208:211], v[48:51]
	v_mfma_f32_16x16x32_bf16 v[44:47], v[136:139], v[216:219], v[44:47]
	v_mfma_f32_16x16x32_bf16 v[40:43], v[180:183], v[216:219], v[40:43]
	v_mfma_f32_16x16x32_bf16 v[28:31], v[136:139], v[224:227], v[28:31]
	v_mfma_f32_16x16x32_bf16 v[24:27], v[180:183], v[224:227], v[24:27]
	v_mfma_f32_16x16x32_bf16 v[12:15], v[136:139], v[232:235], v[12:15]
	v_mfma_f32_16x16x32_bf16 v[8:11], v[180:183], v[232:235], v[8:11]
	v_mfma_f32_16x16x32_bf16 v[52:55], v[164:167], v[212:215], v[52:55]
	v_mfma_f32_16x16x32_bf16 v[48:51], v[184:187], v[212:215], v[48:51]
	v_mfma_f32_16x16x32_bf16 v[44:47], v[164:167], v[220:223], v[44:47]
	v_mfma_f32_16x16x32_bf16 v[40:43], v[184:187], v[220:223], v[40:43]
	v_mfma_f32_16x16x32_bf16 v[28:31], v[164:167], v[228:231], v[28:31]
	v_mfma_f32_16x16x32_bf16 v[24:27], v[184:187], v[228:231], v[24:27]
	v_mfma_f32_16x16x32_bf16 v[12:15], v[164:167], v[236:239], v[12:15]
	v_mfma_f32_16x16x32_bf16 v[8:11], v[184:187], v[236:239], v[8:11]
	s_setprio 0
	s_setprio 1
	v_mfma_f32_16x16x32_bf16 v[60:63], v[188:191], v[208:211], v[60:63]
	v_mfma_f32_16x16x32_bf16 v[56:59], v[200:203], v[208:211], v[56:59]
	v_mfma_f32_16x16x32_bf16 v[36:39], v[188:191], v[216:219], v[36:39]
	v_mfma_f32_16x16x32_bf16 v[32:35], v[200:203], v[216:219], v[32:35]
	v_mfma_f32_16x16x32_bf16 v[20:23], v[188:191], v[224:227], v[20:23]
	v_mfma_f32_16x16x32_bf16 v[16:19], v[200:203], v[224:227], v[16:19]
	v_mfma_f32_16x16x32_bf16 v[4:7], v[188:191], v[232:235], v[4:7]
	v_mfma_f32_16x16x32_bf16 v[0:3], v[200:203], v[232:235], v[0:3]
	v_mfma_f32_16x16x32_bf16 v[60:63], v[196:199], v[212:215], v[60:63]
	v_mfma_f32_16x16x32_bf16 v[56:59], v[204:207], v[212:215], v[56:59]
	v_mfma_f32_16x16x32_bf16 v[36:39], v[196:199], v[220:223], v[36:39]
	v_mfma_f32_16x16x32_bf16 v[32:35], v[204:207], v[220:223], v[32:35]
	v_mfma_f32_16x16x32_bf16 v[20:23], v[196:199], v[228:231], v[20:23]
	v_mfma_f32_16x16x32_bf16 v[16:19], v[204:207], v[228:231], v[16:19]
	v_mfma_f32_16x16x32_bf16 v[4:7], v[196:199], v[236:239], v[4:7]
	v_mfma_f32_16x16x32_bf16 v[0:3], v[204:207], v[236:239], v[0:3]
	s_setprio 0
	s_barrier
	s_add_i32 s64, s64, 2
	s_add_u32 s14, s14, 0x100
	s_addc_u32 s15, s15, 0
	s_add_u32 s58, s58, 0x100
	s_addc_u32 s59, s59, 0
	s_cmp_gt_u32 s64, 13
	s_cbranch_scc1 .Lgemm_kdone_0

.Lgemm_kdone_0:
	s_and_b64 vcc, exec, s[12:13]
	s_cbranch_vccz .LBB0_274
	s_barrier

.LBB0_367:
	s_ashr_i32 s25, s24, 31
	s_lshl_b64 s[22:23], s[24:25], 19
	s_add_u32 s26, s84, s22
	s_addc_u32 s27, s85, s23
	s_and_b64 s[22:23], s[0:1], exec
	s_cselect_b32 s25, s27, s15
	s_cselect_b32 s50, s26, s14
	s_ashr_i32 s21, s20, 31
	s_lshl_b64 s[22:23], s[20:21], 19
	s_add_u32 s28, s30, s22
	s_addc_u32 s29, s31, s23
	s_and_b64 s[22:23], s[0:1], exec
	s_cselect_b32 s21, s29, s3
	s_cselect_b32 s51, s28, s2
	s_add_u32 s14, s14, 0x40080
	s_addc_u32 s15, s15, 0
	s_add_u32 s52, s2, 0x100
	s_addc_u32 s53, s3, 0
	s_mov_b32 s54, -2
	s_waitcnt vmcnt(0)
	ds_read_b128 v[158:161], v154
	ds_read_b128 v[162:165], v154 offset:1024
	ds_read_b128 v[166:169], v154 offset:2048
	ds_read_b128 v[182:185], v154 offset:3072
	ds_read_b128 v[186:189], v155
	ds_read_b128 v[190:193], v155 offset:1024
	ds_read_b128 v[196:199], v155 offset:2048
	ds_read_b128 v[200:203], v155 offset:3072
	s_add_u32 s2, s14, 0xfffc0080
	s_addc_u32 s3, s15, -1
	s_cmp_eq_u32 s54, 12
	s_cselect_b32 s23, s25, s3
	s_cselect_b32 s22, s50, s2
	s_cselect_b32 s3, s21, s53
	s_cselect_b32 s2, s51, s52
	v_lshl_add_u64 v[136:137], s[14:15], 0, v[128:129]
	s_add_i32 m0, s37, 0xc000
	ds_read_b128 v[204:207], v156
	ds_read_b128 v[208:211], v156 offset:1024
	ds_read_b128 v[212:215], v156 offset:2048
	ds_read_b128 v[216:219], v156 offset:3072
	ds_read_b128 v[220:223], v156 offset:4096
	ds_read_b128 v[224:227], v156 offset:5120
	ds_read_b128 v[228:231], v156 offset:6144
	ds_read_b128 v[232:235], v156 offset:7168
	global_load_lds_dwordx4 v[136:137], off
	v_lshl_add_u64 v[136:137], s[14:15], 0, v[130:131]
	s_add_i32 m0, s37, 0xe000
	s_nop 0
	global_load_lds_dwordx4 v[136:137], off
	s_waitcnt vmcnt(8)
	s_waitcnt lgkmcnt(0)
	s_barrier
	s_setprio 1
	s_waitcnt lgkmcnt(0)
	v_mfma_f32_16x16x32_bf16 v[112:115], v[158:161], v[204:207], 0
	v_mfma_f32_16x16x32_bf16 v[108:111], v[166:169], v[204:207], 0
	v_mfma_f32_16x16x32_bf16 v[104:107], v[158:161], v[212:215], 0
	v_mfma_f32_16x16x32_bf16 v[100:103], v[166:169], v[212:215], 0
	v_mfma_f32_16x16x32_bf16 v[92:95], v[158:161], v[220:223], 0
	v_mfma_f32_16x16x32_bf16 v[84:87], v[166:169], v[220:223], 0
	v_mfma_f32_16x16x32_bf16 v[76:79], v[158:161], v[228:231], 0
	v_mfma_f32_16x16x32_bf16 v[68:71], v[166:169], v[228:231], 0
	v_mfma_f32_16x16x32_bf16 v[112:115], v[162:165], v[208:211], v[112:115]
	v_mfma_f32_16x16x32_bf16 v[108:111], v[182:185], v[208:211], v[108:111]
	v_mfma_f32_16x16x32_bf16 v[104:107], v[162:165], v[216:219], v[104:107]
	v_mfma_f32_16x16x32_bf16 v[100:103], v[182:185], v[216:219], v[100:103]
	v_mfma_f32_16x16x32_bf16 v[92:95], v[162:165], v[224:227], v[92:95]
	v_mfma_f32_16x16x32_bf16 v[84:87], v[182:185], v[224:227], v[84:87]
	v_mfma_f32_16x16x32_bf16 v[76:79], v[162:165], v[232:235], v[76:79]
	v_mfma_f32_16x16x32_bf16 v[68:71], v[182:185], v[232:235], v[68:71]
	s_setprio 0
	s_setprio 1
	v_mfma_f32_16x16x32_bf16 v[124:127], v[186:189], v[204:207], 0
	v_mfma_f32_16x16x32_bf16 v[120:123], v[196:199], v[204:207], 0
	v_mfma_f32_16x16x32_bf16 v[116:119], v[186:189], v[212:215], 0
	v_mfma_f32_16x16x32_bf16 v[96:99], v[196:199], v[212:215], 0
	v_mfma_f32_16x16x32_bf16 v[88:91], v[186:189], v[220:223], 0
	v_mfma_f32_16x16x32_bf16 v[80:83], v[196:199], v[220:223], 0
	v_mfma_f32_16x16x32_bf16 v[72:75], v[186:189], v[228:231], 0
	v_mfma_f32_16x16x32_bf16 v[64:67], v[196:199], v[228:231], 0
	v_mfma_f32_16x16x32_bf16 v[124:127], v[190:193], v[208:211], v[124:127]
	v_mfma_f32_16x16x32_bf16 v[120:123], v[200:203], v[208:211], v[120:123]
	v_mfma_f32_16x16x32_bf16 v[116:119], v[190:193], v[216:219], v[116:119]
	v_mfma_f32_16x16x32_bf16 v[96:99], v[200:203], v[216:219], v[96:99]
	v_mfma_f32_16x16x32_bf16 v[88:91], v[190:193], v[224:227], v[88:91]
	v_mfma_f32_16x16x32_bf16 v[80:83], v[200:203], v[224:227], v[80:83]
	v_mfma_f32_16x16x32_bf16 v[72:75], v[190:193], v[232:235], v[72:75]
	v_mfma_f32_16x16x32_bf16 v[64:67], v[200:203], v[232:235], v[64:67]
	s_setprio 0
	s_barrier
	s_add_i32 s55, s46, s34
	v_lshl_add_u64 v[136:137], s[2:3], 0, v[142:143]
	s_mov_b32 m0, s55
	ds_read_b128 v[204:207], v156 offset:16384
	ds_read_b128 v[208:211], v156 offset:17408
	ds_read_b128 v[212:215], v156 offset:18432
	ds_read_b128 v[216:219], v156 offset:19456
	ds_read_b128 v[220:223], v156 offset:20480
	ds_read_b128 v[224:227], v156 offset:21504
	ds_read_b128 v[228:231], v156 offset:22528
	ds_read_b128 v[232:235], v156 offset:23552
	global_load_lds_dwordx4 v[136:137], off
	s_add_i32 m0, s55, 0x2000
	s_add_u32 s56, s2, 0x40000
	v_lshl_add_u64 v[236:237], s[2:3], 0, v[146:147]
	s_addc_u32 s57, s3, 0
	s_add_i32 s55, s47, s34
	global_load_lds_dwordx4 v[236:237], off
	v_lshl_add_u64 v[238:239], s[56:57], 0, v[142:143]
	s_mov_b32 m0, s55
	v_lshl_add_u64 v[240:241], s[22:23], 0, v[144:145]
	global_load_lds_dwordx4 v[238:239], off
	v_lshl_add_u64 v[238:239], s[56:57], 0, v[146:147]
	s_add_i32 m0, s55, 0x2000
	s_nop 0
	global_load_lds_dwordx4 v[238:239], off
	v_lshl_add_u64 v[238:239], s[22:23], 0, v[140:141]
	s_mov_b32 m0, s37
	s_nop 0
	global_load_lds_dwordx4 v[238:239], off
	s_mov_b32 m0, s38
	s_nop 0
	global_load_lds_dwordx4 v[240:241], off
	s_waitcnt vmcnt(8)
	s_waitcnt lgkmcnt(0)
	s_barrier
	s_setprio 1
	s_waitcnt lgkmcnt(0)
	v_mfma_f32_16x16x32_bf16 v[60:63], v[158:161], v[204:207], 0
	v_mfma_f32_16x16x32_bf16 v[52:55], v[166:169], v[204:207], 0
	v_mfma_f32_16x16x32_bf16 v[44:47], v[158:161], v[212:215], 0
	v_mfma_f32_16x16x32_bf16 v[36:39], v[166:169], v[212:215], 0
	v_mfma_f32_16x16x32_bf16 v[28:31], v[158:161], v[220:223], 0
	v_mfma_f32_16x16x32_bf16 v[20:23], v[166:169], v[220:223], 0
	v_mfma_f32_16x16x32_bf16 v[12:15], v[158:161], v[228:231], 0
	v_mfma_f32_16x16x32_bf16 v[4:7], v[166:169], v[228:231], 0
	v_mfma_f32_16x16x32_bf16 v[60:63], v[162:165], v[208:211], v[60:63]
	v_mfma_f32_16x16x32_bf16 v[52:55], v[182:185], v[208:211], v[52:55]
	v_mfma_f32_16x16x32_bf16 v[44:47], v[162:165], v[216:219], v[44:47]
	v_mfma_f32_16x16x32_bf16 v[36:39], v[182:185], v[216:219], v[36:39]
	v_mfma_f32_16x16x32_bf16 v[28:31], v[162:165], v[224:227], v[28:31]
	v_mfma_f32_16x16x32_bf16 v[20:23], v[182:185], v[224:227], v[20:23]
	v_mfma_f32_16x16x32_bf16 v[12:15], v[162:165], v[232:235], v[12:15]
	v_mfma_f32_16x16x32_bf16 v[4:7], v[182:185], v[232:235], v[4:7]
	s_setprio 0
	s_setprio 1
	v_mfma_f32_16x16x32_bf16 v[56:59], v[186:189], v[204:207], 0
	v_mfma_f32_16x16x32_bf16 v[48:51], v[196:199], v[204:207], 0
	v_mfma_f32_16x16x32_bf16 v[40:43], v[186:189], v[212:215], 0
	v_mfma_f32_16x16x32_bf16 v[32:35], v[196:199], v[212:215], 0
	v_mfma_f32_16x16x32_bf16 v[24:27], v[186:189], v[220:223], 0
	v_mfma_f32_16x16x32_bf16 v[16:19], v[196:199], v[220:223], 0
	v_mfma_f32_16x16x32_bf16 v[8:11], v[186:189], v[228:231], 0
	v_mfma_f32_16x16x32_bf16 v[0:3], v[196:199], v[228:231], 0
	v_mfma_f32_16x16x32_bf16 v[56:59], v[190:193], v[208:211], v[56:59]
	v_mfma_f32_16x16x32_bf16 v[48:51], v[200:203], v[208:211], v[48:51]
	v_mfma_f32_16x16x32_bf16 v[40:43], v[190:193], v[216:219], v[40:43]
	v_mfma_f32_16x16x32_bf16 v[32:35], v[200:203], v[216:219], v[32:35]
	v_mfma_f32_16x16x32_bf16 v[24:27], v[190:193], v[224:227], v[24:27]
	v_mfma_f32_16x16x32_bf16 v[16:19], v[200:203], v[224:227], v[16:19]
	v_mfma_f32_16x16x32_bf16 v[8:11], v[190:193], v[232:235], v[8:11]
	v_mfma_f32_16x16x32_bf16 v[0:3], v[200:203], v[232:235], v[0:3]
	s_setprio 0
	s_barrier
	s_add_i32 s55, 0, 0x18000
	s_add_i32 s56, 0, 0x1c000
	v_add_u32_e32 v182, s55, v139
	v_add_u32_e32 v200, s56, v139
	ds_read_b128 v[158:161], v182
	ds_read_b128 v[162:165], v182 offset:1024
	ds_read_b128 v[166:169], v182 offset:2048
	ds_read_b128 v[182:185], v182 offset:3072
	ds_read_b128 v[186:189], v200
	ds_read_b128 v[190:193], v200 offset:1024
	ds_read_b128 v[196:199], v200 offset:2048
	ds_read_b128 v[200:203], v200 offset:3072
	s_add_u32 s22, s22, 0x40000
	s_addc_u32 s23, s23, 0
	s_mov_b32 m0, s39
	v_lshl_add_u64 v[242:243], s[22:23], 0, v[140:141]
	ds_read_b128 v[204:207], v156 offset:32768
	ds_read_b128 v[208:211], v156 offset:33792
	ds_read_b128 v[212:215], v156 offset:34816
	ds_read_b128 v[216:219], v156 offset:35840
	ds_read_b128 v[220:223], v156 offset:36864
	ds_read_b128 v[224:227], v156 offset:37888
	ds_read_b128 v[228:231], v156 offset:38912
	ds_read_b128 v[232:235], v156 offset:39936
	global_load_lds_dwordx4 v[242:243], off
	v_lshl_add_u64 v[242:243], s[22:23], 0, v[144:145]
	s_mov_b32 m0, s40
	s_nop 0
	global_load_lds_dwordx4 v[242:243], off
	s_waitcnt vmcnt(8)
	s_waitcnt lgkmcnt(0)
	s_barrier
	s_setprio 1
	s_waitcnt lgkmcnt(0)
	v_mfma_f32_16x16x32_bf16 v[112:115], v[158:161], v[204:207], v[112:115]
	v_mfma_f32_16x16x32_bf16 v[108:111], v[166:169], v[204:207], v[108:111]
	v_mfma_f32_16x16x32_bf16 v[104:107], v[158:161], v[212:215], v[104:107]
	v_mfma_f32_16x16x32_bf16 v[100:103], v[166:169], v[212:215], v[100:103]
	v_mfma_f32_16x16x32_bf16 v[92:95], v[158:161], v[220:223], v[92:95]
	v_mfma_f32_16x16x32_bf16 v[84:87], v[166:169], v[220:223], v[84:87]
	v_mfma_f32_16x16x32_bf16 v[76:79], v[158:161], v[228:231], v[76:79]
	v_mfma_f32_16x16x32_bf16 v[68:71], v[166:169], v[228:231], v[68:71]
	v_mfma_f32_16x16x32_bf16 v[112:115], v[162:165], v[208:211], v[112:115]
	v_mfma_f32_16x16x32_bf16 v[108:111], v[182:185], v[208:211], v[108:111]
	v_mfma_f32_16x16x32_bf16 v[104:107], v[162:165], v[216:219], v[104:107]
	v_mfma_f32_16x16x32_bf16 v[100:103], v[182:185], v[216:219], v[100:103]
	v_mfma_f32_16x16x32_bf16 v[92:95], v[162:165], v[224:227], v[92:95]
	v_mfma_f32_16x16x32_bf16 v[84:87], v[182:185], v[224:227], v[84:87]
	v_mfma_f32_16x16x32_bf16 v[76:79], v[162:165], v[232:235], v[76:79]
	v_mfma_f32_16x16x32_bf16 v[68:71], v[182:185], v[232:235], v[68:71]
	s_setprio 0
	s_setprio 1
	v_mfma_f32_16x16x32_bf16 v[124:127], v[186:189], v[204:207], v[124:127]
	v_mfma_f32_16x16x32_bf16 v[120:123], v[196:199], v[204:207], v[120:123]
	v_mfma_f32_16x16x32_bf16 v[116:119], v[186:189], v[212:215], v[116:119]
	v_mfma_f32_16x16x32_bf16 v[96:99], v[196:199], v[212:215], v[96:99]
	v_mfma_f32_16x16x32_bf16 v[88:91], v[186:189], v[220:223], v[88:91]
	v_mfma_f32_16x16x32_bf16 v[80:83], v[196:199], v[220:223], v[80:83]
	v_mfma_f32_16x16x32_bf16 v[72:75], v[186:189], v[228:231], v[72:75]
	v_mfma_f32_16x16x32_bf16 v[64:67], v[196:199], v[228:231], v[64:67]
	v_mfma_f32_16x16x32_bf16 v[124:127], v[190:193], v[208:211], v[124:127]
	v_mfma_f32_16x16x32_bf16 v[120:123], v[200:203], v[208:211], v[120:123]
	v_mfma_f32_16x16x32_bf16 v[116:119], v[190:193], v[216:219], v[116:119]
	v_mfma_f32_16x16x32_bf16 v[96:99], v[200:203], v[216:219], v[96:99]
	v_mfma_f32_16x16x32_bf16 v[88:91], v[190:193], v[224:227], v[88:91]
	v_mfma_f32_16x16x32_bf16 v[80:83], v[200:203], v[224:227], v[80:83]
	v_mfma_f32_16x16x32_bf16 v[72:75], v[190:193], v[232:235], v[72:75]
	v_mfma_f32_16x16x32_bf16 v[64:67], v[200:203], v[232:235], v[64:67]
	s_setprio 0
	s_barrier
	s_add_i32 s22, s55, s34
	v_lshl_add_u64 v[136:137], v[136:137], 0, s[8:9]
	s_mov_b32 m0, s22
	ds_read_b128 v[204:207], v156 offset:49152
	ds_read_b128 v[208:211], v156 offset:50176
	ds_read_b128 v[212:215], v156 offset:51200
	ds_read_b128 v[216:219], v156 offset:52224
	ds_read_b128 v[220:223], v156 offset:53248
	ds_read_b128 v[224:227], v156 offset:54272
	ds_read_b128 v[228:231], v156 offset:55296
	ds_read_b128 v[232:235], v156 offset:56320
	global_load_lds_dwordx4 v[136:137], off
	s_add_i32 m0, s22, 0x2000
	s_add_u32 s2, s2, 0x40080
	v_lshl_add_u64 v[136:137], v[236:237], 0, s[8:9]
	s_addc_u32 s3, s3, 0
	s_add_i32 s22, s56, s34
	global_load_lds_dwordx4 v[136:137], off
	v_lshl_add_u64 v[136:137], s[2:3], 0, v[142:143]
	s_mov_b32 m0, s22
	s_nop 0
	global_load_lds_dwordx4 v[136:137], off
	v_lshl_add_u64 v[136:137], s[2:3], 0, v[146:147]
	s_add_i32 m0, s22, 0x2000
	s_nop 0
	global_load_lds_dwordx4 v[136:137], off
	v_lshl_add_u64 v[136:137], v[238:239], 0, s[8:9]
	s_mov_b32 m0, s42
	s_nop 0
	global_load_lds_dwordx4 v[136:137], off
	v_lshl_add_u64 v[136:137], v[240:241], 0, s[8:9]
	s_mov_b32 m0, s43
	s_nop 0
	global_load_lds_dwordx4 v[136:137], off
	s_waitcnt vmcnt(8)
	s_waitcnt lgkmcnt(0)
	s_barrier
	s_setprio 1
	s_waitcnt lgkmcnt(0)
	v_mfma_f32_16x16x32_bf16 v[60:63], v[158:161], v[204:207], v[60:63]
	v_mfma_f32_16x16x32_bf16 v[52:55], v[166:169], v[204:207], v[52:55]
	v_mfma_f32_16x16x32_bf16 v[44:47], v[158:161], v[212:215], v[44:47]
	v_mfma_f32_16x16x32_bf16 v[36:39], v[166:169], v[212:215], v[36:39]
	v_mfma_f32_16x16x32_bf16 v[28:31], v[158:161], v[220:223], v[28:31]
	v_mfma_f32_16x16x32_bf16 v[20:23], v[166:169], v[220:223], v[20:23]
	v_mfma_f32_16x16x32_bf16 v[12:15], v[158:161], v[228:231], v[12:15]
	v_mfma_f32_16x16x32_bf16 v[4:7], v[166:169], v[228:231], v[4:7]
	v_mfma_f32_16x16x32_bf16 v[60:63], v[162:165], v[208:211], v[60:63]
	v_mfma_f32_16x16x32_bf16 v[52:55], v[182:185], v[208:211], v[52:55]
	v_mfma_f32_16x16x32_bf16 v[44:47], v[162:165], v[216:219], v[44:47]
	v_mfma_f32_16x16x32_bf16 v[36:39], v[182:185], v[216:219], v[36:39]
	v_mfma_f32_16x16x32_bf16 v[28:31], v[162:165], v[224:227], v[28:31]
	v_mfma_f32_16x16x32_bf16 v[20:23], v[182:185], v[224:227], v[20:23]
	v_mfma_f32_16x16x32_bf16 v[12:15], v[162:165], v[232:235], v[12:15]
	v_mfma_f32_16x16x32_bf16 v[4:7], v[182:185], v[232:235], v[4:7]
	s_setprio 0
	s_setprio 1
	v_mfma_f32_16x16x32_bf16 v[56:59], v[186:189], v[204:207], v[56:59]
	v_mfma_f32_16x16x32_bf16 v[48:51], v[196:199], v[204:207], v[48:51]
	v_mfma_f32_16x16x32_bf16 v[40:43], v[186:189], v[212:215], v[40:43]
	v_mfma_f32_16x16x32_bf16 v[32:35], v[196:199], v[212:215], v[32:35]
	v_mfma_f32_16x16x32_bf16 v[24:27], v[186:189], v[220:223], v[24:27]
	v_mfma_f32_16x16x32_bf16 v[16:19], v[196:199], v[220:223], v[16:19]
	v_mfma_f32_16x16x32_bf16 v[8:11], v[186:189], v[228:231], v[8:11]
	v_mfma_f32_16x16x32_bf16 v[0:3], v[196:199], v[228:231], v[0:3]
	v_mfma_f32_16x16x32_bf16 v[56:59], v[190:193], v[208:211], v[56:59]
	v_mfma_f32_16x16x32_bf16 v[48:51], v[200:203], v[208:211], v[48:51]
	v_mfma_f32_16x16x32_bf16 v[40:43], v[190:193], v[216:219], v[40:43]
	v_mfma_f32_16x16x32_bf16 v[32:35], v[200:203], v[216:219], v[32:35]
	v_mfma_f32_16x16x32_bf16 v[24:27], v[190:193], v[224:227], v[24:27]
	v_mfma_f32_16x16x32_bf16 v[16:19], v[200:203], v[224:227], v[16:19]
	v_mfma_f32_16x16x32_bf16 v[8:11], v[190:193], v[232:235], v[8:11]
	v_mfma_f32_16x16x32_bf16 v[0:3], v[200:203], v[232:235], v[0:3]
	s_setprio 0
	s_barrier
	s_add_i32 s54, s54, 2
	s_add_u32 s14, s14, 0x100
	s_addc_u32 s15, s15, 0
	s_add_u32 s52, s52, 0x100
	s_addc_u32 s53, s53, 0
	s_cmp_gt_u32 s54, 13
	s_cbranch_scc1 .Lgemm_kdone_1

.Lgemm_kdone_1:
	s_and_b64 vcc, exec, s[18:19]
	s_cbranch_vccz .LBB0_371
	s_barrier
.LBB0_371:
	v_lshl_add_u32 v136, s4, 8, v138
	v_ashrrev_i32_e32 v137, 31, v136
	v_lshl_add_u64 v[162:163], v[136:137], 3, s[62:63]
	global_load_dwordx2 v[164:165], v[162:163], off
	global_load_dwordx2 v[166:167], v[162:163], off offset:128
	v_lshl_or_b32 v168, s5, 7, v153
	v_pk_mul_f32 v[188:189], v[108:109], v[120:121]
	v_mov_b64_e32 v[120:121], s[16:17]
	v_ashrrev_i32_e32 v169, 31, v168
	v_pk_mul_f32 v[192:193], v[104:105], v[116:117]
	v_or_b32_e32 v161, 16, v136
	v_or_b32_e32 v199, 32, v136
	v_or_b32_e32 v200, 48, v136
	v_add_u32_e32 v201, 0x80, v136
	v_add_u32_e32 v160, 0x90, v136
	v_add_u32_e32 v159, 0xa0, v136
	v_add_u32_e32 v158, 0xb0, v136
	v_mad_i64_i32 v[196:197], s[2:3], v136, s49, v[120:121]
	v_lshlrev_b64 v[116:117], 1, v[168:169]
	global_load_dwordx2 v[168:169], v[162:163], off offset:256
	global_load_dwordx2 v[136:137], v[162:163], off offset:384
	v_pk_mul_f32 v[190:191], v[106:107], v[118:119]
	v_pk_mul_f32 v[184:185], v[112:113], v[124:125]
	v_pk_mul_f32 v[186:187], v[110:111], v[122:123]
	v_pk_mul_f32 v[182:183], v[114:115], v[126:127]
	v_pk_mul_f32 v[96:97], v[100:101], v[96:97]
	v_pk_mul_f32 v[98:99], v[102:103], v[98:99]
	v_pk_mul_f32 v[88:89], v[92:93], v[88:89]
	v_pk_mul_f32 v[90:91], v[94:95], v[90:91]
	v_pk_mul_f32 v[80:81], v[84:85], v[80:81]
	v_pk_mul_f32 v[82:83], v[86:87], v[82:83]
	v_pk_mul_f32 v[72:73], v[76:77], v[72:73]
	v_pk_mul_f32 v[74:75], v[78:79], v[74:75]
	v_pk_mul_f32 v[64:65], v[68:69], v[64:65]
	v_pk_mul_f32 v[66:67], v[70:71], v[66:67]
	v_pk_mul_f32 v[56:57], v[60:61], v[56:57]
	v_pk_mul_f32 v[58:59], v[62:63], v[58:59]
	v_pk_mul_f32 v[48:49], v[52:53], v[48:49]
	v_pk_mul_f32 v[50:51], v[54:55], v[50:51]
	v_pk_mul_f32 v[40:41], v[44:45], v[40:41]
	v_pk_mul_f32 v[42:43], v[46:47], v[42:43]
	v_pk_mul_f32 v[32:33], v[36:37], v[32:33]
	v_pk_mul_f32 v[34:35], v[38:39], v[34:35]
	v_pk_mul_f32 v[24:25], v[28:29], v[24:25]
	v_pk_mul_f32 v[26:27], v[30:31], v[26:27]
	v_pk_mul_f32 v[16:17], v[20:21], v[16:17]
	v_pk_mul_f32 v[18:19], v[22:23], v[18:19]
	v_pk_mul_f32 v[8:9], v[12:13], v[8:9]
	v_pk_mul_f32 v[10:11], v[14:15], v[10:11]
	v_pk_mul_f32 v[0:1], v[4:5], v[0:1]
	v_pk_mul_f32 v[2:3], v[6:7], v[2:3]
	s_waitcnt vmcnt(0)
	v_ffbh_u32_e32 v118, v165
	v_ffbh_u32_e32 v119, v167
	v_min_u32_e32 v124, 32, v118
	v_min_u32_e32 v125, 32, v119
	v_lshlrev_b64 v[118:119], v124, v[164:165]
	v_lshlrev_b64 v[122:123], v125, v[166:167]
	v_min_u32_e32 v118, 1, v118
	v_min_u32_e32 v122, 1, v122
	v_or_b32_e32 v118, v119, v118
	v_or_b32_e32 v119, v123, v122
	v_cvt_f32_u32_e32 v118, v118
	v_cvt_f32_u32_e32 v119, v119
	v_sub_u32_e32 v122, 32, v124
	v_sub_u32_e32 v123, 32, v125
	v_ldexp_f32 v118, v118, v122
	v_ldexp_f32 v119, v119, v123
	v_fmamk_f32 v118, v118, 0x30800000, v157
	v_fmamk_f32 v119, v119, 0x30800000, v157
	v_rsq_f32_e32 v164, v118
	v_rsq_f32_e32 v165, v119
	global_load_dwordx2 v[126:127], v[162:163], off offset:1024
	global_load_dwordx2 v[124:125], v[162:163], off offset:1152
	global_load_dwordx2 v[122:123], v[162:163], off offset:1280
	global_load_dwordx2 v[118:119], v[162:163], off offset:1408
	v_mov_b32_e32 v166, v164
	v_mul_f32_e32 v164, 0xbfb8aa3b, v166
	v_lshl_add_u64 v[162:163], v[196:197], 0, v[116:117]
	v_mul_f32_e32 v196, 0xbfb8aa3b, v165
	v_pk_mul_f32 v[112:113], v[112:113], v[164:165] op_sel_hi:[1,0]
	v_pk_mul_f32 v[114:115], v[114:115], v[164:165] op_sel_hi:[1,0]
	v_pk_mul_f32 v[108:109], v[108:109], v[164:165] op_sel_hi:[1,0]
	v_pk_mul_f32 v[110:111], v[110:111], v[164:165] op_sel_hi:[1,0]
	v_pk_mul_f32 v[104:105], v[104:105], v[196:197] op_sel_hi:[1,0]
	v_exp_f32_e32 v112, v112
	v_exp_f32_e32 v113, v113
	v_exp_f32_e32 v114, v114
	v_exp_f32_e32 v115, v115
	v_exp_f32_e32 v108, v108
	v_exp_f32_e32 v109, v109
	v_exp_f32_e32 v110, v110
	v_exp_f32_e32 v111, v111
	v_exp_f32_e32 v104, v104
	v_exp_f32_e32 v105, v105
	v_pk_mul_f32 v[106:107], v[106:107], v[196:197] op_sel_hi:[1,0]
	v_pk_add_f32 v[112:113], v[112:113], 1.0 op_sel_hi:[1,0]
	v_exp_f32_e32 v106, v106
	v_exp_f32_e32 v107, v107
	v_pk_add_f32 v[114:115], v[114:115], 1.0 op_sel_hi:[1,0]
	v_pk_add_f32 v[108:109], v[108:109], 1.0 op_sel_hi:[1,0]
	v_pk_add_f32 v[110:111], v[110:111], 1.0 op_sel_hi:[1,0]
	v_pk_add_f32 v[104:105], v[104:105], 1.0 op_sel_hi:[1,0]
	v_rcp_f32_e32 v112, v112
	v_rcp_f32_e32 v113, v113
	v_rcp_f32_e32 v114, v114
	v_rcp_f32_e32 v115, v115
	v_rcp_f32_e32 v108, v108
	v_rcp_f32_e32 v109, v109
	v_rcp_f32_e32 v110, v110
	v_rcp_f32_e32 v111, v111
	v_rcp_f32_e32 v104, v104
	v_rcp_f32_e32 v105, v105
	v_mul_f32_e32 v166, v166, v166
	v_pk_add_f32 v[106:107], v[106:107], 1.0 op_sel_hi:[1,0]
	v_mul_f32_e32 v198, v165, v165
	v_rcp_f32_e32 v164, v106
	v_rcp_f32_e32 v165, v107
	v_pk_mul_f32 v[106:107], v[166:167], v[112:113] op_sel_hi:[0,1]
	v_pk_mul_f32 v[112:113], v[166:167], v[114:115] op_sel_hi:[0,1]
	v_pk_mul_f32 v[108:109], v[166:167], v[108:109] op_sel_hi:[0,1]
	v_pk_mul_f32 v[110:111], v[166:167], v[110:111] op_sel_hi:[0,1]
	v_pk_mul_f32 v[104:105], v[198:199], v[104:105] op_sel_hi:[0,1]
	v_pk_mul_f32 v[106:107], v[184:185], v[106:107]
	v_pk_mul_f32 v[112:113], v[182:183], v[112:113]
	v_pk_mul_f32 v[108:109], v[188:189], v[108:109]
	v_pk_mul_f32 v[110:111], v[186:187], v[110:111]
	v_pk_mul_f32 v[114:115], v[192:193], v[104:105]
	v_cvt_pk_bf16_f32 v104, v106, v107
	v_cvt_pk_bf16_f32 v105, v112, v113
	v_cvt_pk_bf16_f32 v106, v108, v109
	v_cvt_pk_bf16_f32 v107, v110, v111
	global_store_dwordx4 v[162:163], v[104:107], off
	v_cvt_pk_bf16_f32 v108, v114, v115
	s_nop 0
	v_pk_mul_f32 v[104:105], v[100:101], v[196:197] op_sel_hi:[1,0]
	v_pk_mul_f32 v[100:101], v[102:103], v[196:197] op_sel_hi:[1,0]
	v_exp_f32_e32 v104, v104
	v_exp_f32_e32 v105, v105
	v_exp_f32_e32 v100, v100
	v_exp_f32_e32 v101, v101
	v_pk_mul_f32 v[106:107], v[198:199], v[164:165] op_sel_hi:[0,1]
	v_pk_add_f32 v[104:105], v[104:105], 1.0 op_sel_hi:[1,0]
	v_pk_mul_f32 v[106:107], v[190:191], v[106:107]
	v_rcp_f32_e32 v104, v104
	v_rcp_f32_e32 v105, v105
	v_cvt_pk_bf16_f32 v109, v106, v107
	v_pk_mul_f32 v[102:103], v[198:199], v[104:105] op_sel_hi:[0,1]
	v_pk_mul_f32 v[96:97], v[96:97], v[102:103]
	s_nop 0
	v_cvt_pk_bf16_f32 v110, v96, v97
	v_pk_add_f32 v[96:97], v[100:101], 1.0 op_sel_hi:[1,0]
	v_ffbh_u32_e32 v100, v169
	v_min_u32_e32 v102, 32, v100
	v_lshlrev_b64 v[100:101], v102, v[168:169]
	v_rcp_f32_e32 v96, v96
	v_rcp_f32_e32 v97, v97
	v_min_u32_e32 v100, 1, v100
	v_or_b32_e32 v100, v101, v100
	v_cvt_f32_u32_e32 v100, v100
	v_pk_mul_f32 v[96:97], v[198:199], v[96:97] op_sel_hi:[0,1]
	v_pk_mul_f32 v[96:97], v[98:99], v[96:97]
	v_sub_u32_e32 v98, 32, v102
	v_ldexp_f32 v98, v100, v98
	v_fmamk_f32 v98, v98, 0x30800000, v157
	v_cvt_pk_bf16_f32 v111, v96, v97
	v_mad_i64_i32 v[96:97], s[2:3], v161, s49, v[120:121]
	v_rsq_f32_e32 v98, v98
	v_lshl_add_u64 v[96:97], v[96:97], 0, v[116:117]
	global_store_dwordx4 v[96:97], v[108:111], off
	v_mov_b32_e32 v99, v98
	v_mul_f32_e32 v98, 0xbfb8aa3b, v99
	v_pk_mul_f32 v[100:101], v[92:93], v[98:99] op_sel_hi:[1,0]
	v_pk_mul_f32 v[92:93], v[94:95], v[98:99] op_sel_hi:[1,0]
	v_exp_f32_e32 v100, v100
	v_exp_f32_e32 v101, v101
	v_exp_f32_e32 v92, v92
	v_exp_f32_e32 v93, v93
	v_mul_f32_e32 v96, v99, v99
	v_pk_add_f32 v[100:101], v[100:101], 1.0 op_sel_hi:[1,0]
	v_pk_add_f32 v[92:93], v[92:93], 1.0 op_sel_hi:[1,0]
	v_rcp_f32_e32 v100, v100
	v_rcp_f32_e32 v101, v101
	v_rcp_f32_e32 v92, v92
	v_rcp_f32_e32 v93, v93
	v_pk_mul_f32 v[94:95], v[96:97], v[100:101] op_sel_hi:[0,1]
	v_pk_mul_f32 v[88:89], v[88:89], v[94:95]
	v_pk_mul_f32 v[94:95], v[84:85], v[98:99] op_sel_hi:[1,0]
	v_pk_mul_f32 v[92:93], v[96:97], v[92:93] op_sel_hi:[0,1]
	v_exp_f32_e32 v94, v94
	v_exp_f32_e32 v95, v95
	v_pk_mul_f32 v[90:91], v[90:91], v[92:93]
	v_cvt_pk_bf16_f32 v88, v88, v89
	v_cvt_pk_bf16_f32 v89, v90, v91
	v_pk_add_f32 v[90:91], v[94:95], 1.0 op_sel_hi:[1,0]
	v_pk_mul_f32 v[84:85], v[86:87], v[98:99] op_sel_hi:[1,0]
	v_rcp_f32_e32 v90, v90
	v_rcp_f32_e32 v91, v91
	v_exp_f32_e32 v84, v84
	v_exp_f32_e32 v85, v85
	v_pk_mul_f32 v[86:87], v[96:97], v[90:91] op_sel_hi:[0,1]
	v_pk_mul_f32 v[80:81], v[80:81], v[86:87]
	s_nop 0
	v_cvt_pk_bf16_f32 v90, v80, v81
	v_pk_add_f32 v[80:81], v[84:85], 1.0 op_sel_hi:[1,0]
	v_ffbh_u32_e32 v84, v137
	v_min_u32_e32 v86, 32, v84
	v_lshlrev_b64 v[84:85], v86, v[136:137]
	v_rcp_f32_e32 v80, v80
	v_rcp_f32_e32 v81, v81
	v_min_u32_e32 v84, 1, v84
	v_or_b32_e32 v84, v85, v84
	v_cvt_f32_u32_e32 v84, v84
	v_pk_mul_f32 v[80:81], v[96:97], v[80:81] op_sel_hi:[0,1]
	v_pk_mul_f32 v[80:81], v[82:83], v[80:81]
	v_sub_u32_e32 v82, 32, v86
	v_ldexp_f32 v82, v84, v82
	v_fmamk_f32 v82, v82, 0x30800000, v157
	v_cvt_pk_bf16_f32 v91, v80, v81
	v_mad_i64_i32 v[80:81], s[2:3], v199, s49, v[120:121]
	v_rsq_f32_e32 v82, v82
	v_lshl_add_u64 v[80:81], v[80:81], 0, v[116:117]
	global_store_dwordx4 v[80:81], v[88:91], off
	v_mov_b32_e32 v83, v82
	v_mul_f32_e32 v82, 0xbfb8aa3b, v83
	v_pk_mul_f32 v[84:85], v[76:77], v[82:83] op_sel_hi:[1,0]
	v_pk_mul_f32 v[76:77], v[78:79], v[82:83] op_sel_hi:[1,0]
	v_exp_f32_e32 v84, v84
	v_exp_f32_e32 v85, v85
	v_exp_f32_e32 v76, v76
	v_exp_f32_e32 v77, v77
	v_mul_f32_e32 v80, v83, v83
	v_pk_add_f32 v[84:85], v[84:85], 1.0 op_sel_hi:[1,0]
	v_pk_add_f32 v[76:77], v[76:77], 1.0 op_sel_hi:[1,0]
	v_rcp_f32_e32 v84, v84
	v_rcp_f32_e32 v85, v85
	v_rcp_f32_e32 v76, v76
	v_rcp_f32_e32 v77, v77
	v_pk_mul_f32 v[78:79], v[80:81], v[84:85] op_sel_hi:[0,1]
	v_pk_mul_f32 v[72:73], v[72:73], v[78:79]
	v_pk_mul_f32 v[78:79], v[68:69], v[82:83] op_sel_hi:[1,0]
	v_pk_mul_f32 v[76:77], v[80:81], v[76:77] op_sel_hi:[0,1]
	v_exp_f32_e32 v78, v78
	v_exp_f32_e32 v79, v79
	v_pk_mul_f32 v[74:75], v[74:75], v[76:77]
	v_cvt_pk_bf16_f32 v72, v72, v73
	v_cvt_pk_bf16_f32 v73, v74, v75
	v_pk_add_f32 v[74:75], v[78:79], 1.0 op_sel_hi:[1,0]
	v_pk_mul_f32 v[68:69], v[70:71], v[82:83] op_sel_hi:[1,0]
	v_rcp_f32_e32 v74, v74
	v_rcp_f32_e32 v75, v75
	v_exp_f32_e32 v68, v68
	v_exp_f32_e32 v69, v69
	v_pk_mul_f32 v[70:71], v[80:81], v[74:75] op_sel_hi:[0,1]
	v_pk_mul_f32 v[64:65], v[64:65], v[70:71]
	s_nop 0
	v_cvt_pk_bf16_f32 v74, v64, v65
	v_pk_add_f32 v[64:65], v[68:69], 1.0 op_sel_hi:[1,0]
	s_waitcnt vmcnt(6)
	v_ffbh_u32_e32 v68, v127
	v_min_u32_e32 v70, 32, v68
	v_lshlrev_b64 v[68:69], v70, v[126:127]
	v_rcp_f32_e32 v64, v64
	v_rcp_f32_e32 v65, v65
	v_min_u32_e32 v68, 1, v68
	v_or_b32_e32 v68, v69, v68
	v_cvt_f32_u32_e32 v68, v68
	v_pk_mul_f32 v[64:65], v[80:81], v[64:65] op_sel_hi:[0,1]
	v_pk_mul_f32 v[64:65], v[66:67], v[64:65]
	v_sub_u32_e32 v66, 32, v70
	v_ldexp_f32 v66, v68, v66
	v_fmamk_f32 v66, v66, 0x30800000, v157
	v_cvt_pk_bf16_f32 v75, v64, v65
	v_mad_i64_i32 v[64:65], s[2:3], v200, s49, v[120:121]
	v_rsq_f32_e32 v66, v66
	v_lshl_add_u64 v[64:65], v[64:65], 0, v[116:117]
	global_store_dwordx4 v[64:65], v[72:75], off
	v_mov_b32_e32 v67, v66
	v_mul_f32_e32 v66, 0xbfb8aa3b, v67
	v_pk_mul_f32 v[68:69], v[60:61], v[66:67] op_sel_hi:[1,0]
	v_pk_mul_f32 v[60:61], v[62:63], v[66:67] op_sel_hi:[1,0]
	v_exp_f32_e32 v68, v68
	v_exp_f32_e32 v69, v69
	v_exp_f32_e32 v60, v60
	v_exp_f32_e32 v61, v61
	v_mul_f32_e32 v64, v67, v67
	v_pk_add_f32 v[68:69], v[68:69], 1.0 op_sel_hi:[1,0]
	v_pk_add_f32 v[60:61], v[60:61], 1.0 op_sel_hi:[1,0]
	v_rcp_f32_e32 v68, v68
	v_rcp_f32_e32 v69, v69
	v_rcp_f32_e32 v60, v60
	v_rcp_f32_e32 v61, v61
	v_pk_mul_f32 v[62:63], v[64:65], v[68:69] op_sel_hi:[0,1]
	v_pk_mul_f32 v[56:57], v[56:57], v[62:63]
	v_pk_mul_f32 v[62:63], v[52:53], v[66:67] op_sel_hi:[1,0]
	v_pk_mul_f32 v[60:61], v[64:65], v[60:61] op_sel_hi:[0,1]
	v_exp_f32_e32 v62, v62
	v_exp_f32_e32 v63, v63
	v_pk_mul_f32 v[58:59], v[58:59], v[60:61]
	v_cvt_pk_bf16_f32 v56, v56, v57
	v_cvt_pk_bf16_f32 v57, v58, v59
	v_pk_add_f32 v[58:59], v[62:63], 1.0 op_sel_hi:[1,0]
	v_pk_mul_f32 v[52:53], v[54:55], v[66:67] op_sel_hi:[1,0]
	v_rcp_f32_e32 v58, v58
	v_rcp_f32_e32 v59, v59
	v_exp_f32_e32 v52, v52
	v_exp_f32_e32 v53, v53
	v_pk_mul_f32 v[54:55], v[64:65], v[58:59] op_sel_hi:[0,1]
	v_pk_mul_f32 v[48:49], v[48:49], v[54:55]
	s_nop 0
	v_cvt_pk_bf16_f32 v58, v48, v49
	v_pk_add_f32 v[48:49], v[52:53], 1.0 op_sel_hi:[1,0]
	s_waitcnt vmcnt(6)
	v_ffbh_u32_e32 v52, v125
	v_min_u32_e32 v54, 32, v52
	v_lshlrev_b64 v[52:53], v54, v[124:125]
	v_rcp_f32_e32 v48, v48
	v_rcp_f32_e32 v49, v49
	v_min_u32_e32 v52, 1, v52
	v_or_b32_e32 v52, v53, v52
	v_cvt_f32_u32_e32 v52, v52
	v_pk_mul_f32 v[48:49], v[64:65], v[48:49] op_sel_hi:[0,1]
	v_pk_mul_f32 v[48:49], v[50:51], v[48:49]
	v_sub_u32_e32 v50, 32, v54
	v_ldexp_f32 v50, v52, v50
	v_fmamk_f32 v50, v50, 0x30800000, v157
	v_cvt_pk_bf16_f32 v59, v48, v49
	v_mad_i64_i32 v[48:49], s[2:3], v201, s49, v[120:121]
	v_rsq_f32_e32 v50, v50
	v_lshl_add_u64 v[48:49], v[48:49], 0, v[116:117]
	global_store_dwordx4 v[48:49], v[56:59], off
	v_mov_b32_e32 v51, v50
	v_mul_f32_e32 v50, 0xbfb8aa3b, v51
	v_pk_mul_f32 v[52:53], v[44:45], v[50:51] op_sel_hi:[1,0]
	v_pk_mul_f32 v[44:45], v[46:47], v[50:51] op_sel_hi:[1,0]
	v_exp_f32_e32 v52, v52
	v_exp_f32_e32 v53, v53
	v_exp_f32_e32 v44, v44
	v_exp_f32_e32 v45, v45
	v_mul_f32_e32 v48, v51, v51
	v_pk_add_f32 v[52:53], v[52:53], 1.0 op_sel_hi:[1,0]
	v_pk_add_f32 v[44:45], v[44:45], 1.0 op_sel_hi:[1,0]
	v_rcp_f32_e32 v52, v52
	v_rcp_f32_e32 v53, v53
	v_rcp_f32_e32 v44, v44
	v_rcp_f32_e32 v45, v45
	v_pk_mul_f32 v[46:47], v[48:49], v[52:53] op_sel_hi:[0,1]
	v_pk_mul_f32 v[40:41], v[40:41], v[46:47]
	v_pk_mul_f32 v[46:47], v[36:37], v[50:51] op_sel_hi:[1,0]
	v_pk_mul_f32 v[44:45], v[48:49], v[44:45] op_sel_hi:[0,1]
	v_exp_f32_e32 v46, v46
	v_exp_f32_e32 v47, v47
	v_pk_mul_f32 v[42:43], v[42:43], v[44:45]
	v_cvt_pk_bf16_f32 v40, v40, v41
	v_cvt_pk_bf16_f32 v41, v42, v43
	v_pk_add_f32 v[42:43], v[46:47], 1.0 op_sel_hi:[1,0]
	v_pk_mul_f32 v[36:37], v[38:39], v[50:51] op_sel_hi:[1,0]
	v_rcp_f32_e32 v42, v42
	v_rcp_f32_e32 v43, v43
	v_exp_f32_e32 v36, v36
	v_exp_f32_e32 v37, v37
	v_pk_mul_f32 v[38:39], v[48:49], v[42:43] op_sel_hi:[0,1]
	v_pk_mul_f32 v[32:33], v[32:33], v[38:39]
	s_nop 0
	v_cvt_pk_bf16_f32 v42, v32, v33
	v_pk_add_f32 v[32:33], v[36:37], 1.0 op_sel_hi:[1,0]
	s_waitcnt vmcnt(6)
	v_ffbh_u32_e32 v36, v123
	v_min_u32_e32 v38, 32, v36
	v_lshlrev_b64 v[36:37], v38, v[122:123]
	v_rcp_f32_e32 v32, v32
	v_rcp_f32_e32 v33, v33
	v_min_u32_e32 v36, 1, v36
	v_or_b32_e32 v36, v37, v36
	v_cvt_f32_u32_e32 v36, v36
	v_pk_mul_f32 v[32:33], v[48:49], v[32:33] op_sel_hi:[0,1]
	v_pk_mul_f32 v[32:33], v[34:35], v[32:33]
	v_sub_u32_e32 v34, 32, v38
	v_ldexp_f32 v34, v36, v34
	v_fmamk_f32 v34, v34, 0x30800000, v157
	v_cvt_pk_bf16_f32 v43, v32, v33
	v_mad_i64_i32 v[32:33], s[2:3], v160, s49, v[120:121]
	v_rsq_f32_e32 v34, v34
	v_lshl_add_u64 v[32:33], v[32:33], 0, v[116:117]
	global_store_dwordx4 v[32:33], v[40:43], off
	v_mov_b32_e32 v35, v34
	v_mul_f32_e32 v34, 0xbfb8aa3b, v35
	v_pk_mul_f32 v[36:37], v[28:29], v[34:35] op_sel_hi:[1,0]
	v_pk_mul_f32 v[28:29], v[30:31], v[34:35] op_sel_hi:[1,0]
	v_exp_f32_e32 v36, v36
	v_exp_f32_e32 v37, v37
	v_exp_f32_e32 v28, v28
	v_exp_f32_e32 v29, v29
	v_mul_f32_e32 v32, v35, v35
	v_pk_add_f32 v[36:37], v[36:37], 1.0 op_sel_hi:[1,0]
	v_pk_add_f32 v[28:29], v[28:29], 1.0 op_sel_hi:[1,0]
	v_rcp_f32_e32 v36, v36
	v_rcp_f32_e32 v37, v37
	v_rcp_f32_e32 v28, v28
	v_rcp_f32_e32 v29, v29
	v_pk_mul_f32 v[30:31], v[32:33], v[36:37] op_sel_hi:[0,1]
	v_pk_mul_f32 v[24:25], v[24:25], v[30:31]
	v_pk_mul_f32 v[30:31], v[20:21], v[34:35] op_sel_hi:[1,0]
	v_pk_mul_f32 v[28:29], v[32:33], v[28:29] op_sel_hi:[0,1]
	v_exp_f32_e32 v30, v30
	v_exp_f32_e32 v31, v31
	v_pk_mul_f32 v[26:27], v[26:27], v[28:29]
	v_cvt_pk_bf16_f32 v24, v24, v25
	v_cvt_pk_bf16_f32 v25, v26, v27
	v_pk_add_f32 v[26:27], v[30:31], 1.0 op_sel_hi:[1,0]
	v_pk_mul_f32 v[20:21], v[22:23], v[34:35] op_sel_hi:[1,0]
	v_rcp_f32_e32 v26, v26
	v_rcp_f32_e32 v27, v27
	v_exp_f32_e32 v20, v20
	v_exp_f32_e32 v21, v21
	v_pk_mul_f32 v[22:23], v[32:33], v[26:27] op_sel_hi:[0,1]
	v_pk_mul_f32 v[16:17], v[16:17], v[22:23]
	s_nop 0
	v_cvt_pk_bf16_f32 v26, v16, v17
	v_pk_add_f32 v[16:17], v[20:21], 1.0 op_sel_hi:[1,0]
	s_waitcnt vmcnt(6)
	v_ffbh_u32_e32 v20, v119
	v_min_u32_e32 v22, 32, v20
	v_lshlrev_b64 v[20:21], v22, v[118:119]
	v_rcp_f32_e32 v16, v16
	v_rcp_f32_e32 v17, v17
	v_min_u32_e32 v20, 1, v20
	v_or_b32_e32 v20, v21, v20
	v_cvt_f32_u32_e32 v20, v20
	v_pk_mul_f32 v[16:17], v[32:33], v[16:17] op_sel_hi:[0,1]
	v_pk_mul_f32 v[16:17], v[18:19], v[16:17]
	v_sub_u32_e32 v18, 32, v22
	v_ldexp_f32 v18, v20, v18
	v_fmamk_f32 v18, v18, 0x30800000, v157
	v_cvt_pk_bf16_f32 v27, v16, v17
	v_mad_i64_i32 v[16:17], s[2:3], v159, s49, v[120:121]
	v_rsq_f32_e32 v18, v18
	v_lshl_add_u64 v[16:17], v[16:17], 0, v[116:117]
	global_store_dwordx4 v[16:17], v[24:27], off
	v_mov_b32_e32 v19, v18
	v_mul_f32_e32 v18, 0xbfb8aa3b, v19
	v_pk_mul_f32 v[20:21], v[12:13], v[18:19] op_sel_hi:[1,0]
	v_pk_mul_f32 v[12:13], v[14:15], v[18:19] op_sel_hi:[1,0]
	v_exp_f32_e32 v20, v20
	v_exp_f32_e32 v21, v21
	v_exp_f32_e32 v12, v12
	v_exp_f32_e32 v13, v13
	v_mul_f32_e32 v16, v19, v19
	v_pk_add_f32 v[20:21], v[20:21], 1.0 op_sel_hi:[1,0]
	s_andn2_b64 vcc, exec, s[0:1]
	v_rcp_f32_e32 v20, v20
	v_rcp_f32_e32 v21, v21
	v_pk_add_f32 v[12:13], v[12:13], 1.0 op_sel_hi:[1,0]
	s_mov_b64 s[0:1], -1
	v_rcp_f32_e32 v12, v12
	v_rcp_f32_e32 v13, v13
	v_pk_mul_f32 v[14:15], v[16:17], v[20:21] op_sel_hi:[0,1]
	v_pk_mul_f32 v[8:9], v[8:9], v[14:15]
	v_pk_mul_f32 v[14:15], v[4:5], v[18:19] op_sel_hi:[1,0]
	v_pk_mul_f32 v[12:13], v[16:17], v[12:13] op_sel_hi:[0,1]
	v_exp_f32_e32 v14, v14
	v_exp_f32_e32 v15, v15
	v_pk_mul_f32 v[10:11], v[10:11], v[12:13]
	v_pk_mul_f32 v[12:13], v[6:7], v[18:19] op_sel_hi:[1,0]
	v_cvt_pk_bf16_f32 v8, v8, v9
	v_exp_f32_e32 v12, v12
	v_exp_f32_e32 v13, v13
	v_cvt_pk_bf16_f32 v9, v10, v11
	v_pk_add_f32 v[10:11], v[14:15], 1.0 op_sel_hi:[1,0]
	v_pk_add_f32 v[4:5], v[12:13], 1.0 op_sel_hi:[1,0]
	v_rcp_f32_e32 v10, v10
	v_rcp_f32_e32 v11, v11
	v_rcp_f32_e32 v4, v4
	v_rcp_f32_e32 v5, v5
	v_pk_mul_f32 v[6:7], v[16:17], v[10:11] op_sel_hi:[0,1]
	v_pk_mul_f32 v[0:1], v[0:1], v[6:7]
	s_nop 0
	v_cvt_pk_bf16_f32 v10, v0, v1
	v_pk_mul_f32 v[0:1], v[16:17], v[4:5] op_sel_hi:[0,1]
	v_pk_mul_f32 v[0:1], v[2:3], v[0:1]
	s_nop 0
	v_cvt_pk_bf16_f32 v11, v0, v1
	v_mad_i64_i32 v[0:1], s[2:3], v158, s49, v[120:121]
	v_lshl_add_u64 v[0:1], v[0:1], 0, v[116:117]
	global_store_dwordx4 v[0:1], v[8:11], off
	s_cbranch_vccnz .LBB0_364
	s_andn2_b64 vcc, exec, s[6:7]
	s_cbranch_vccnz .LBB0_363
	s_barrier
	s_branch .LBB0_363

.LBB0_454:
	s_add_u32 s14, s14, 0xb0080
	s_addc_u32 s15, s15, 0
	s_add_u32 s65, s2, 0x100
	s_addc_u32 s66, s3, 0
	s_mov_b32 s67, -2
	s_waitcnt lgkmcnt(0)
	s_waitcnt vmcnt(0)
	ds_read_b128 v[128:131], v147
	ds_read_b128 v[132:135], v147 offset:1024
	ds_read_b128 v[136:139], v147 offset:2048
	ds_read_b128 v[164:167], v147 offset:3072
	ds_read_b128 v[188:191], v184
	ds_read_b128 v[196:199], v184 offset:1024
	ds_read_b128 v[200:203], v184 offset:2048
	ds_read_b128 v[204:207], v184 offset:3072
	s_add_u32 s2, s14, 0xfff50080
	s_addc_u32 s3, s15, -1
	s_cmp_eq_u32 s67, 40
	s_cselect_b32 s23, s1, s3
	s_cselect_b32 s22, s0, s2
	s_cselect_b32 s3, s31, s66
	s_cselect_b32 s2, s30, s65
	v_lshl_add_u64 v[168:169], s[14:15], 0, v[156:157]
	s_add_i32 m0, s37, 0xc000
	ds_read_b128 v[208:211], v185
	ds_read_b128 v[212:215], v185 offset:1024
	ds_read_b128 v[216:219], v185 offset:2048
	ds_read_b128 v[220:223], v185 offset:3072
	ds_read_b128 v[224:227], v185 offset:4096
	ds_read_b128 v[228:231], v185 offset:5120
	ds_read_b128 v[232:235], v185 offset:6144
	ds_read_b128 v[236:239], v185 offset:7168
	global_load_lds_dwordx4 v[168:169], off
	v_lshl_add_u64 v[168:169], s[14:15], 0, v[158:159]
	s_add_i32 m0, s37, 0xe000
	s_nop 0
	global_load_lds_dwordx4 v[168:169], off
	s_waitcnt vmcnt(8)
	s_waitcnt lgkmcnt(0)
	s_barrier
	s_setprio 1
	s_waitcnt lgkmcnt(0)
	v_mfma_f32_16x16x32_bf16 v[124:127], v[128:131], v[208:211], 0
	v_mfma_f32_16x16x32_bf16 v[120:123], v[136:139], v[208:211], 0
	v_mfma_f32_16x16x32_bf16 v[108:111], v[128:131], v[216:219], 0
	v_mfma_f32_16x16x32_bf16 v[104:107], v[136:139], v[216:219], 0
	v_mfma_f32_16x16x32_bf16 v[92:95], v[128:131], v[224:227], 0
	v_mfma_f32_16x16x32_bf16 v[88:91], v[136:139], v[224:227], 0
	v_mfma_f32_16x16x32_bf16 v[76:79], v[128:131], v[232:235], 0
	v_mfma_f32_16x16x32_bf16 v[72:75], v[136:139], v[232:235], 0
	v_mfma_f32_16x16x32_bf16 v[124:127], v[132:135], v[212:215], v[124:127]
	v_mfma_f32_16x16x32_bf16 v[120:123], v[164:167], v[212:215], v[120:123]
	v_mfma_f32_16x16x32_bf16 v[108:111], v[132:135], v[220:223], v[108:111]
	v_mfma_f32_16x16x32_bf16 v[104:107], v[164:167], v[220:223], v[104:107]
	v_mfma_f32_16x16x32_bf16 v[92:95], v[132:135], v[228:231], v[92:95]
	v_mfma_f32_16x16x32_bf16 v[88:91], v[164:167], v[228:231], v[88:91]
	v_mfma_f32_16x16x32_bf16 v[76:79], v[132:135], v[236:239], v[76:79]
	v_mfma_f32_16x16x32_bf16 v[72:75], v[164:167], v[236:239], v[72:75]
	s_setprio 0
	s_setprio 1
	v_mfma_f32_16x16x32_bf16 v[116:119], v[188:191], v[208:211], 0
	v_mfma_f32_16x16x32_bf16 v[112:115], v[200:203], v[208:211], 0
	v_mfma_f32_16x16x32_bf16 v[100:103], v[188:191], v[216:219], 0
	v_mfma_f32_16x16x32_bf16 v[96:99], v[200:203], v[216:219], 0
	v_mfma_f32_16x16x32_bf16 v[84:87], v[188:191], v[224:227], 0
	v_mfma_f32_16x16x32_bf16 v[80:83], v[200:203], v[224:227], 0
	v_mfma_f32_16x16x32_bf16 v[68:71], v[188:191], v[232:235], 0
	v_mfma_f32_16x16x32_bf16 v[64:67], v[200:203], v[232:235], 0
	v_mfma_f32_16x16x32_bf16 v[116:119], v[196:199], v[212:215], v[116:119]
	v_mfma_f32_16x16x32_bf16 v[112:115], v[204:207], v[212:215], v[112:115]
	v_mfma_f32_16x16x32_bf16 v[100:103], v[196:199], v[220:223], v[100:103]
	v_mfma_f32_16x16x32_bf16 v[96:99], v[204:207], v[220:223], v[96:99]
	v_mfma_f32_16x16x32_bf16 v[84:87], v[196:199], v[228:231], v[84:87]
	v_mfma_f32_16x16x32_bf16 v[80:83], v[204:207], v[228:231], v[80:83]
	v_mfma_f32_16x16x32_bf16 v[68:71], v[196:199], v[236:239], v[68:71]
	v_mfma_f32_16x16x32_bf16 v[64:67], v[204:207], v[236:239], v[64:67]
	s_setprio 0
	s_barrier
	s_add_i32 s68, s51, s36
	v_lshl_add_u64 v[168:169], s[2:3], 0, v[150:151]
	s_mov_b32 m0, s68
	ds_read_b128 v[208:211], v185 offset:16384
	ds_read_b128 v[212:215], v185 offset:17408
	ds_read_b128 v[216:219], v185 offset:18432
	ds_read_b128 v[220:223], v185 offset:19456
	ds_read_b128 v[224:227], v185 offset:20480
	ds_read_b128 v[228:231], v185 offset:21504
	ds_read_b128 v[232:235], v185 offset:22528
	ds_read_b128 v[236:239], v185 offset:23552
	global_load_lds_dwordx4 v[168:169], off
	s_add_i32 m0, s68, 0x2000
	s_add_u32 s68, s2, 0xb0000
	v_lshl_add_u64 v[192:193], s[2:3], 0, v[154:155]
	s_addc_u32 s69, s3, 0
	s_add_i32 s70, s52, s36
	global_load_lds_dwordx4 v[192:193], off
	v_lshl_add_u64 v[240:241], s[68:69], 0, v[150:151]
	s_mov_b32 m0, s70
	v_lshl_add_u64 v[242:243], s[22:23], 0, v[152:153]
	global_load_lds_dwordx4 v[240:241], off
	v_lshl_add_u64 v[240:241], s[68:69], 0, v[154:155]
	s_add_i32 m0, s70, 0x2000
	s_nop 0
	global_load_lds_dwordx4 v[240:241], off
	v_lshl_add_u64 v[240:241], s[22:23], 0, v[148:149]
	s_mov_b32 m0, s37
	s_nop 0
	global_load_lds_dwordx4 v[240:241], off
	s_mov_b32 m0, s38
	s_nop 0
	global_load_lds_dwordx4 v[242:243], off
	s_waitcnt vmcnt(8)
	s_waitcnt lgkmcnt(0)
	s_barrier
	s_setprio 1
	s_waitcnt lgkmcnt(0)
	v_mfma_f32_16x16x32_bf16 v[60:63], v[128:131], v[208:211], 0
	v_mfma_f32_16x16x32_bf16 v[56:59], v[136:139], v[208:211], 0
	v_mfma_f32_16x16x32_bf16 v[44:47], v[128:131], v[216:219], 0
	v_mfma_f32_16x16x32_bf16 v[40:43], v[136:139], v[216:219], 0
	v_mfma_f32_16x16x32_bf16 v[28:31], v[128:131], v[224:227], 0
	v_mfma_f32_16x16x32_bf16 v[24:27], v[136:139], v[224:227], 0
	v_mfma_f32_16x16x32_bf16 v[12:15], v[128:131], v[232:235], 0
	v_mfma_f32_16x16x32_bf16 v[8:11], v[136:139], v[232:235], 0
	v_mfma_f32_16x16x32_bf16 v[60:63], v[132:135], v[212:215], v[60:63]
	v_mfma_f32_16x16x32_bf16 v[56:59], v[164:167], v[212:215], v[56:59]
	v_mfma_f32_16x16x32_bf16 v[44:47], v[132:135], v[220:223], v[44:47]
	v_mfma_f32_16x16x32_bf16 v[40:43], v[164:167], v[220:223], v[40:43]
	v_mfma_f32_16x16x32_bf16 v[28:31], v[132:135], v[228:231], v[28:31]
	v_mfma_f32_16x16x32_bf16 v[24:27], v[164:167], v[228:231], v[24:27]
	v_mfma_f32_16x16x32_bf16 v[12:15], v[132:135], v[236:239], v[12:15]
	v_mfma_f32_16x16x32_bf16 v[8:11], v[164:167], v[236:239], v[8:11]
	s_setprio 0
	s_setprio 1
	v_mfma_f32_16x16x32_bf16 v[52:55], v[188:191], v[208:211], 0
	v_mfma_f32_16x16x32_bf16 v[48:51], v[200:203], v[208:211], 0
	v_mfma_f32_16x16x32_bf16 v[36:39], v[188:191], v[216:219], 0
	v_mfma_f32_16x16x32_bf16 v[32:35], v[200:203], v[216:219], 0
	v_mfma_f32_16x16x32_bf16 v[20:23], v[188:191], v[224:227], 0
	v_mfma_f32_16x16x32_bf16 v[16:19], v[200:203], v[224:227], 0
	v_mfma_f32_16x16x32_bf16 v[4:7], v[188:191], v[232:235], 0
	v_mfma_f32_16x16x32_bf16 v[0:3], v[200:203], v[232:235], 0
	v_mfma_f32_16x16x32_bf16 v[52:55], v[196:199], v[212:215], v[52:55]
	v_mfma_f32_16x16x32_bf16 v[48:51], v[204:207], v[212:215], v[48:51]
	v_mfma_f32_16x16x32_bf16 v[36:39], v[196:199], v[220:223], v[36:39]
	v_mfma_f32_16x16x32_bf16 v[32:35], v[204:207], v[220:223], v[32:35]
	v_mfma_f32_16x16x32_bf16 v[20:23], v[196:199], v[228:231], v[20:23]
	v_mfma_f32_16x16x32_bf16 v[16:19], v[204:207], v[228:231], v[16:19]
	v_mfma_f32_16x16x32_bf16 v[4:7], v[196:199], v[236:239], v[4:7]
	v_mfma_f32_16x16x32_bf16 v[0:3], v[204:207], v[236:239], v[0:3]
	s_setprio 0
	s_barrier
	s_add_i32 s68, 0, 0x18000
	s_add_i32 s69, 0, 0x1c000
	v_add_u32_e32 v164, s68, v141
	v_add_u32_e32 v187, s69, v141
	ds_read_b128 v[128:131], v164
	ds_read_b128 v[132:135], v164 offset:1024
	ds_read_b128 v[136:139], v164 offset:2048
	ds_read_b128 v[164:167], v164 offset:3072
	ds_read_b128 v[188:191], v187
	ds_read_b128 v[196:199], v187 offset:1024
	ds_read_b128 v[200:203], v187 offset:2048
	ds_read_b128 v[204:207], v187 offset:3072
	s_add_u32 s22, s22, 0xb0000
	s_addc_u32 s23, s23, 0
	s_mov_b32 m0, s39
	v_lshl_add_u64 v[244:245], s[22:23], 0, v[148:149]
	ds_read_b128 v[208:211], v185 offset:32768
	ds_read_b128 v[212:215], v185 offset:33792
	ds_read_b128 v[216:219], v185 offset:34816
	ds_read_b128 v[220:223], v185 offset:35840
	ds_read_b128 v[224:227], v185 offset:36864
	ds_read_b128 v[228:231], v185 offset:37888
	ds_read_b128 v[232:235], v185 offset:38912
	ds_read_b128 v[236:239], v185 offset:39936
	global_load_lds_dwordx4 v[244:245], off
	v_lshl_add_u64 v[244:245], s[22:23], 0, v[152:153]
	s_mov_b32 m0, s40
	s_nop 0
	global_load_lds_dwordx4 v[244:245], off
	s_waitcnt vmcnt(8)
	s_waitcnt lgkmcnt(0)
	s_barrier
	s_setprio 1
	s_waitcnt lgkmcnt(0)
	v_mfma_f32_16x16x32_bf16 v[124:127], v[128:131], v[208:211], v[124:127]
	v_mfma_f32_16x16x32_bf16 v[120:123], v[136:139], v[208:211], v[120:123]
	v_mfma_f32_16x16x32_bf16 v[108:111], v[128:131], v[216:219], v[108:111]
	v_mfma_f32_16x16x32_bf16 v[104:107], v[136:139], v[216:219], v[104:107]
	v_mfma_f32_16x16x32_bf16 v[92:95], v[128:131], v[224:227], v[92:95]
	v_mfma_f32_16x16x32_bf16 v[88:91], v[136:139], v[224:227], v[88:91]
	v_mfma_f32_16x16x32_bf16 v[76:79], v[128:131], v[232:235], v[76:79]
	v_mfma_f32_16x16x32_bf16 v[72:75], v[136:139], v[232:235], v[72:75]
	v_mfma_f32_16x16x32_bf16 v[124:127], v[132:135], v[212:215], v[124:127]
	v_mfma_f32_16x16x32_bf16 v[120:123], v[164:167], v[212:215], v[120:123]
	v_mfma_f32_16x16x32_bf16 v[108:111], v[132:135], v[220:223], v[108:111]
	v_mfma_f32_16x16x32_bf16 v[104:107], v[164:167], v[220:223], v[104:107]
	v_mfma_f32_16x16x32_bf16 v[92:95], v[132:135], v[228:231], v[92:95]
	v_mfma_f32_16x16x32_bf16 v[88:91], v[164:167], v[228:231], v[88:91]
	v_mfma_f32_16x16x32_bf16 v[76:79], v[132:135], v[236:239], v[76:79]
	v_mfma_f32_16x16x32_bf16 v[72:75], v[164:167], v[236:239], v[72:75]
	s_setprio 0
	s_setprio 1
	v_mfma_f32_16x16x32_bf16 v[116:119], v[188:191], v[208:211], v[116:119]
	v_mfma_f32_16x16x32_bf16 v[112:115], v[200:203], v[208:211], v[112:115]
	v_mfma_f32_16x16x32_bf16 v[100:103], v[188:191], v[216:219], v[100:103]
	v_mfma_f32_16x16x32_bf16 v[96:99], v[200:203], v[216:219], v[96:99]
	v_mfma_f32_16x16x32_bf16 v[84:87], v[188:191], v[224:227], v[84:87]
	v_mfma_f32_16x16x32_bf16 v[80:83], v[200:203], v[224:227], v[80:83]
	v_mfma_f32_16x16x32_bf16 v[68:71], v[188:191], v[232:235], v[68:71]
	v_mfma_f32_16x16x32_bf16 v[64:67], v[200:203], v[232:235], v[64:67]
	v_mfma_f32_16x16x32_bf16 v[116:119], v[196:199], v[212:215], v[116:119]
	v_mfma_f32_16x16x32_bf16 v[112:115], v[204:207], v[212:215], v[112:115]
	v_mfma_f32_16x16x32_bf16 v[100:103], v[196:199], v[220:223], v[100:103]
	v_mfma_f32_16x16x32_bf16 v[96:99], v[204:207], v[220:223], v[96:99]
	v_mfma_f32_16x16x32_bf16 v[84:87], v[196:199], v[228:231], v[84:87]
	v_mfma_f32_16x16x32_bf16 v[80:83], v[204:207], v[228:231], v[80:83]
	v_mfma_f32_16x16x32_bf16 v[68:71], v[196:199], v[236:239], v[68:71]
	v_mfma_f32_16x16x32_bf16 v[64:67], v[204:207], v[236:239], v[64:67]
	s_setprio 0
	s_barrier
	s_add_i32 s22, s68, s36
	v_lshl_add_u64 v[168:169], v[168:169], 0, s[26:27]
	s_mov_b32 m0, s22
	ds_read_b128 v[208:211], v185 offset:49152
	ds_read_b128 v[212:215], v185 offset:50176
	ds_read_b128 v[216:219], v185 offset:51200
	ds_read_b128 v[220:223], v185 offset:52224
	ds_read_b128 v[224:227], v185 offset:53248
	ds_read_b128 v[228:231], v185 offset:54272
	ds_read_b128 v[232:235], v185 offset:55296
	ds_read_b128 v[236:239], v185 offset:56320
	global_load_lds_dwordx4 v[168:169], off
	s_add_i32 m0, s22, 0x2000
	s_add_u32 s2, s2, 0xb0080
	v_lshl_add_u64 v[168:169], v[192:193], 0, s[26:27]
	s_addc_u32 s3, s3, 0
	s_add_i32 s22, s69, s36
	global_load_lds_dwordx4 v[168:169], off
	v_lshl_add_u64 v[168:169], s[2:3], 0, v[150:151]
	s_mov_b32 m0, s22
	s_nop 0
	global_load_lds_dwordx4 v[168:169], off
	v_lshl_add_u64 v[168:169], s[2:3], 0, v[154:155]
	s_add_i32 m0, s22, 0x2000
	s_nop 0
	global_load_lds_dwordx4 v[168:169], off
	v_lshl_add_u64 v[168:169], v[240:241], 0, s[26:27]
	s_mov_b32 m0, s44
	s_nop 0
	global_load_lds_dwordx4 v[168:169], off
	v_lshl_add_u64 v[168:169], v[242:243], 0, s[26:27]
	s_mov_b32 m0, s45
	s_nop 0
	global_load_lds_dwordx4 v[168:169], off
	s_waitcnt vmcnt(8)
	s_waitcnt lgkmcnt(0)
	s_barrier
	s_setprio 1
	s_waitcnt lgkmcnt(0)
	v_mfma_f32_16x16x32_bf16 v[60:63], v[128:131], v[208:211], v[60:63]
	v_mfma_f32_16x16x32_bf16 v[56:59], v[136:139], v[208:211], v[56:59]
	v_mfma_f32_16x16x32_bf16 v[44:47], v[128:131], v[216:219], v[44:47]
	v_mfma_f32_16x16x32_bf16 v[40:43], v[136:139], v[216:219], v[40:43]
	v_mfma_f32_16x16x32_bf16 v[28:31], v[128:131], v[224:227], v[28:31]
	v_mfma_f32_16x16x32_bf16 v[24:27], v[136:139], v[224:227], v[24:27]
	v_mfma_f32_16x16x32_bf16 v[12:15], v[128:131], v[232:235], v[12:15]
	v_mfma_f32_16x16x32_bf16 v[8:11], v[136:139], v[232:235], v[8:11]
	v_mfma_f32_16x16x32_bf16 v[60:63], v[132:135], v[212:215], v[60:63]
	v_mfma_f32_16x16x32_bf16 v[56:59], v[164:167], v[212:215], v[56:59]
	v_mfma_f32_16x16x32_bf16 v[44:47], v[132:135], v[220:223], v[44:47]
	v_mfma_f32_16x16x32_bf16 v[40:43], v[164:167], v[220:223], v[40:43]
	v_mfma_f32_16x16x32_bf16 v[28:31], v[132:135], v[228:231], v[28:31]
	v_mfma_f32_16x16x32_bf16 v[24:27], v[164:167], v[228:231], v[24:27]
	v_mfma_f32_16x16x32_bf16 v[12:15], v[132:135], v[236:239], v[12:15]
	v_mfma_f32_16x16x32_bf16 v[8:11], v[164:167], v[236:239], v[8:11]
	s_setprio 0
	s_setprio 1
	v_mfma_f32_16x16x32_bf16 v[52:55], v[188:191], v[208:211], v[52:55]
	v_mfma_f32_16x16x32_bf16 v[48:51], v[200:203], v[208:211], v[48:51]
	v_mfma_f32_16x16x32_bf16 v[36:39], v[188:191], v[216:219], v[36:39]
	v_mfma_f32_16x16x32_bf16 v[32:35], v[200:203], v[216:219], v[32:35]
	v_mfma_f32_16x16x32_bf16 v[20:23], v[188:191], v[224:227], v[20:23]
	v_mfma_f32_16x16x32_bf16 v[16:19], v[200:203], v[224:227], v[16:19]
	v_mfma_f32_16x16x32_bf16 v[4:7], v[188:191], v[232:235], v[4:7]
	v_mfma_f32_16x16x32_bf16 v[0:3], v[200:203], v[232:235], v[0:3]
	v_mfma_f32_16x16x32_bf16 v[52:55], v[196:199], v[212:215], v[52:55]
	v_mfma_f32_16x16x32_bf16 v[48:51], v[204:207], v[212:215], v[48:51]
	v_mfma_f32_16x16x32_bf16 v[36:39], v[196:199], v[220:223], v[36:39]
	v_mfma_f32_16x16x32_bf16 v[32:35], v[204:207], v[220:223], v[32:35]
	v_mfma_f32_16x16x32_bf16 v[20:23], v[196:199], v[228:231], v[20:23]
	v_mfma_f32_16x16x32_bf16 v[16:19], v[204:207], v[228:231], v[16:19]
	v_mfma_f32_16x16x32_bf16 v[4:7], v[196:199], v[236:239], v[4:7]
	v_mfma_f32_16x16x32_bf16 v[0:3], v[204:207], v[236:239], v[0:3]
	s_setprio 0
	s_barrier
	s_add_i32 s67, s67, 2
	s_add_u32 s14, s14, 0x100
	s_addc_u32 s15, s15, 0
	s_add_u32 s65, s65, 0x100
	s_addc_u32 s66, s66, 0
	s_cmp_gt_u32 s67, 41
	s_cbranch_scc1 .Lgemm_kdone_2

.Lgemm_kdone_2:
	s_and_b64 vcc, exec, s[28:29]
	s_cbranch_vccz .LBB0_458
	s_barrier

.LBB0_551:
	s_ashr_i32 s41, s40, 31
	s_lshl_b64 s[22:23], s[40:41], 19
	s_add_u32 s42, s84, s22
	s_addc_u32 s43, s85, s23
	s_and_b64 s[22:23], s[4:5], exec
	s_cselect_b32 s41, s43, s15
	s_cselect_b32 s69, s42, s14
	s_ashr_i32 s39, s38, 31
	s_lshl_b64 s[22:23], s[38:39], 19
	s_add_u32 s44, s34, s22
	s_addc_u32 s45, s35, s23
	s_and_b64 s[22:23], s[4:5], exec
	s_cselect_b32 s39, s45, s3
	s_cselect_b32 s70, s44, s2
	s_add_u32 s14, s14, 0x40080
	s_addc_u32 s15, s15, 0
	s_add_u32 s71, s2, 0x100
	s_addc_u32 s72, s3, 0
	s_mov_b32 s73, -2
	s_waitcnt vmcnt(0)
	ds_read_b128 v[156:159], v155
	ds_read_b128 v[160:163], v155 offset:1024
	ds_read_b128 v[184:187], v155 offset:2048
	ds_read_b128 v[188:191], v155 offset:3072
	ds_read_b128 v[196:199], v166
	ds_read_b128 v[200:203], v166 offset:1024
	ds_read_b128 v[204:207], v166 offset:2048
	ds_read_b128 v[208:211], v166 offset:3072
	s_add_u32 s2, s14, 0xfffc0080
	s_addc_u32 s3, s15, -1
	s_cmp_eq_u32 s73, 12
	s_cselect_b32 s23, s41, s3
	s_cselect_b32 s22, s69, s2
	s_cselect_b32 s3, s39, s72
	s_cselect_b32 s2, s70, s71
	v_lshl_add_u64 v[138:139], s[14:15], 0, v[130:131]
	s_add_i32 m0, s49, 0xc000
	ds_read_b128 v[212:215], v167
	ds_read_b128 v[216:219], v167 offset:1024
	ds_read_b128 v[220:223], v167 offset:2048
	ds_read_b128 v[224:227], v167 offset:3072
	ds_read_b128 v[228:231], v167 offset:4096
	ds_read_b128 v[232:235], v167 offset:5120
	ds_read_b128 v[236:239], v167 offset:6144
	ds_read_b128 v[240:243], v167 offset:7168
	global_load_lds_dwordx4 v[138:139], off
	v_lshl_add_u64 v[138:139], s[14:15], 0, v[132:133]
	s_add_i32 m0, s49, 0xe000
	s_nop 0
	global_load_lds_dwordx4 v[138:139], off
	s_waitcnt vmcnt(8)
	s_waitcnt lgkmcnt(0)
	s_barrier
	s_setprio 1
	s_waitcnt lgkmcnt(0)
	v_mfma_f32_16x16x32_bf16 v[124:127], v[156:159], v[212:215], 0
	v_mfma_f32_16x16x32_bf16 v[120:123], v[184:187], v[212:215], 0
	v_mfma_f32_16x16x32_bf16 v[116:119], v[156:159], v[220:223], 0
	v_mfma_f32_16x16x32_bf16 v[112:115], v[184:187], v[220:223], 0
	v_mfma_f32_16x16x32_bf16 v[92:95], v[156:159], v[228:231], 0
	v_mfma_f32_16x16x32_bf16 v[88:91], v[184:187], v[228:231], 0
	v_mfma_f32_16x16x32_bf16 v[76:79], v[156:159], v[236:239], 0
	v_mfma_f32_16x16x32_bf16 v[72:75], v[184:187], v[236:239], 0
	v_mfma_f32_16x16x32_bf16 v[124:127], v[160:163], v[216:219], v[124:127]
	v_mfma_f32_16x16x32_bf16 v[120:123], v[188:191], v[216:219], v[120:123]
	v_mfma_f32_16x16x32_bf16 v[116:119], v[160:163], v[224:227], v[116:119]
	v_mfma_f32_16x16x32_bf16 v[112:115], v[188:191], v[224:227], v[112:115]
	v_mfma_f32_16x16x32_bf16 v[92:95], v[160:163], v[232:235], v[92:95]
	v_mfma_f32_16x16x32_bf16 v[88:91], v[188:191], v[232:235], v[88:91]
	v_mfma_f32_16x16x32_bf16 v[76:79], v[160:163], v[240:243], v[76:79]
	v_mfma_f32_16x16x32_bf16 v[72:75], v[188:191], v[240:243], v[72:75]
	s_setprio 0
	s_setprio 1
	v_mfma_f32_16x16x32_bf16 v[108:111], v[196:199], v[212:215], 0
	v_mfma_f32_16x16x32_bf16 v[104:107], v[204:207], v[212:215], 0
	v_mfma_f32_16x16x32_bf16 v[100:103], v[196:199], v[220:223], 0
	v_mfma_f32_16x16x32_bf16 v[96:99], v[204:207], v[220:223], 0
	v_mfma_f32_16x16x32_bf16 v[84:87], v[196:199], v[228:231], 0
	v_mfma_f32_16x16x32_bf16 v[80:83], v[204:207], v[228:231], 0
	v_mfma_f32_16x16x32_bf16 v[68:71], v[196:199], v[236:239], 0
	v_mfma_f32_16x16x32_bf16 v[64:67], v[204:207], v[236:239], 0
	v_mfma_f32_16x16x32_bf16 v[108:111], v[200:203], v[216:219], v[108:111]
	v_mfma_f32_16x16x32_bf16 v[104:107], v[208:211], v[216:219], v[104:107]
	v_mfma_f32_16x16x32_bf16 v[100:103], v[200:203], v[224:227], v[100:103]
	v_mfma_f32_16x16x32_bf16 v[96:99], v[208:211], v[224:227], v[96:99]
	v_mfma_f32_16x16x32_bf16 v[84:87], v[200:203], v[232:235], v[84:87]
	v_mfma_f32_16x16x32_bf16 v[80:83], v[208:211], v[232:235], v[80:83]
	v_mfma_f32_16x16x32_bf16 v[68:71], v[200:203], v[240:243], v[68:71]
	v_mfma_f32_16x16x32_bf16 v[64:67], v[208:211], v[240:243], v[64:67]
	s_setprio 0
	s_barrier
	s_add_i32 s74, s58, s46
	v_lshl_add_u64 v[138:139], s[2:3], 0, v[142:143]
	s_mov_b32 m0, s74
	ds_read_b128 v[212:215], v167 offset:16384
	ds_read_b128 v[216:219], v167 offset:17408
	ds_read_b128 v[220:223], v167 offset:18432
	ds_read_b128 v[224:227], v167 offset:19456
	ds_read_b128 v[228:231], v167 offset:20480
	ds_read_b128 v[232:235], v167 offset:21504
	ds_read_b128 v[236:239], v167 offset:22528
	ds_read_b128 v[240:243], v167 offset:23552
	global_load_lds_dwordx4 v[138:139], off
	s_add_i32 m0, s74, 0x2000
	s_add_u32 s74, s2, 0x40000
	v_lshl_add_u64 v[164:165], s[2:3], 0, v[146:147]
	s_addc_u32 s75, s3, 0
	s_add_i32 s76, s59, s46
	global_load_lds_dwordx4 v[164:165], off
	v_lshl_add_u64 v[192:193], s[74:75], 0, v[142:143]
	s_mov_b32 m0, s76
	v_lshl_add_u64 v[244:245], s[22:23], 0, v[144:145]
	global_load_lds_dwordx4 v[192:193], off
	v_lshl_add_u64 v[192:193], s[74:75], 0, v[146:147]
	s_add_i32 m0, s76, 0x2000
	s_nop 0
	global_load_lds_dwordx4 v[192:193], off
	v_lshl_add_u64 v[192:193], s[22:23], 0, v[140:141]
	s_mov_b32 m0, s49
	s_nop 0
	global_load_lds_dwordx4 v[192:193], off
	s_mov_b32 m0, s50
	s_nop 0
	global_load_lds_dwordx4 v[244:245], off
	s_waitcnt vmcnt(8)
	s_waitcnt lgkmcnt(0)
	s_barrier
	s_setprio 1
	s_waitcnt lgkmcnt(0)
	v_mfma_f32_16x16x32_bf16 v[60:63], v[156:159], v[212:215], 0
	v_mfma_f32_16x16x32_bf16 v[56:59], v[184:187], v[212:215], 0
	v_mfma_f32_16x16x32_bf16 v[44:47], v[156:159], v[220:223], 0
	v_mfma_f32_16x16x32_bf16 v[40:43], v[184:187], v[220:223], 0
	v_mfma_f32_16x16x32_bf16 v[28:31], v[156:159], v[228:231], 0
	v_mfma_f32_16x16x32_bf16 v[24:27], v[184:187], v[228:231], 0
	v_mfma_f32_16x16x32_bf16 v[12:15], v[156:159], v[236:239], 0
	v_mfma_f32_16x16x32_bf16 v[8:11], v[184:187], v[236:239], 0
	v_mfma_f32_16x16x32_bf16 v[60:63], v[160:163], v[216:219], v[60:63]
	v_mfma_f32_16x16x32_bf16 v[56:59], v[188:191], v[216:219], v[56:59]
	v_mfma_f32_16x16x32_bf16 v[44:47], v[160:163], v[224:227], v[44:47]
	v_mfma_f32_16x16x32_bf16 v[40:43], v[188:191], v[224:227], v[40:43]
	v_mfma_f32_16x16x32_bf16 v[28:31], v[160:163], v[232:235], v[28:31]
	v_mfma_f32_16x16x32_bf16 v[24:27], v[188:191], v[232:235], v[24:27]
	v_mfma_f32_16x16x32_bf16 v[12:15], v[160:163], v[240:243], v[12:15]
	v_mfma_f32_16x16x32_bf16 v[8:11], v[188:191], v[240:243], v[8:11]
	s_setprio 0
	s_setprio 1
	v_mfma_f32_16x16x32_bf16 v[52:55], v[196:199], v[212:215], 0
	v_mfma_f32_16x16x32_bf16 v[48:51], v[204:207], v[212:215], 0
	v_mfma_f32_16x16x32_bf16 v[36:39], v[196:199], v[220:223], 0
	v_mfma_f32_16x16x32_bf16 v[32:35], v[204:207], v[220:223], 0
	v_mfma_f32_16x16x32_bf16 v[20:23], v[196:199], v[228:231], 0
	v_mfma_f32_16x16x32_bf16 v[16:19], v[204:207], v[228:231], 0
	v_mfma_f32_16x16x32_bf16 v[4:7], v[196:199], v[236:239], 0
	v_mfma_f32_16x16x32_bf16 v[0:3], v[204:207], v[236:239], 0
	v_mfma_f32_16x16x32_bf16 v[52:55], v[200:203], v[216:219], v[52:55]
	v_mfma_f32_16x16x32_bf16 v[48:51], v[208:211], v[216:219], v[48:51]
	v_mfma_f32_16x16x32_bf16 v[36:39], v[200:203], v[224:227], v[36:39]
	v_mfma_f32_16x16x32_bf16 v[32:35], v[208:211], v[224:227], v[32:35]
	v_mfma_f32_16x16x32_bf16 v[20:23], v[200:203], v[232:235], v[20:23]
	v_mfma_f32_16x16x32_bf16 v[16:19], v[208:211], v[232:235], v[16:19]
	v_mfma_f32_16x16x32_bf16 v[4:7], v[200:203], v[240:243], v[4:7]
	v_mfma_f32_16x16x32_bf16 v[0:3], v[208:211], v[240:243], v[0:3]
	s_setprio 0
	s_barrier
	s_add_i32 s74, 0, 0x18000
	v_add_u32_e32 v128, s74, v151
	s_add_i32 s75, 0, 0x1c000
	ds_read_b128 v[156:159], v128
	ds_read_b128 v[160:163], v128 offset:1024
	ds_read_b128 v[184:187], v128 offset:2048
	ds_read_b128 v[188:191], v128 offset:3072
	v_add_u32_e32 v128, s75, v151
	ds_read_b128 v[196:199], v128
	ds_read_b128 v[200:203], v128 offset:1024
	ds_read_b128 v[204:207], v128 offset:2048
	ds_read_b128 v[208:211], v128 offset:3072
	s_add_u32 s22, s22, 0x40000
	s_addc_u32 s23, s23, 0
	s_mov_b32 m0, s51
	v_lshl_add_u64 v[246:247], s[22:23], 0, v[140:141]
	ds_read_b128 v[212:215], v167 offset:32768
	ds_read_b128 v[216:219], v167 offset:33792
	ds_read_b128 v[220:223], v167 offset:34816
	ds_read_b128 v[224:227], v167 offset:35840
	ds_read_b128 v[228:231], v167 offset:36864
	ds_read_b128 v[232:235], v167 offset:37888
	ds_read_b128 v[236:239], v167 offset:38912
	ds_read_b128 v[240:243], v167 offset:39936
	global_load_lds_dwordx4 v[246:247], off
	v_lshl_add_u64 v[246:247], s[22:23], 0, v[144:145]
	s_mov_b32 m0, s52
	s_nop 0
	global_load_lds_dwordx4 v[246:247], off
	s_waitcnt vmcnt(8)
	s_waitcnt lgkmcnt(0)
	s_barrier
	s_setprio 1
	s_waitcnt lgkmcnt(0)
	v_mfma_f32_16x16x32_bf16 v[124:127], v[156:159], v[212:215], v[124:127]
	v_mfma_f32_16x16x32_bf16 v[120:123], v[184:187], v[212:215], v[120:123]
	v_mfma_f32_16x16x32_bf16 v[116:119], v[156:159], v[220:223], v[116:119]
	v_mfma_f32_16x16x32_bf16 v[112:115], v[184:187], v[220:223], v[112:115]
	v_mfma_f32_16x16x32_bf16 v[92:95], v[156:159], v[228:231], v[92:95]
	v_mfma_f32_16x16x32_bf16 v[88:91], v[184:187], v[228:231], v[88:91]
	v_mfma_f32_16x16x32_bf16 v[76:79], v[156:159], v[236:239], v[76:79]
	v_mfma_f32_16x16x32_bf16 v[72:75], v[184:187], v[236:239], v[72:75]
	v_mfma_f32_16x16x32_bf16 v[124:127], v[160:163], v[216:219], v[124:127]
	v_mfma_f32_16x16x32_bf16 v[120:123], v[188:191], v[216:219], v[120:123]
	v_mfma_f32_16x16x32_bf16 v[116:119], v[160:163], v[224:227], v[116:119]
	v_mfma_f32_16x16x32_bf16 v[112:115], v[188:191], v[224:227], v[112:115]
	v_mfma_f32_16x16x32_bf16 v[92:95], v[160:163], v[232:235], v[92:95]
	v_mfma_f32_16x16x32_bf16 v[88:91], v[188:191], v[232:235], v[88:91]
	v_mfma_f32_16x16x32_bf16 v[76:79], v[160:163], v[240:243], v[76:79]
	v_mfma_f32_16x16x32_bf16 v[72:75], v[188:191], v[240:243], v[72:75]
	s_setprio 0
	s_setprio 1
	v_mfma_f32_16x16x32_bf16 v[108:111], v[196:199], v[212:215], v[108:111]
	v_mfma_f32_16x16x32_bf16 v[104:107], v[204:207], v[212:215], v[104:107]
	v_mfma_f32_16x16x32_bf16 v[100:103], v[196:199], v[220:223], v[100:103]
	v_mfma_f32_16x16x32_bf16 v[96:99], v[204:207], v[220:223], v[96:99]
	v_mfma_f32_16x16x32_bf16 v[84:87], v[196:199], v[228:231], v[84:87]
	v_mfma_f32_16x16x32_bf16 v[80:83], v[204:207], v[228:231], v[80:83]
	v_mfma_f32_16x16x32_bf16 v[68:71], v[196:199], v[236:239], v[68:71]
	v_mfma_f32_16x16x32_bf16 v[64:67], v[204:207], v[236:239], v[64:67]
	v_mfma_f32_16x16x32_bf16 v[108:111], v[200:203], v[216:219], v[108:111]
	v_mfma_f32_16x16x32_bf16 v[104:107], v[208:211], v[216:219], v[104:107]
	v_mfma_f32_16x16x32_bf16 v[100:103], v[200:203], v[224:227], v[100:103]
	v_mfma_f32_16x16x32_bf16 v[96:99], v[208:211], v[224:227], v[96:99]
	v_mfma_f32_16x16x32_bf16 v[84:87], v[200:203], v[232:235], v[84:87]
	v_mfma_f32_16x16x32_bf16 v[80:83], v[208:211], v[232:235], v[80:83]
	v_mfma_f32_16x16x32_bf16 v[68:71], v[200:203], v[240:243], v[68:71]
	v_mfma_f32_16x16x32_bf16 v[64:67], v[208:211], v[240:243], v[64:67]
	s_setprio 0
	s_barrier
	s_add_i32 s22, s74, s46
	v_lshl_add_u64 v[138:139], v[138:139], 0, s[24:25]
	s_mov_b32 m0, s22
	ds_read_b128 v[212:215], v167 offset:49152
	ds_read_b128 v[216:219], v167 offset:50176
	ds_read_b128 v[220:223], v167 offset:51200
	ds_read_b128 v[224:227], v167 offset:52224
	ds_read_b128 v[228:231], v167 offset:53248
	ds_read_b128 v[232:235], v167 offset:54272
	ds_read_b128 v[236:239], v167 offset:55296
	ds_read_b128 v[240:243], v167 offset:56320
	global_load_lds_dwordx4 v[138:139], off
	s_add_i32 m0, s22, 0x2000
	s_add_u32 s2, s2, 0x40080
	v_lshl_add_u64 v[138:139], v[164:165], 0, s[24:25]
	s_addc_u32 s3, s3, 0
	s_add_i32 s22, s75, s46
	global_load_lds_dwordx4 v[138:139], off
	v_lshl_add_u64 v[138:139], s[2:3], 0, v[142:143]
	s_mov_b32 m0, s22
	s_nop 0
	global_load_lds_dwordx4 v[138:139], off
	v_lshl_add_u64 v[138:139], s[2:3], 0, v[146:147]
	s_add_i32 m0, s22, 0x2000
	s_nop 0
	global_load_lds_dwordx4 v[138:139], off
	v_lshl_add_u64 v[138:139], v[192:193], 0, s[24:25]
	s_mov_b32 m0, s54
	s_nop 0
	global_load_lds_dwordx4 v[138:139], off
	v_lshl_add_u64 v[138:139], v[244:245], 0, s[24:25]
	s_mov_b32 m0, s55
	s_nop 0
	global_load_lds_dwordx4 v[138:139], off
	s_waitcnt vmcnt(8)
	s_waitcnt lgkmcnt(0)
	s_barrier
	s_setprio 1
	s_waitcnt lgkmcnt(0)
	v_mfma_f32_16x16x32_bf16 v[60:63], v[156:159], v[212:215], v[60:63]
	v_mfma_f32_16x16x32_bf16 v[56:59], v[184:187], v[212:215], v[56:59]
	v_mfma_f32_16x16x32_bf16 v[44:47], v[156:159], v[220:223], v[44:47]
	v_mfma_f32_16x16x32_bf16 v[40:43], v[184:187], v[220:223], v[40:43]
	v_mfma_f32_16x16x32_bf16 v[28:31], v[156:159], v[228:231], v[28:31]
	v_mfma_f32_16x16x32_bf16 v[24:27], v[184:187], v[228:231], v[24:27]
	v_mfma_f32_16x16x32_bf16 v[12:15], v[156:159], v[236:239], v[12:15]
	v_mfma_f32_16x16x32_bf16 v[8:11], v[184:187], v[236:239], v[8:11]
	v_mfma_f32_16x16x32_bf16 v[60:63], v[160:163], v[216:219], v[60:63]
	v_mfma_f32_16x16x32_bf16 v[56:59], v[188:191], v[216:219], v[56:59]
	v_mfma_f32_16x16x32_bf16 v[44:47], v[160:163], v[224:227], v[44:47]
	v_mfma_f32_16x16x32_bf16 v[40:43], v[188:191], v[224:227], v[40:43]
	v_mfma_f32_16x16x32_bf16 v[28:31], v[160:163], v[232:235], v[28:31]
	v_mfma_f32_16x16x32_bf16 v[24:27], v[188:191], v[232:235], v[24:27]
	v_mfma_f32_16x16x32_bf16 v[12:15], v[160:163], v[240:243], v[12:15]
	v_mfma_f32_16x16x32_bf16 v[8:11], v[188:191], v[240:243], v[8:11]
	s_setprio 0
	s_setprio 1
	v_mfma_f32_16x16x32_bf16 v[52:55], v[196:199], v[212:215], v[52:55]
	v_mfma_f32_16x16x32_bf16 v[48:51], v[204:207], v[212:215], v[48:51]
	v_mfma_f32_16x16x32_bf16 v[36:39], v[196:199], v[220:223], v[36:39]
	v_mfma_f32_16x16x32_bf16 v[32:35], v[204:207], v[220:223], v[32:35]
	v_mfma_f32_16x16x32_bf16 v[20:23], v[196:199], v[228:231], v[20:23]
	v_mfma_f32_16x16x32_bf16 v[16:19], v[204:207], v[228:231], v[16:19]
	v_mfma_f32_16x16x32_bf16 v[4:7], v[196:199], v[236:239], v[4:7]
	v_mfma_f32_16x16x32_bf16 v[0:3], v[204:207], v[236:239], v[0:3]
	v_mfma_f32_16x16x32_bf16 v[52:55], v[200:203], v[216:219], v[52:55]
	v_mfma_f32_16x16x32_bf16 v[48:51], v[208:211], v[216:219], v[48:51]
	v_mfma_f32_16x16x32_bf16 v[36:39], v[200:203], v[224:227], v[36:39]
	v_mfma_f32_16x16x32_bf16 v[32:35], v[208:211], v[224:227], v[32:35]
	v_mfma_f32_16x16x32_bf16 v[20:23], v[200:203], v[232:235], v[20:23]
	v_mfma_f32_16x16x32_bf16 v[16:19], v[208:211], v[232:235], v[16:19]
	v_mfma_f32_16x16x32_bf16 v[4:7], v[200:203], v[240:243], v[4:7]
	v_mfma_f32_16x16x32_bf16 v[0:3], v[208:211], v[240:243], v[0:3]
	s_setprio 0
	s_barrier
	s_add_i32 s73, s73, 2
	s_add_u32 s14, s14, 0x100
	s_addc_u32 s15, s15, 0
	s_add_u32 s71, s71, 0x100
	s_addc_u32 s72, s72, 0
	s_cmp_gt_u32 s73, 13
	s_cbranch_scc1 .Lgemm_kdone_3

.Lgemm_kdone_3:
	s_and_b64 vcc, exec, s[26:27]
	s_cbranch_vccz .LBB0_555
	s_barrier
.LBB0_555:
	v_lshl_add_u32 v138, s0, 8, v149
	v_ashrrev_i32_e32 v139, 31, v138
	v_lshl_add_u64 v[156:157], v[138:139], 3, s[20:21]
	v_or_b32_e32 v186, 16, v138
	global_load_dwordx2 v[184:185], v[156:157], off
	v_ashrrev_i32_e32 v187, 31, v186
	v_or_b32_e32 v188, 32, v138
	v_lshl_add_u64 v[158:159], v[186:187], 3, s[20:21]
	v_ashrrev_i32_e32 v189, 31, v188
	v_lshl_add_u64 v[160:161], v[188:189], 3, s[20:21]
	global_load_dwordx2 v[190:191], v[158:159], off
	global_load_dwordx2 v[192:193], v[160:161], off
	v_or_b32_e32 v162, 48, v138
	v_ashrrev_i32_e32 v163, 31, v162
	v_lshl_add_u64 v[196:197], v[162:163], 3, s[20:21]
	global_load_dwordx2 v[164:165], v[156:157], off offset:1024
	global_load_dwordx2 v[160:161], v[156:157], off offset:1152
	global_load_dwordx2 v[158:159], v[156:157], off offset:1280
	s_nop 0
	global_load_dwordx2 v[196:197], v[196:197], off
	s_nop 0
	global_load_dwordx2 v[156:157], v[156:157], off offset:1408
	s_ashr_i32 s0, s1, 2
	s_sub_i32 s2, 1, s0
	s_cmp_lg_u32 s0, 2
	s_cselect_b32 s2, s2, 2
	s_mul_hi_i32 s3, s2, 0x4080000
	s_mul_i32 s2, s2, 0x4080000
	s_add_u32 s2, s16, s2
	s_addc_u32 s3, s17, s3
	s_lshl_b32 s1, s1, 8
	s_cmp_eq_u32 s0, 1
	s_cselect_b64 vcc, -1, 0
	s_and_b32 s0, s1, 0x300
	v_or_b32_e32 v128, s0, v153
	v_lshlrev_b32_e32 v128, 1, v128
	v_lshl_add_u64 v[198:199], s[2:3], 0, v[128:129]
	v_cndmask_b32_e32 v200, 1.0, v169, vcc
	v_lshlrev_b64 v[138:139], 11, v[138:139]
	v_lshlrev_b64 v[186:187], 11, v[186:187]
	v_lshl_add_u64 v[138:139], v[198:199], 0, v[138:139]
	v_lshl_add_u64 v[186:187], v[198:199], 0, v[186:187]
	v_readlane_b32 s72, v248, 23
	v_readlane_b32 s73, v248, 24
	s_waitcnt vmcnt(0)
	v_ffbh_u32_e32 v128, v185
	v_min_u32_e32 v128, 32, v128
	v_lshlrev_b64 v[184:185], v128, v[184:185]
	v_min_u32_e32 v184, 1, v184
	v_or_b32_e32 v184, v185, v184
	v_ffbh_u32_e32 v201, v191
	v_min_u32_e32 v201, 32, v201
	v_lshlrev_b64 v[190:191], v201, v[190:191]
	v_min_u32_e32 v185, 1, v190
	v_cvt_f32_u32_e32 v190, v184
	v_or_b32_e32 v184, v191, v185
	v_cvt_f32_u32_e32 v191, v184
	v_sub_u32_e32 v128, 32, v128
	v_sub_u32_e32 v201, 32, v201
	v_ldexp_f32 v128, v190, v128
	v_fmamk_f32 v128, v128, 0x30800000, v168
	v_ldexp_f32 v190, v191, v201
	v_fmamk_f32 v190, v190, 0x30800000, v168
	v_ffbh_u32_e32 v202, v193
	v_rsq_f32_e32 v128, v128
	v_rsq_f32_e32 v190, v190
	v_min_u32_e32 v202, 32, v202
	v_mul_f32_e32 v128, v200, v128
	v_mov_b32_e32 v201, v190
	v_lshlrev_b64 v[184:185], v202, v[192:193]
	v_pk_mul_f32 v[126:127], v[126:127], v[128:129] op_sel_hi:[1,0]
	v_pk_mul_f32 v[124:125], v[124:125], v[128:129] op_sel_hi:[1,0]
	v_pk_mul_f32 v[122:123], v[122:123], v[128:129] op_sel_hi:[1,0]
	v_pk_mul_f32 v[120:121], v[120:121], v[128:129] op_sel_hi:[1,0]
	v_pk_mul_f32 v[110:111], v[110:111], v[128:129] op_sel_hi:[1,0]
	v_pk_mul_f32 v[108:109], v[108:109], v[128:129] op_sel_hi:[1,0]
	v_pk_mul_f32 v[190:191], v[106:107], v[128:129] op_sel_hi:[1,0]
	v_pk_mul_f32 v[192:193], v[104:105], v[128:129] op_sel_hi:[1,0]
	v_mul_f32_e32 v128, v200, v201
	v_pk_mul_f32 v[118:119], v[118:119], v[128:129] op_sel_hi:[1,0]
	v_pk_mul_f32 v[116:117], v[116:117], v[128:129] op_sel_hi:[1,0]
	v_pk_mul_f32 v[114:115], v[114:115], v[128:129] op_sel_hi:[1,0]
	v_pk_mul_f32 v[112:113], v[112:113], v[128:129] op_sel_hi:[1,0]
	v_min_u32_e32 v184, 1, v184
	v_cvt_pk_bf16_f32 v104, v124, v125
	v_cvt_pk_bf16_f32 v105, v126, v127
	v_cvt_pk_bf16_f32 v106, v120, v121
	v_cvt_pk_bf16_f32 v107, v122, v123
	v_pk_mul_f32 v[120:121], v[98:99], v[128:129] op_sel_hi:[1,0]
	v_pk_mul_f32 v[122:123], v[96:97], v[128:129] op_sel_hi:[1,0]
	v_cvt_pk_bf16_f32 v96, v116, v117
	v_cvt_pk_bf16_f32 v97, v118, v119
	v_cvt_pk_bf16_f32 v98, v112, v113
	v_cvt_pk_bf16_f32 v99, v114, v115
	v_cvt_pk_bf16_f32 v108, v108, v109
	v_cvt_pk_bf16_f32 v109, v110, v111
	v_cvt_pk_bf16_f32 v110, v192, v193
	v_cvt_pk_bf16_f32 v111, v190, v191
	global_store_dwordx4 v[138:139], v[104:107], off
	global_store_dwordx4 v[138:139], v[108:111], off offset:256
	global_store_dwordx4 v[186:187], v[96:99], off
	v_pk_mul_f32 v[100:101], v[100:101], v[128:129] op_sel_hi:[1,0]
	v_pk_mul_f32 v[102:103], v[102:103], v[128:129] op_sel_hi:[1,0]
	v_or_b32_e32 v96, v185, v184
	v_cvt_f32_u32_e32 v98, v96
	v_sub_u32_e32 v99, 32, v202
	v_cvt_pk_bf16_f32 v96, v100, v101
	v_cvt_pk_bf16_f32 v97, v102, v103
	v_ldexp_f32 v98, v98, v99
	v_fmamk_f32 v98, v98, 0x30800000, v168
	s_mov_b64 s[0:1], -1
	s_nop 0
	v_rsq_f32_e32 v100, v98
	v_cvt_pk_bf16_f32 v98, v122, v123
	v_cvt_pk_bf16_f32 v99, v120, v121
	global_store_dwordx4 v[186:187], v[96:99], off offset:256
	s_nop 1
	v_mov_b32_e32 v96, v100
	v_mul_f32_e32 v96, v200, v96
	v_lshlrev_b64 v[98:99], 11, v[188:189]
	v_pk_mul_f32 v[94:95], v[94:95], v[96:97] op_sel_hi:[1,0]
	v_pk_mul_f32 v[92:93], v[92:93], v[96:97] op_sel_hi:[1,0]
	v_pk_mul_f32 v[100:101], v[90:91], v[96:97] op_sel_hi:[1,0]
	v_pk_mul_f32 v[90:91], v[88:89], v[96:97] op_sel_hi:[1,0]
	v_lshl_add_u64 v[98:99], v[198:199], 0, v[98:99]
	v_cvt_pk_bf16_f32 v88, v92, v93
	v_cvt_pk_bf16_f32 v89, v94, v95
	v_cvt_pk_bf16_f32 v90, v90, v91
	v_cvt_pk_bf16_f32 v91, v100, v101
	global_store_dwordx4 v[98:99], v[88:91], off
	v_pk_mul_f32 v[84:85], v[84:85], v[96:97] op_sel_hi:[1,0]
	v_pk_mul_f32 v[86:87], v[86:87], v[96:97] op_sel_hi:[1,0]
	v_pk_mul_f32 v[88:89], v[82:83], v[96:97] op_sel_hi:[1,0]
	v_pk_mul_f32 v[82:83], v[80:81], v[96:97] op_sel_hi:[1,0]
	v_ffbh_u32_e32 v80, v197
	v_min_u32_e32 v90, 32, v80
	v_lshlrev_b64 v[80:81], v90, v[196:197]
	v_min_u32_e32 v80, 1, v80
	v_or_b32_e32 v80, v81, v80
	v_cvt_f32_u32_e32 v91, v80
	v_cvt_pk_bf16_f32 v80, v84, v85
	v_sub_u32_e32 v84, 32, v90
	v_cvt_pk_bf16_f32 v81, v86, v87
	v_ldexp_f32 v84, v91, v84
	v_fmamk_f32 v84, v84, 0x30800000, v168
	v_cvt_pk_bf16_f32 v82, v82, v83
	v_cvt_pk_bf16_f32 v83, v88, v89
	v_rsq_f32_e32 v84, v84
	global_store_dwordx4 v[98:99], v[80:83], off offset:256
	s_nop 1
	v_mov_b32_e32 v80, v84
	v_mul_f32_e32 v80, v200, v80
	v_lshlrev_b64 v[82:83], 11, v[162:163]
	v_pk_mul_f32 v[78:79], v[78:79], v[80:81] op_sel_hi:[1,0]
	v_pk_mul_f32 v[76:77], v[76:77], v[80:81] op_sel_hi:[1,0]
	v_pk_mul_f32 v[84:85], v[74:75], v[80:81] op_sel_hi:[1,0]
	v_pk_mul_f32 v[74:75], v[72:73], v[80:81] op_sel_hi:[1,0]
	v_lshl_add_u64 v[82:83], v[198:199], 0, v[82:83]
	v_cvt_pk_bf16_f32 v72, v76, v77
	v_cvt_pk_bf16_f32 v73, v78, v79
	v_cvt_pk_bf16_f32 v74, v74, v75
	v_cvt_pk_bf16_f32 v75, v84, v85
	global_store_dwordx4 v[82:83], v[72:75], off
	v_pk_mul_f32 v[68:69], v[68:69], v[80:81] op_sel_hi:[1,0]
	v_pk_mul_f32 v[70:71], v[70:71], v[80:81] op_sel_hi:[1,0]
	v_pk_mul_f32 v[72:73], v[66:67], v[80:81] op_sel_hi:[1,0]
	v_pk_mul_f32 v[66:67], v[64:65], v[80:81] op_sel_hi:[1,0]
	v_ffbh_u32_e32 v64, v165
	v_min_u32_e32 v74, 32, v64
	v_lshlrev_b64 v[64:65], v74, v[164:165]
	v_min_u32_e32 v64, 1, v64
	v_or_b32_e32 v64, v65, v64
	v_cvt_f32_u32_e32 v75, v64
	v_cvt_pk_bf16_f32 v64, v68, v69
	v_sub_u32_e32 v68, 32, v74
	v_cvt_pk_bf16_f32 v65, v70, v71
	v_ldexp_f32 v68, v75, v68
	v_fmamk_f32 v68, v68, 0x30800000, v168
	v_cvt_pk_bf16_f32 v66, v66, v67
	v_cvt_pk_bf16_f32 v67, v72, v73
	v_rsq_f32_e32 v68, v68
	global_store_dwordx4 v[82:83], v[64:67], off offset:256
	s_nop 1
	v_mov_b32_e32 v64, v68
	v_mul_f32_e32 v64, v200, v64
	v_pk_mul_f32 v[60:61], v[60:61], v[64:65] op_sel_hi:[1,0]
	v_pk_mul_f32 v[62:63], v[62:63], v[64:65] op_sel_hi:[1,0]
	v_pk_mul_f32 v[68:69], v[58:59], v[64:65] op_sel_hi:[1,0]
	v_pk_mul_f32 v[58:59], v[56:57], v[64:65] op_sel_hi:[1,0]
	v_cvt_pk_bf16_f32 v56, v60, v61
	v_add_co_u32_e32 v60, vcc, s65, v138
	v_cvt_pk_bf16_f32 v57, v62, v63
	v_cvt_pk_bf16_f32 v58, v58, v59
	v_cvt_pk_bf16_f32 v59, v68, v69
	v_addc_co_u32_e32 v61, vcc, 0, v139, vcc
	global_store_dwordx4 v[60:61], v[56:59], off
	v_pk_mul_f32 v[52:53], v[52:53], v[64:65] op_sel_hi:[1,0]
	v_pk_mul_f32 v[54:55], v[54:55], v[64:65] op_sel_hi:[1,0]
	v_pk_mul_f32 v[56:57], v[50:51], v[64:65] op_sel_hi:[1,0]
	v_pk_mul_f32 v[50:51], v[48:49], v[64:65] op_sel_hi:[1,0]
	v_ffbh_u32_e32 v48, v161
	v_min_u32_e32 v58, 32, v48
	v_lshlrev_b64 v[48:49], v58, v[160:161]
	v_min_u32_e32 v48, 1, v48
	v_or_b32_e32 v48, v49, v48
	v_cvt_f32_u32_e32 v59, v48
	v_cvt_pk_bf16_f32 v48, v52, v53
	v_sub_u32_e32 v52, 32, v58
	v_lshl_add_u64 v[66:67], v[138:139], 0, s[6:7]
	v_ldexp_f32 v52, v59, v52
	v_fmamk_f32 v52, v52, 0x30800000, v168
	v_cvt_pk_bf16_f32 v49, v54, v55
	v_cvt_pk_bf16_f32 v50, v50, v51
	v_rsq_f32_e32 v52, v52
	v_cvt_pk_bf16_f32 v51, v56, v57
	global_store_dwordx4 v[66:67], v[48:51], off offset:256
	s_nop 1
	v_mov_b32_e32 v48, v52
	v_mul_f32_e32 v48, v200, v48
	v_pk_mul_f32 v[44:45], v[44:45], v[48:49] op_sel_hi:[1,0]
	v_pk_mul_f32 v[46:47], v[46:47], v[48:49] op_sel_hi:[1,0]
	v_pk_mul_f32 v[52:53], v[42:43], v[48:49] op_sel_hi:[1,0]
	v_pk_mul_f32 v[42:43], v[40:41], v[48:49] op_sel_hi:[1,0]
	v_cvt_pk_bf16_f32 v40, v44, v45
	v_add_co_u32_e32 v44, vcc, s66, v138
	v_cvt_pk_bf16_f32 v41, v46, v47
	v_cvt_pk_bf16_f32 v42, v42, v43
	v_cvt_pk_bf16_f32 v43, v52, v53
	v_addc_co_u32_e32 v45, vcc, 0, v139, vcc
	global_store_dwordx4 v[44:45], v[40:43], off
	v_pk_mul_f32 v[36:37], v[36:37], v[48:49] op_sel_hi:[1,0]
	v_pk_mul_f32 v[38:39], v[38:39], v[48:49] op_sel_hi:[1,0]
	v_pk_mul_f32 v[40:41], v[34:35], v[48:49] op_sel_hi:[1,0]
	v_pk_mul_f32 v[34:35], v[32:33], v[48:49] op_sel_hi:[1,0]
	v_ffbh_u32_e32 v32, v159
	v_min_u32_e32 v42, 32, v32
	v_lshlrev_b64 v[32:33], v42, v[158:159]
	v_min_u32_e32 v32, 1, v32
	v_or_b32_e32 v32, v33, v32
	v_cvt_f32_u32_e32 v43, v32
	v_cvt_pk_bf16_f32 v32, v36, v37
	v_sub_u32_e32 v36, 32, v42
	v_lshl_add_u64 v[50:51], v[138:139], 0, s[28:29]
	v_ldexp_f32 v36, v43, v36
	v_fmamk_f32 v36, v36, 0x30800000, v168
	v_cvt_pk_bf16_f32 v33, v38, v39
	v_cvt_pk_bf16_f32 v34, v34, v35
	v_rsq_f32_e32 v36, v36
	v_cvt_pk_bf16_f32 v35, v40, v41
	global_store_dwordx4 v[50:51], v[32:35], off offset:256
	s_nop 1
	v_mov_b32_e32 v32, v36
	v_mul_f32_e32 v32, v200, v32
	v_pk_mul_f32 v[28:29], v[28:29], v[32:33] op_sel_hi:[1,0]
	v_pk_mul_f32 v[30:31], v[30:31], v[32:33] op_sel_hi:[1,0]
	v_pk_mul_f32 v[36:37], v[26:27], v[32:33] op_sel_hi:[1,0]
	v_pk_mul_f32 v[26:27], v[24:25], v[32:33] op_sel_hi:[1,0]
	v_cvt_pk_bf16_f32 v24, v28, v29
	v_add_co_u32_e32 v28, vcc, s67, v138
	v_cvt_pk_bf16_f32 v25, v30, v31
	v_cvt_pk_bf16_f32 v26, v26, v27
	v_cvt_pk_bf16_f32 v27, v36, v37
	v_addc_co_u32_e32 v29, vcc, 0, v139, vcc
	global_store_dwordx4 v[28:29], v[24:27], off
	v_pk_mul_f32 v[20:21], v[20:21], v[32:33] op_sel_hi:[1,0]
	v_pk_mul_f32 v[22:23], v[22:23], v[32:33] op_sel_hi:[1,0]
	v_pk_mul_f32 v[24:25], v[18:19], v[32:33] op_sel_hi:[1,0]
	v_pk_mul_f32 v[18:19], v[16:17], v[32:33] op_sel_hi:[1,0]
	v_ffbh_u32_e32 v16, v157
	v_min_u32_e32 v26, 32, v16
	v_lshlrev_b64 v[16:17], v26, v[156:157]
	v_min_u32_e32 v16, 1, v16
	v_or_b32_e32 v16, v17, v16
	v_cvt_f32_u32_e32 v27, v16
	v_cvt_pk_bf16_f32 v16, v20, v21
	v_sub_u32_e32 v20, 32, v26
	v_lshl_add_u64 v[34:35], v[138:139], 0, s[30:31]
	v_ldexp_f32 v20, v27, v20
	v_fmamk_f32 v20, v20, 0x30800000, v168
	v_cvt_pk_bf16_f32 v17, v22, v23
	v_cvt_pk_bf16_f32 v18, v18, v19
	v_rsq_f32_e32 v20, v20
	v_cvt_pk_bf16_f32 v19, v24, v25
	global_store_dwordx4 v[34:35], v[16:19], off offset:256
	s_nop 1
	v_mov_b32_e32 v16, v20
	v_mul_f32_e32 v16, v200, v16
	v_pk_mul_f32 v[12:13], v[12:13], v[16:17] op_sel_hi:[1,0]
	v_pk_mul_f32 v[14:15], v[14:15], v[16:17] op_sel_hi:[1,0]
	v_pk_mul_f32 v[20:21], v[10:11], v[16:17] op_sel_hi:[1,0]
	v_pk_mul_f32 v[10:11], v[8:9], v[16:17] op_sel_hi:[1,0]
	v_cvt_pk_bf16_f32 v8, v12, v13
	v_add_co_u32_e32 v12, vcc, s68, v138
	v_cvt_pk_bf16_f32 v9, v14, v15
	v_cvt_pk_bf16_f32 v10, v10, v11
	v_cvt_pk_bf16_f32 v11, v20, v21
	v_addc_co_u32_e32 v13, vcc, 0, v139, vcc
	global_store_dwordx4 v[12:13], v[8:11], off
	v_pk_mul_f32 v[6:7], v[6:7], v[16:17] op_sel_hi:[1,0]
	v_pk_mul_f32 v[4:5], v[4:5], v[16:17] op_sel_hi:[1,0]
	v_pk_mul_f32 v[8:9], v[2:3], v[16:17] op_sel_hi:[1,0]
	v_pk_mul_f32 v[2:3], v[0:1], v[16:17] op_sel_hi:[1,0]
	v_lshl_add_u64 v[18:19], v[138:139], 0, s[36:37]
	v_cvt_pk_bf16_f32 v0, v4, v5
	v_cvt_pk_bf16_f32 v1, v6, v7
	v_cvt_pk_bf16_f32 v2, v2, v3
	v_cvt_pk_bf16_f32 v3, v8, v9
	s_andn2_b64 vcc, exec, s[4:5]
	global_store_dwordx4 v[18:19], v[0:3], off offset:256
	s_cbranch_vccnz .LBB0_548
	s_andn2_b64 vcc, exec, s[10:11]
	s_cbranch_vccnz .LBB0_547
	s_barrier
	s_branch .LBB0_547

.LBB0_724:
	s_ashr_i32 s27, s26, 31
	s_lshl_b64 s[22:23], s[26:27], 19
	s_add_u32 s28, s16, s22
	s_addc_u32 s29, s17, s23
	s_and_b64 s[22:23], s[6:7], exec
	s_cselect_b32 s27, s29, s15
	s_cselect_b32 s59, s28, s14
	s_ashr_i32 s25, s24, 31
	s_lshl_b64 s[22:23], s[24:25], 19
	s_add_u32 s30, s35, s22
	s_addc_u32 s31, s38, s23
	s_and_b64 s[22:23], s[6:7], exec
	s_cselect_b32 s25, s31, s3
	s_cselect_b32 s64, s30, s2
	s_add_u32 s14, s14, 0x40080
	s_addc_u32 s15, s15, 0
	s_add_u32 s65, s2, 0x100
	s_addc_u32 s66, s3, 0
	s_mov_b32 s67, -2
	s_waitcnt lgkmcnt(0)
	s_waitcnt vmcnt(0)
	ds_read_b128 v[128:131], v155
	ds_read_b128 v[132:135], v155 offset:1024
	ds_read_b128 v[136:139], v155 offset:2048
	ds_read_b128 v[164:167], v155 offset:3072
	ds_read_b128 v[188:191], v184
	ds_read_b128 v[196:199], v184 offset:1024
	ds_read_b128 v[200:203], v184 offset:2048
	ds_read_b128 v[204:207], v184 offset:3072
	s_add_u32 s2, s14, 0xfffc0080
	s_addc_u32 s3, s15, -1
	s_cmp_eq_u32 s67, 12
	s_cselect_b32 s23, s27, s3
	s_cselect_b32 s22, s59, s2
	s_cselect_b32 s3, s25, s66
	s_cselect_b32 s2, s64, s65
	v_lshl_add_u64 v[168:169], s[14:15], 0, v[156:157]
	s_add_i32 m0, s37, 0xc000
	ds_read_b128 v[208:211], v185
	ds_read_b128 v[212:215], v185 offset:1024
	ds_read_b128 v[216:219], v185 offset:2048
	ds_read_b128 v[220:223], v185 offset:3072
	ds_read_b128 v[224:227], v185 offset:4096
	ds_read_b128 v[228:231], v185 offset:5120
	ds_read_b128 v[232:235], v185 offset:6144
	ds_read_b128 v[236:239], v185 offset:7168
	global_load_lds_dwordx4 v[168:169], off
	v_lshl_add_u64 v[168:169], s[14:15], 0, v[158:159]
	s_add_i32 m0, s37, 0xe000
	s_nop 0
	global_load_lds_dwordx4 v[168:169], off
	s_waitcnt vmcnt(8)
	s_waitcnt lgkmcnt(0)
	s_barrier
	s_setprio 1
	s_waitcnt lgkmcnt(0)
	v_mfma_f32_16x16x32_bf16 v[124:127], v[128:131], v[208:211], 0
	v_mfma_f32_16x16x32_bf16 v[120:123], v[136:139], v[208:211], 0
	v_mfma_f32_16x16x32_bf16 v[108:111], v[128:131], v[216:219], 0
	v_mfma_f32_16x16x32_bf16 v[104:107], v[136:139], v[216:219], 0
	v_mfma_f32_16x16x32_bf16 v[92:95], v[128:131], v[224:227], 0
	v_mfma_f32_16x16x32_bf16 v[88:91], v[136:139], v[224:227], 0
	v_mfma_f32_16x16x32_bf16 v[76:79], v[128:131], v[232:235], 0
	v_mfma_f32_16x16x32_bf16 v[72:75], v[136:139], v[232:235], 0
	v_mfma_f32_16x16x32_bf16 v[124:127], v[132:135], v[212:215], v[124:127]
	v_mfma_f32_16x16x32_bf16 v[120:123], v[164:167], v[212:215], v[120:123]
	v_mfma_f32_16x16x32_bf16 v[108:111], v[132:135], v[220:223], v[108:111]
	v_mfma_f32_16x16x32_bf16 v[104:107], v[164:167], v[220:223], v[104:107]
	v_mfma_f32_16x16x32_bf16 v[92:95], v[132:135], v[228:231], v[92:95]
	v_mfma_f32_16x16x32_bf16 v[88:91], v[164:167], v[228:231], v[88:91]
	v_mfma_f32_16x16x32_bf16 v[76:79], v[132:135], v[236:239], v[76:79]
	v_mfma_f32_16x16x32_bf16 v[72:75], v[164:167], v[236:239], v[72:75]
	s_setprio 0
	s_setprio 1
	v_mfma_f32_16x16x32_bf16 v[116:119], v[188:191], v[208:211], 0
	v_mfma_f32_16x16x32_bf16 v[112:115], v[200:203], v[208:211], 0
	v_mfma_f32_16x16x32_bf16 v[100:103], v[188:191], v[216:219], 0
	v_mfma_f32_16x16x32_bf16 v[96:99], v[200:203], v[216:219], 0
	v_mfma_f32_16x16x32_bf16 v[84:87], v[188:191], v[224:227], 0
	v_mfma_f32_16x16x32_bf16 v[80:83], v[200:203], v[224:227], 0
	v_mfma_f32_16x16x32_bf16 v[68:71], v[188:191], v[232:235], 0
	v_mfma_f32_16x16x32_bf16 v[64:67], v[200:203], v[232:235], 0
	v_mfma_f32_16x16x32_bf16 v[116:119], v[196:199], v[212:215], v[116:119]
	v_mfma_f32_16x16x32_bf16 v[112:115], v[204:207], v[212:215], v[112:115]
	v_mfma_f32_16x16x32_bf16 v[100:103], v[196:199], v[220:223], v[100:103]
	v_mfma_f32_16x16x32_bf16 v[96:99], v[204:207], v[220:223], v[96:99]
	v_mfma_f32_16x16x32_bf16 v[84:87], v[196:199], v[228:231], v[84:87]
	v_mfma_f32_16x16x32_bf16 v[80:83], v[204:207], v[228:231], v[80:83]
	v_mfma_f32_16x16x32_bf16 v[68:71], v[196:199], v[236:239], v[68:71]
	v_mfma_f32_16x16x32_bf16 v[64:67], v[204:207], v[236:239], v[64:67]
	s_setprio 0
	s_barrier
	s_add_i32 s68, s52, s39
	v_lshl_add_u64 v[168:169], s[2:3], 0, v[142:143]
	s_mov_b32 m0, s68
	ds_read_b128 v[208:211], v185 offset:16384
	ds_read_b128 v[212:215], v185 offset:17408
	ds_read_b128 v[216:219], v185 offset:18432
	ds_read_b128 v[220:223], v185 offset:19456
	ds_read_b128 v[224:227], v185 offset:20480
	ds_read_b128 v[228:231], v185 offset:21504
	ds_read_b128 v[232:235], v185 offset:22528
	ds_read_b128 v[236:239], v185 offset:23552
	global_load_lds_dwordx4 v[168:169], off
	s_add_i32 m0, s68, 0x2000
	s_add_u32 s68, s2, 0x40000
	v_lshl_add_u64 v[192:193], s[2:3], 0, v[146:147]
	s_addc_u32 s69, s3, 0
	s_add_i32 s70, s53, s39
	global_load_lds_dwordx4 v[192:193], off
	v_lshl_add_u64 v[240:241], s[68:69], 0, v[142:143]
	s_mov_b32 m0, s70
	v_lshl_add_u64 v[242:243], s[22:23], 0, v[144:145]
	global_load_lds_dwordx4 v[240:241], off
	v_lshl_add_u64 v[240:241], s[68:69], 0, v[146:147]
	s_add_i32 m0, s70, 0x2000
	s_nop 0
	global_load_lds_dwordx4 v[240:241], off
	v_lshl_add_u64 v[240:241], s[22:23], 0, v[140:141]
	s_mov_b32 m0, s37
	s_nop 0
	global_load_lds_dwordx4 v[240:241], off
	s_mov_b32 m0, s40
	s_nop 0
	global_load_lds_dwordx4 v[242:243], off
	s_waitcnt vmcnt(8)
	s_waitcnt lgkmcnt(0)
	s_barrier
	s_setprio 1
	s_waitcnt lgkmcnt(0)
	v_mfma_f32_16x16x32_bf16 v[60:63], v[128:131], v[208:211], 0
	v_mfma_f32_16x16x32_bf16 v[56:59], v[136:139], v[208:211], 0
	v_mfma_f32_16x16x32_bf16 v[44:47], v[128:131], v[216:219], 0
	v_mfma_f32_16x16x32_bf16 v[40:43], v[136:139], v[216:219], 0
	v_mfma_f32_16x16x32_bf16 v[28:31], v[128:131], v[224:227], 0
	v_mfma_f32_16x16x32_bf16 v[24:27], v[136:139], v[224:227], 0
	v_mfma_f32_16x16x32_bf16 v[12:15], v[128:131], v[232:235], 0
	v_mfma_f32_16x16x32_bf16 v[8:11], v[136:139], v[232:235], 0
	v_mfma_f32_16x16x32_bf16 v[60:63], v[132:135], v[212:215], v[60:63]
	v_mfma_f32_16x16x32_bf16 v[56:59], v[164:167], v[212:215], v[56:59]
	v_mfma_f32_16x16x32_bf16 v[44:47], v[132:135], v[220:223], v[44:47]
	v_mfma_f32_16x16x32_bf16 v[40:43], v[164:167], v[220:223], v[40:43]
	v_mfma_f32_16x16x32_bf16 v[28:31], v[132:135], v[228:231], v[28:31]
	v_mfma_f32_16x16x32_bf16 v[24:27], v[164:167], v[228:231], v[24:27]
	v_mfma_f32_16x16x32_bf16 v[12:15], v[132:135], v[236:239], v[12:15]
	v_mfma_f32_16x16x32_bf16 v[8:11], v[164:167], v[236:239], v[8:11]
	s_setprio 0
	s_setprio 1
	v_mfma_f32_16x16x32_bf16 v[52:55], v[188:191], v[208:211], 0
	v_mfma_f32_16x16x32_bf16 v[48:51], v[200:203], v[208:211], 0
	v_mfma_f32_16x16x32_bf16 v[36:39], v[188:191], v[216:219], 0
	v_mfma_f32_16x16x32_bf16 v[32:35], v[200:203], v[216:219], 0
	v_mfma_f32_16x16x32_bf16 v[20:23], v[188:191], v[224:227], 0
	v_mfma_f32_16x16x32_bf16 v[16:19], v[200:203], v[224:227], 0
	v_mfma_f32_16x16x32_bf16 v[4:7], v[188:191], v[232:235], 0
	v_mfma_f32_16x16x32_bf16 v[0:3], v[200:203], v[232:235], 0
	v_mfma_f32_16x16x32_bf16 v[52:55], v[196:199], v[212:215], v[52:55]
	v_mfma_f32_16x16x32_bf16 v[48:51], v[204:207], v[212:215], v[48:51]
	v_mfma_f32_16x16x32_bf16 v[36:39], v[196:199], v[220:223], v[36:39]
	v_mfma_f32_16x16x32_bf16 v[32:35], v[204:207], v[220:223], v[32:35]
	v_mfma_f32_16x16x32_bf16 v[20:23], v[196:199], v[228:231], v[20:23]
	v_mfma_f32_16x16x32_bf16 v[16:19], v[204:207], v[228:231], v[16:19]
	v_mfma_f32_16x16x32_bf16 v[4:7], v[196:199], v[236:239], v[4:7]
	v_mfma_f32_16x16x32_bf16 v[0:3], v[204:207], v[236:239], v[0:3]
	s_setprio 0
	s_barrier
	s_add_i32 s68, 0, 0x18000
	s_add_i32 s69, 0, 0x1c000
	v_add_u32_e32 v164, s68, v149
	v_add_u32_e32 v187, s69, v149
	ds_read_b128 v[128:131], v164
	ds_read_b128 v[132:135], v164 offset:1024
	ds_read_b128 v[136:139], v164 offset:2048
	ds_read_b128 v[164:167], v164 offset:3072
	ds_read_b128 v[188:191], v187
	ds_read_b128 v[196:199], v187 offset:1024
	ds_read_b128 v[200:203], v187 offset:2048
	ds_read_b128 v[204:207], v187 offset:3072
	s_add_u32 s22, s22, 0x40000
	s_addc_u32 s23, s23, 0
	s_mov_b32 m0, s41
	v_lshl_add_u64 v[244:245], s[22:23], 0, v[140:141]
	ds_read_b128 v[208:211], v185 offset:32768
	ds_read_b128 v[212:215], v185 offset:33792
	ds_read_b128 v[216:219], v185 offset:34816
	ds_read_b128 v[220:223], v185 offset:35840
	ds_read_b128 v[224:227], v185 offset:36864
	ds_read_b128 v[228:231], v185 offset:37888
	ds_read_b128 v[232:235], v185 offset:38912
	ds_read_b128 v[236:239], v185 offset:39936
	global_load_lds_dwordx4 v[244:245], off
	v_lshl_add_u64 v[244:245], s[22:23], 0, v[144:145]
	s_mov_b32 m0, s42
	s_nop 0
	global_load_lds_dwordx4 v[244:245], off
	s_waitcnt vmcnt(8)
	s_waitcnt lgkmcnt(0)
	s_barrier
	s_setprio 1
	s_waitcnt lgkmcnt(0)
	v_mfma_f32_16x16x32_bf16 v[124:127], v[128:131], v[208:211], v[124:127]
	v_mfma_f32_16x16x32_bf16 v[120:123], v[136:139], v[208:211], v[120:123]
	v_mfma_f32_16x16x32_bf16 v[108:111], v[128:131], v[216:219], v[108:111]
	v_mfma_f32_16x16x32_bf16 v[104:107], v[136:139], v[216:219], v[104:107]
	v_mfma_f32_16x16x32_bf16 v[92:95], v[128:131], v[224:227], v[92:95]
	v_mfma_f32_16x16x32_bf16 v[88:91], v[136:139], v[224:227], v[88:91]
	v_mfma_f32_16x16x32_bf16 v[76:79], v[128:131], v[232:235], v[76:79]
	v_mfma_f32_16x16x32_bf16 v[72:75], v[136:139], v[232:235], v[72:75]
	v_mfma_f32_16x16x32_bf16 v[124:127], v[132:135], v[212:215], v[124:127]
	v_mfma_f32_16x16x32_bf16 v[120:123], v[164:167], v[212:215], v[120:123]
	v_mfma_f32_16x16x32_bf16 v[108:111], v[132:135], v[220:223], v[108:111]
	v_mfma_f32_16x16x32_bf16 v[104:107], v[164:167], v[220:223], v[104:107]
	v_mfma_f32_16x16x32_bf16 v[92:95], v[132:135], v[228:231], v[92:95]
	v_mfma_f32_16x16x32_bf16 v[88:91], v[164:167], v[228:231], v[88:91]
	v_mfma_f32_16x16x32_bf16 v[76:79], v[132:135], v[236:239], v[76:79]
	v_mfma_f32_16x16x32_bf16 v[72:75], v[164:167], v[236:239], v[72:75]
	s_setprio 0
	s_setprio 1
	v_mfma_f32_16x16x32_bf16 v[116:119], v[188:191], v[208:211], v[116:119]
	v_mfma_f32_16x16x32_bf16 v[112:115], v[200:203], v[208:211], v[112:115]
	v_mfma_f32_16x16x32_bf16 v[100:103], v[188:191], v[216:219], v[100:103]
	v_mfma_f32_16x16x32_bf16 v[96:99], v[200:203], v[216:219], v[96:99]
	v_mfma_f32_16x16x32_bf16 v[84:87], v[188:191], v[224:227], v[84:87]
	v_mfma_f32_16x16x32_bf16 v[80:83], v[200:203], v[224:227], v[80:83]
	v_mfma_f32_16x16x32_bf16 v[68:71], v[188:191], v[232:235], v[68:71]
	v_mfma_f32_16x16x32_bf16 v[64:67], v[200:203], v[232:235], v[64:67]
	v_mfma_f32_16x16x32_bf16 v[116:119], v[196:199], v[212:215], v[116:119]
	v_mfma_f32_16x16x32_bf16 v[112:115], v[204:207], v[212:215], v[112:115]
	v_mfma_f32_16x16x32_bf16 v[100:103], v[196:199], v[220:223], v[100:103]
	v_mfma_f32_16x16x32_bf16 v[96:99], v[204:207], v[220:223], v[96:99]
	v_mfma_f32_16x16x32_bf16 v[84:87], v[196:199], v[228:231], v[84:87]
	v_mfma_f32_16x16x32_bf16 v[80:83], v[204:207], v[228:231], v[80:83]
	v_mfma_f32_16x16x32_bf16 v[68:71], v[196:199], v[236:239], v[68:71]
	v_mfma_f32_16x16x32_bf16 v[64:67], v[204:207], v[236:239], v[64:67]
	s_setprio 0
	s_barrier
	s_add_i32 s22, s68, s39
	v_lshl_add_u64 v[168:169], v[168:169], 0, s[18:19]
	s_mov_b32 m0, s22
	ds_read_b128 v[208:211], v185 offset:49152
	ds_read_b128 v[212:215], v185 offset:50176
	ds_read_b128 v[216:219], v185 offset:51200
	ds_read_b128 v[220:223], v185 offset:52224
	ds_read_b128 v[224:227], v185 offset:53248
	ds_read_b128 v[228:231], v185 offset:54272
	ds_read_b128 v[232:235], v185 offset:55296
	ds_read_b128 v[236:239], v185 offset:56320
	global_load_lds_dwordx4 v[168:169], off
	s_add_i32 m0, s22, 0x2000
	s_add_u32 s2, s2, 0x40080
	v_lshl_add_u64 v[168:169], v[192:193], 0, s[18:19]
	s_addc_u32 s3, s3, 0
	s_add_i32 s22, s69, s39
	global_load_lds_dwordx4 v[168:169], off
	v_lshl_add_u64 v[168:169], s[2:3], 0, v[142:143]
	s_mov_b32 m0, s22
	s_nop 0
	global_load_lds_dwordx4 v[168:169], off
	v_lshl_add_u64 v[168:169], s[2:3], 0, v[146:147]
	s_add_i32 m0, s22, 0x2000
	s_nop 0
	global_load_lds_dwordx4 v[168:169], off
	v_lshl_add_u64 v[168:169], v[240:241], 0, s[18:19]
	s_mov_b32 m0, s46
	s_nop 0
	global_load_lds_dwordx4 v[168:169], off
	v_lshl_add_u64 v[168:169], v[242:243], 0, s[18:19]
	s_mov_b32 m0, s47
	s_nop 0
	global_load_lds_dwordx4 v[168:169], off
	s_waitcnt vmcnt(8)
	s_waitcnt lgkmcnt(0)
	s_barrier
	s_setprio 1
	s_waitcnt lgkmcnt(0)
	v_mfma_f32_16x16x32_bf16 v[60:63], v[128:131], v[208:211], v[60:63]
	v_mfma_f32_16x16x32_bf16 v[56:59], v[136:139], v[208:211], v[56:59]
	v_mfma_f32_16x16x32_bf16 v[44:47], v[128:131], v[216:219], v[44:47]
	v_mfma_f32_16x16x32_bf16 v[40:43], v[136:139], v[216:219], v[40:43]
	v_mfma_f32_16x16x32_bf16 v[28:31], v[128:131], v[224:227], v[28:31]
	v_mfma_f32_16x16x32_bf16 v[24:27], v[136:139], v[224:227], v[24:27]
	v_mfma_f32_16x16x32_bf16 v[12:15], v[128:131], v[232:235], v[12:15]
	v_mfma_f32_16x16x32_bf16 v[8:11], v[136:139], v[232:235], v[8:11]
	v_mfma_f32_16x16x32_bf16 v[60:63], v[132:135], v[212:215], v[60:63]
	v_mfma_f32_16x16x32_bf16 v[56:59], v[164:167], v[212:215], v[56:59]
	v_mfma_f32_16x16x32_bf16 v[44:47], v[132:135], v[220:223], v[44:47]
	v_mfma_f32_16x16x32_bf16 v[40:43], v[164:167], v[220:223], v[40:43]
	v_mfma_f32_16x16x32_bf16 v[28:31], v[132:135], v[228:231], v[28:31]
	v_mfma_f32_16x16x32_bf16 v[24:27], v[164:167], v[228:231], v[24:27]
	v_mfma_f32_16x16x32_bf16 v[12:15], v[132:135], v[236:239], v[12:15]
	v_mfma_f32_16x16x32_bf16 v[8:11], v[164:167], v[236:239], v[8:11]
	s_setprio 0
	s_setprio 1
	v_mfma_f32_16x16x32_bf16 v[52:55], v[188:191], v[208:211], v[52:55]
	v_mfma_f32_16x16x32_bf16 v[48:51], v[200:203], v[208:211], v[48:51]
	v_mfma_f32_16x16x32_bf16 v[36:39], v[188:191], v[216:219], v[36:39]
	v_mfma_f32_16x16x32_bf16 v[32:35], v[200:203], v[216:219], v[32:35]
	v_mfma_f32_16x16x32_bf16 v[20:23], v[188:191], v[224:227], v[20:23]
	v_mfma_f32_16x16x32_bf16 v[16:19], v[200:203], v[224:227], v[16:19]
	v_mfma_f32_16x16x32_bf16 v[4:7], v[188:191], v[232:235], v[4:7]
	v_mfma_f32_16x16x32_bf16 v[0:3], v[200:203], v[232:235], v[0:3]
	v_mfma_f32_16x16x32_bf16 v[52:55], v[196:199], v[212:215], v[52:55]
	v_mfma_f32_16x16x32_bf16 v[48:51], v[204:207], v[212:215], v[48:51]
	v_mfma_f32_16x16x32_bf16 v[36:39], v[196:199], v[220:223], v[36:39]
	v_mfma_f32_16x16x32_bf16 v[32:35], v[204:207], v[220:223], v[32:35]
	v_mfma_f32_16x16x32_bf16 v[20:23], v[196:199], v[228:231], v[20:23]
	v_mfma_f32_16x16x32_bf16 v[16:19], v[204:207], v[228:231], v[16:19]
	v_mfma_f32_16x16x32_bf16 v[4:7], v[196:199], v[236:239], v[4:7]
	v_mfma_f32_16x16x32_bf16 v[0:3], v[204:207], v[236:239], v[0:3]
	s_setprio 0
	s_barrier
	s_add_i32 s67, s67, 2
	s_add_u32 s14, s14, 0x100
	s_addc_u32 s15, s15, 0
	s_add_u32 s65, s65, 0x100
	s_addc_u32 s66, s66, 0
	s_cmp_gt_u32 s67, 13
	s_cbranch_scc1 .Lgemm_kdone_4

.Lgemm_kdone_4:
	s_and_b64 vcc, exec, s[20:21]
	s_cbranch_vccz .LBB0_728
	s_barrier

.LBB0_808:
	s_ashr_i32 s25, s24, 31
	s_lshl_b64 s[22:23], s[24:25], 19
	s_add_u32 s26, s84, s22
	s_addc_u32 s27, s85, s23
	s_and_b64 s[22:23], s[4:5], exec
	s_cselect_b32 s25, s27, s15
	s_cselect_b32 s50, s26, s14
	s_ashr_i32 s21, s20, 31
	s_lshl_b64 s[22:23], s[20:21], 19
	s_add_u32 s28, s30, s22
	s_addc_u32 s29, s31, s23
	s_and_b64 s[22:23], s[4:5], exec
	s_cselect_b32 s21, s29, s3
	s_cselect_b32 s51, s28, s2
	s_add_u32 s14, s14, 0x40080
	s_addc_u32 s15, s15, 0
	s_add_u32 s52, s2, 0x100
	s_addc_u32 s53, s3, 0
	s_mov_b32 s54, -2
	s_waitcnt vmcnt(0)
	ds_read_b128 v[136:139], v155
	ds_read_b128 v[162:165], v155 offset:1024
	ds_read_b128 v[166:169], v155 offset:2048
	ds_read_b128 v[178:181], v155 offset:3072
	ds_read_b128 v[184:187], v158
	ds_read_b128 v[188:191], v158 offset:1024
	ds_read_b128 v[196:199], v158 offset:2048
	ds_read_b128 v[200:203], v158 offset:3072
	s_add_u32 s2, s14, 0xfffc0080
	s_addc_u32 s3, s15, -1
	s_cmp_eq_u32 s54, 12
	s_cselect_b32 s23, s25, s3
	s_cselect_b32 s22, s50, s2
	s_cselect_b32 s3, s21, s53
	s_cselect_b32 s2, s51, s52
	v_lshl_add_u64 v[156:157], s[14:15], 0, v[128:129]
	s_add_i32 m0, s37, 0xc000
	ds_read_b128 v[204:207], v159
	ds_read_b128 v[208:211], v159 offset:1024
	ds_read_b128 v[212:215], v159 offset:2048
	ds_read_b128 v[216:219], v159 offset:3072
	ds_read_b128 v[220:223], v159 offset:4096
	ds_read_b128 v[224:227], v159 offset:5120
	ds_read_b128 v[228:231], v159 offset:6144
	ds_read_b128 v[232:235], v159 offset:7168
	global_load_lds_dwordx4 v[156:157], off
	v_lshl_add_u64 v[156:157], s[14:15], 0, v[130:131]
	s_add_i32 m0, s37, 0xe000
	s_nop 0
	global_load_lds_dwordx4 v[156:157], off
	s_waitcnt vmcnt(8)
	s_waitcnt lgkmcnt(0)
	s_barrier
	s_setprio 1
	s_waitcnt lgkmcnt(0)
	v_mfma_f32_16x16x32_bf16 v[112:115], v[136:139], v[204:207], 0
	v_mfma_f32_16x16x32_bf16 v[108:111], v[166:169], v[204:207], 0
	v_mfma_f32_16x16x32_bf16 v[104:107], v[136:139], v[212:215], 0
	v_mfma_f32_16x16x32_bf16 v[100:103], v[166:169], v[212:215], 0
	v_mfma_f32_16x16x32_bf16 v[92:95], v[136:139], v[220:223], 0
	v_mfma_f32_16x16x32_bf16 v[84:87], v[166:169], v[220:223], 0
	v_mfma_f32_16x16x32_bf16 v[76:79], v[136:139], v[228:231], 0
	v_mfma_f32_16x16x32_bf16 v[68:71], v[166:169], v[228:231], 0
	v_mfma_f32_16x16x32_bf16 v[112:115], v[162:165], v[208:211], v[112:115]
	v_mfma_f32_16x16x32_bf16 v[108:111], v[178:181], v[208:211], v[108:111]
	v_mfma_f32_16x16x32_bf16 v[104:107], v[162:165], v[216:219], v[104:107]
	v_mfma_f32_16x16x32_bf16 v[100:103], v[178:181], v[216:219], v[100:103]
	v_mfma_f32_16x16x32_bf16 v[92:95], v[162:165], v[224:227], v[92:95]
	v_mfma_f32_16x16x32_bf16 v[84:87], v[178:181], v[224:227], v[84:87]
	v_mfma_f32_16x16x32_bf16 v[76:79], v[162:165], v[232:235], v[76:79]
	v_mfma_f32_16x16x32_bf16 v[68:71], v[178:181], v[232:235], v[68:71]
	s_setprio 0
	s_setprio 1
	v_mfma_f32_16x16x32_bf16 v[124:127], v[184:187], v[204:207], 0
	v_mfma_f32_16x16x32_bf16 v[120:123], v[196:199], v[204:207], 0
	v_mfma_f32_16x16x32_bf16 v[116:119], v[184:187], v[212:215], 0
	v_mfma_f32_16x16x32_bf16 v[96:99], v[196:199], v[212:215], 0
	v_mfma_f32_16x16x32_bf16 v[88:91], v[184:187], v[220:223], 0
	v_mfma_f32_16x16x32_bf16 v[80:83], v[196:199], v[220:223], 0
	v_mfma_f32_16x16x32_bf16 v[72:75], v[184:187], v[228:231], 0
	v_mfma_f32_16x16x32_bf16 v[64:67], v[196:199], v[228:231], 0
	v_mfma_f32_16x16x32_bf16 v[124:127], v[188:191], v[208:211], v[124:127]
	v_mfma_f32_16x16x32_bf16 v[120:123], v[200:203], v[208:211], v[120:123]
	v_mfma_f32_16x16x32_bf16 v[116:119], v[188:191], v[216:219], v[116:119]
	v_mfma_f32_16x16x32_bf16 v[96:99], v[200:203], v[216:219], v[96:99]
	v_mfma_f32_16x16x32_bf16 v[88:91], v[188:191], v[224:227], v[88:91]
	v_mfma_f32_16x16x32_bf16 v[80:83], v[200:203], v[224:227], v[80:83]
	v_mfma_f32_16x16x32_bf16 v[72:75], v[188:191], v[232:235], v[72:75]
	v_mfma_f32_16x16x32_bf16 v[64:67], v[200:203], v[232:235], v[64:67]
	s_setprio 0
	s_barrier
	s_add_i32 s55, s46, s34
	v_lshl_add_u64 v[156:157], s[2:3], 0, v[142:143]
	s_mov_b32 m0, s55
	ds_read_b128 v[204:207], v159 offset:16384
	ds_read_b128 v[208:211], v159 offset:17408
	ds_read_b128 v[212:215], v159 offset:18432
	ds_read_b128 v[216:219], v159 offset:19456
	ds_read_b128 v[220:223], v159 offset:20480
	ds_read_b128 v[224:227], v159 offset:21504
	ds_read_b128 v[228:231], v159 offset:22528
	ds_read_b128 v[232:235], v159 offset:23552
	global_load_lds_dwordx4 v[156:157], off
	s_add_i32 m0, s55, 0x2000
	s_add_u32 s56, s2, 0x40000
	v_lshl_add_u64 v[192:193], s[2:3], 0, v[146:147]
	s_addc_u32 s57, s3, 0
	s_add_i32 s55, s47, s34
	global_load_lds_dwordx4 v[192:193], off
	v_lshl_add_u64 v[236:237], s[56:57], 0, v[142:143]
	s_mov_b32 m0, s55
	v_lshl_add_u64 v[238:239], s[22:23], 0, v[144:145]
	global_load_lds_dwordx4 v[236:237], off
	v_lshl_add_u64 v[236:237], s[56:57], 0, v[146:147]
	s_add_i32 m0, s55, 0x2000
	s_nop 0
	global_load_lds_dwordx4 v[236:237], off
	v_lshl_add_u64 v[236:237], s[22:23], 0, v[140:141]
	s_mov_b32 m0, s37
	s_nop 0
	global_load_lds_dwordx4 v[236:237], off
	s_mov_b32 m0, s38
	s_nop 0
	global_load_lds_dwordx4 v[238:239], off
	s_waitcnt vmcnt(8)
	s_waitcnt lgkmcnt(0)
	s_barrier
	s_setprio 1
	s_waitcnt lgkmcnt(0)
	v_mfma_f32_16x16x32_bf16 v[60:63], v[136:139], v[204:207], 0
	v_mfma_f32_16x16x32_bf16 v[52:55], v[166:169], v[204:207], 0
	v_mfma_f32_16x16x32_bf16 v[44:47], v[136:139], v[212:215], 0
	v_mfma_f32_16x16x32_bf16 v[36:39], v[166:169], v[212:215], 0
	v_mfma_f32_16x16x32_bf16 v[28:31], v[136:139], v[220:223], 0
	v_mfma_f32_16x16x32_bf16 v[20:23], v[166:169], v[220:223], 0
	v_mfma_f32_16x16x32_bf16 v[12:15], v[136:139], v[228:231], 0
	v_mfma_f32_16x16x32_bf16 v[4:7], v[166:169], v[228:231], 0
	v_mfma_f32_16x16x32_bf16 v[60:63], v[162:165], v[208:211], v[60:63]
	v_mfma_f32_16x16x32_bf16 v[52:55], v[178:181], v[208:211], v[52:55]
	v_mfma_f32_16x16x32_bf16 v[44:47], v[162:165], v[216:219], v[44:47]
	v_mfma_f32_16x16x32_bf16 v[36:39], v[178:181], v[216:219], v[36:39]
	v_mfma_f32_16x16x32_bf16 v[28:31], v[162:165], v[224:227], v[28:31]
	v_mfma_f32_16x16x32_bf16 v[20:23], v[178:181], v[224:227], v[20:23]
	v_mfma_f32_16x16x32_bf16 v[12:15], v[162:165], v[232:235], v[12:15]
	v_mfma_f32_16x16x32_bf16 v[4:7], v[178:181], v[232:235], v[4:7]
	s_setprio 0
	s_setprio 1
	v_mfma_f32_16x16x32_bf16 v[56:59], v[184:187], v[204:207], 0
	v_mfma_f32_16x16x32_bf16 v[48:51], v[196:199], v[204:207], 0
	v_mfma_f32_16x16x32_bf16 v[40:43], v[184:187], v[212:215], 0
	v_mfma_f32_16x16x32_bf16 v[32:35], v[196:199], v[212:215], 0
	v_mfma_f32_16x16x32_bf16 v[24:27], v[184:187], v[220:223], 0
	v_mfma_f32_16x16x32_bf16 v[16:19], v[196:199], v[220:223], 0
	v_mfma_f32_16x16x32_bf16 v[8:11], v[184:187], v[228:231], 0
	v_mfma_f32_16x16x32_bf16 v[0:3], v[196:199], v[228:231], 0
	v_mfma_f32_16x16x32_bf16 v[56:59], v[188:191], v[208:211], v[56:59]
	v_mfma_f32_16x16x32_bf16 v[48:51], v[200:203], v[208:211], v[48:51]
	v_mfma_f32_16x16x32_bf16 v[40:43], v[188:191], v[216:219], v[40:43]
	v_mfma_f32_16x16x32_bf16 v[32:35], v[200:203], v[216:219], v[32:35]
	v_mfma_f32_16x16x32_bf16 v[24:27], v[188:191], v[224:227], v[24:27]
	v_mfma_f32_16x16x32_bf16 v[16:19], v[200:203], v[224:227], v[16:19]
	v_mfma_f32_16x16x32_bf16 v[8:11], v[188:191], v[232:235], v[8:11]
	v_mfma_f32_16x16x32_bf16 v[0:3], v[200:203], v[232:235], v[0:3]
	s_setprio 0
	s_barrier
	s_add_i32 s55, 0, 0x18000
	v_add_u32_e32 v161, s55, v151
	s_add_i32 s56, 0, 0x1c000
	ds_read_b128 v[136:139], v161
	ds_read_b128 v[162:165], v161 offset:1024
	ds_read_b128 v[166:169], v161 offset:2048
	ds_read_b128 v[178:181], v161 offset:3072
	v_add_u32_e32 v161, s56, v151
	ds_read_b128 v[184:187], v161
	ds_read_b128 v[188:191], v161 offset:1024
	ds_read_b128 v[196:199], v161 offset:2048
	ds_read_b128 v[200:203], v161 offset:3072
	s_add_u32 s22, s22, 0x40000
	s_addc_u32 s23, s23, 0
	s_mov_b32 m0, s39
	v_lshl_add_u64 v[240:241], s[22:23], 0, v[140:141]
	ds_read_b128 v[204:207], v159 offset:32768
	ds_read_b128 v[208:211], v159 offset:33792
	ds_read_b128 v[212:215], v159 offset:34816
	ds_read_b128 v[216:219], v159 offset:35840
	ds_read_b128 v[220:223], v159 offset:36864
	ds_read_b128 v[224:227], v159 offset:37888
	ds_read_b128 v[228:231], v159 offset:38912
	ds_read_b128 v[232:235], v159 offset:39936
	global_load_lds_dwordx4 v[240:241], off
	v_lshl_add_u64 v[240:241], s[22:23], 0, v[144:145]
	s_mov_b32 m0, s40
	s_nop 0
	global_load_lds_dwordx4 v[240:241], off
	s_waitcnt vmcnt(8)
	s_waitcnt lgkmcnt(0)
	s_barrier
	s_setprio 1
	s_waitcnt lgkmcnt(0)
	v_mfma_f32_16x16x32_bf16 v[112:115], v[136:139], v[204:207], v[112:115]
	v_mfma_f32_16x16x32_bf16 v[108:111], v[166:169], v[204:207], v[108:111]
	v_mfma_f32_16x16x32_bf16 v[104:107], v[136:139], v[212:215], v[104:107]
	v_mfma_f32_16x16x32_bf16 v[100:103], v[166:169], v[212:215], v[100:103]
	v_mfma_f32_16x16x32_bf16 v[92:95], v[136:139], v[220:223], v[92:95]
	v_mfma_f32_16x16x32_bf16 v[84:87], v[166:169], v[220:223], v[84:87]
	v_mfma_f32_16x16x32_bf16 v[76:79], v[136:139], v[228:231], v[76:79]
	v_mfma_f32_16x16x32_bf16 v[68:71], v[166:169], v[228:231], v[68:71]
	v_mfma_f32_16x16x32_bf16 v[112:115], v[162:165], v[208:211], v[112:115]
	v_mfma_f32_16x16x32_bf16 v[108:111], v[178:181], v[208:211], v[108:111]
	v_mfma_f32_16x16x32_bf16 v[104:107], v[162:165], v[216:219], v[104:107]
	v_mfma_f32_16x16x32_bf16 v[100:103], v[178:181], v[216:219], v[100:103]
	v_mfma_f32_16x16x32_bf16 v[92:95], v[162:165], v[224:227], v[92:95]
	v_mfma_f32_16x16x32_bf16 v[84:87], v[178:181], v[224:227], v[84:87]
	v_mfma_f32_16x16x32_bf16 v[76:79], v[162:165], v[232:235], v[76:79]
	v_mfma_f32_16x16x32_bf16 v[68:71], v[178:181], v[232:235], v[68:71]
	s_setprio 0
	s_setprio 1
	v_mfma_f32_16x16x32_bf16 v[124:127], v[184:187], v[204:207], v[124:127]
	v_mfma_f32_16x16x32_bf16 v[120:123], v[196:199], v[204:207], v[120:123]
	v_mfma_f32_16x16x32_bf16 v[116:119], v[184:187], v[212:215], v[116:119]
	v_mfma_f32_16x16x32_bf16 v[96:99], v[196:199], v[212:215], v[96:99]
	v_mfma_f32_16x16x32_bf16 v[88:91], v[184:187], v[220:223], v[88:91]
	v_mfma_f32_16x16x32_bf16 v[80:83], v[196:199], v[220:223], v[80:83]
	v_mfma_f32_16x16x32_bf16 v[72:75], v[184:187], v[228:231], v[72:75]
	v_mfma_f32_16x16x32_bf16 v[64:67], v[196:199], v[228:231], v[64:67]
	v_mfma_f32_16x16x32_bf16 v[124:127], v[188:191], v[208:211], v[124:127]
	v_mfma_f32_16x16x32_bf16 v[120:123], v[200:203], v[208:211], v[120:123]
	v_mfma_f32_16x16x32_bf16 v[116:119], v[188:191], v[216:219], v[116:119]
	v_mfma_f32_16x16x32_bf16 v[96:99], v[200:203], v[216:219], v[96:99]
	v_mfma_f32_16x16x32_bf16 v[88:91], v[188:191], v[224:227], v[88:91]
	v_mfma_f32_16x16x32_bf16 v[80:83], v[200:203], v[224:227], v[80:83]
	v_mfma_f32_16x16x32_bf16 v[72:75], v[188:191], v[232:235], v[72:75]
	v_mfma_f32_16x16x32_bf16 v[64:67], v[200:203], v[232:235], v[64:67]
	s_setprio 0
	s_barrier
	s_add_i32 s22, s55, s34
	v_lshl_add_u64 v[156:157], v[156:157], 0, s[12:13]
	s_mov_b32 m0, s22
	ds_read_b128 v[204:207], v159 offset:49152
	ds_read_b128 v[208:211], v159 offset:50176
	ds_read_b128 v[212:215], v159 offset:51200
	ds_read_b128 v[216:219], v159 offset:52224
	ds_read_b128 v[220:223], v159 offset:53248
	ds_read_b128 v[224:227], v159 offset:54272
	ds_read_b128 v[228:231], v159 offset:55296
	ds_read_b128 v[232:235], v159 offset:56320
	global_load_lds_dwordx4 v[156:157], off
	s_add_i32 m0, s22, 0x2000
	s_add_u32 s2, s2, 0x40080
	v_lshl_add_u64 v[156:157], v[192:193], 0, s[12:13]
	s_addc_u32 s3, s3, 0
	s_add_i32 s22, s56, s34
	global_load_lds_dwordx4 v[156:157], off
	v_lshl_add_u64 v[156:157], s[2:3], 0, v[142:143]
	s_mov_b32 m0, s22
	s_nop 0
	global_load_lds_dwordx4 v[156:157], off
	v_lshl_add_u64 v[156:157], s[2:3], 0, v[146:147]
	s_add_i32 m0, s22, 0x2000
	s_nop 0
	global_load_lds_dwordx4 v[156:157], off
	v_lshl_add_u64 v[156:157], v[236:237], 0, s[12:13]
	s_mov_b32 m0, s42
	s_nop 0
	global_load_lds_dwordx4 v[156:157], off
	v_lshl_add_u64 v[156:157], v[238:239], 0, s[12:13]
	s_mov_b32 m0, s43
	s_nop 0
	global_load_lds_dwordx4 v[156:157], off
	s_waitcnt vmcnt(8)
	s_waitcnt lgkmcnt(0)
	s_barrier
	s_setprio 1
	s_waitcnt lgkmcnt(0)
	v_mfma_f32_16x16x32_bf16 v[60:63], v[136:139], v[204:207], v[60:63]
	v_mfma_f32_16x16x32_bf16 v[52:55], v[166:169], v[204:207], v[52:55]
	v_mfma_f32_16x16x32_bf16 v[44:47], v[136:139], v[212:215], v[44:47]
	v_mfma_f32_16x16x32_bf16 v[36:39], v[166:169], v[212:215], v[36:39]
	v_mfma_f32_16x16x32_bf16 v[28:31], v[136:139], v[220:223], v[28:31]
	v_mfma_f32_16x16x32_bf16 v[20:23], v[166:169], v[220:223], v[20:23]
	v_mfma_f32_16x16x32_bf16 v[12:15], v[136:139], v[228:231], v[12:15]
	v_mfma_f32_16x16x32_bf16 v[4:7], v[166:169], v[228:231], v[4:7]
	v_mfma_f32_16x16x32_bf16 v[60:63], v[162:165], v[208:211], v[60:63]
	v_mfma_f32_16x16x32_bf16 v[52:55], v[178:181], v[208:211], v[52:55]
	v_mfma_f32_16x16x32_bf16 v[44:47], v[162:165], v[216:219], v[44:47]
	v_mfma_f32_16x16x32_bf16 v[36:39], v[178:181], v[216:219], v[36:39]
	v_mfma_f32_16x16x32_bf16 v[28:31], v[162:165], v[224:227], v[28:31]
	v_mfma_f32_16x16x32_bf16 v[20:23], v[178:181], v[224:227], v[20:23]
	v_mfma_f32_16x16x32_bf16 v[12:15], v[162:165], v[232:235], v[12:15]
	v_mfma_f32_16x16x32_bf16 v[4:7], v[178:181], v[232:235], v[4:7]
	s_setprio 0
	s_setprio 1
	v_mfma_f32_16x16x32_bf16 v[56:59], v[184:187], v[204:207], v[56:59]
	v_mfma_f32_16x16x32_bf16 v[48:51], v[196:199], v[204:207], v[48:51]
	v_mfma_f32_16x16x32_bf16 v[40:43], v[184:187], v[212:215], v[40:43]
	v_mfma_f32_16x16x32_bf16 v[32:35], v[196:199], v[212:215], v[32:35]
	v_mfma_f32_16x16x32_bf16 v[24:27], v[184:187], v[220:223], v[24:27]
	v_mfma_f32_16x16x32_bf16 v[16:19], v[196:199], v[220:223], v[16:19]
	v_mfma_f32_16x16x32_bf16 v[8:11], v[184:187], v[228:231], v[8:11]
	v_mfma_f32_16x16x32_bf16 v[0:3], v[196:199], v[228:231], v[0:3]
	v_mfma_f32_16x16x32_bf16 v[56:59], v[188:191], v[208:211], v[56:59]
	v_mfma_f32_16x16x32_bf16 v[48:51], v[200:203], v[208:211], v[48:51]
	v_mfma_f32_16x16x32_bf16 v[40:43], v[188:191], v[216:219], v[40:43]
	v_mfma_f32_16x16x32_bf16 v[32:35], v[200:203], v[216:219], v[32:35]
	v_mfma_f32_16x16x32_bf16 v[24:27], v[188:191], v[224:227], v[24:27]
	v_mfma_f32_16x16x32_bf16 v[16:19], v[200:203], v[224:227], v[16:19]
	v_mfma_f32_16x16x32_bf16 v[8:11], v[188:191], v[232:235], v[8:11]
	v_mfma_f32_16x16x32_bf16 v[0:3], v[200:203], v[232:235], v[0:3]
	s_setprio 0
	s_barrier
	s_add_i32 s54, s54, 2
	s_add_u32 s14, s14, 0x100
	s_addc_u32 s15, s15, 0
	s_add_u32 s52, s52, 0x100
	s_addc_u32 s53, s53, 0
	s_cmp_gt_u32 s54, 13
	s_cbranch_scc1 .Lgemm_kdone_5

.LBB0_812:
	v_lshl_add_u32 v136, s0, 8, v149
	v_ashrrev_i32_e32 v137, 31, v136
	v_lshl_add_u64 v[164:165], v[136:137], 3, s[10:11]
	v_or_b32_e32 v138, 16, v136
	global_load_dwordx2 v[166:167], v[164:165], off
	v_ashrrev_i32_e32 v139, 31, v138
	v_lshl_add_u64 v[156:157], v[138:139], 3, s[10:11]
	global_load_dwordx2 v[168:169], v[156:157], off
	v_lshl_or_b32 v178, s1, 7, v153
	v_pk_mul_f32 v[180:181], v[114:115], v[126:127]
	v_or_b32_e32 v156, 32, v136
	v_or_b32_e32 v126, 48, v136
	v_ashrrev_i32_e32 v179, 31, v178
	v_ashrrev_i32_e32 v157, 31, v156
	v_ashrrev_i32_e32 v127, 31, v126
	v_pk_mul_f32 v[188:189], v[108:109], v[120:121]
	v_mov_b64_e32 v[120:121], s[16:17]
	v_pk_mul_f32 v[190:191], v[106:107], v[118:119]
	v_pk_mul_f32 v[192:193], v[104:105], v[116:117]
	v_lshlrev_b64 v[116:117], 1, v[178:179]
	v_lshl_add_u64 v[118:119], v[156:157], 3, s[10:11]
	v_lshl_add_u64 v[178:179], v[126:127], 3, s[10:11]
	v_pk_mul_f32 v[184:185], v[112:113], v[124:125]
	v_pk_mul_f32 v[186:187], v[110:111], v[122:123]
	v_add_u32_e32 v163, 0x80, v136
	v_add_u32_e32 v162, 0x90, v136
	v_add_u32_e32 v161, 0xa0, v136
	v_add_u32_e32 v139, 0xb0, v136
	v_mad_i64_i32 v[196:197], s[0:1], v136, s49, v[120:121]
	global_load_dwordx2 v[136:137], v[164:165], off offset:1024
	global_load_dwordx2 v[124:125], v[164:165], off offset:1152
	global_load_dwordx2 v[122:123], v[164:165], off offset:1280
	global_load_dwordx2 v[198:199], v[118:119], off
	s_nop 0
	global_load_dwordx2 v[178:179], v[178:179], off
	s_nop 0
	global_load_dwordx2 v[118:119], v[164:165], off offset:1408
	v_pk_mul_f32 v[96:97], v[100:101], v[96:97]
	v_pk_mul_f32 v[98:99], v[102:103], v[98:99]
	v_pk_mul_f32 v[88:89], v[92:93], v[88:89]
	v_pk_mul_f32 v[90:91], v[94:95], v[90:91]
	v_pk_mul_f32 v[80:81], v[84:85], v[80:81]
	v_pk_mul_f32 v[82:83], v[86:87], v[82:83]
	v_pk_mul_f32 v[72:73], v[76:77], v[72:73]
	v_pk_mul_f32 v[74:75], v[78:79], v[74:75]
	v_pk_mul_f32 v[64:65], v[68:69], v[64:65]
	v_pk_mul_f32 v[66:67], v[70:71], v[66:67]
	v_pk_mul_f32 v[56:57], v[60:61], v[56:57]
	v_pk_mul_f32 v[58:59], v[62:63], v[58:59]
	v_pk_mul_f32 v[48:49], v[52:53], v[48:49]
	v_pk_mul_f32 v[50:51], v[54:55], v[50:51]
	v_pk_mul_f32 v[40:41], v[44:45], v[40:41]
	v_pk_mul_f32 v[42:43], v[46:47], v[42:43]
	v_pk_mul_f32 v[32:33], v[36:37], v[32:33]
	v_pk_mul_f32 v[34:35], v[38:39], v[34:35]
	v_pk_mul_f32 v[24:25], v[28:29], v[24:25]
	v_pk_mul_f32 v[26:27], v[30:31], v[26:27]
	v_pk_mul_f32 v[16:17], v[20:21], v[16:17]
	v_pk_mul_f32 v[18:19], v[22:23], v[18:19]
	v_pk_mul_f32 v[8:9], v[12:13], v[8:9]
	v_pk_mul_f32 v[10:11], v[14:15], v[10:11]
	v_pk_mul_f32 v[0:1], v[4:5], v[0:1]
	v_pk_mul_f32 v[2:3], v[6:7], v[2:3]
	s_waitcnt vmcnt(0)
	v_ffbh_u32_e32 v127, v167
	v_min_u32_e32 v127, 32, v127
	v_lshlrev_b64 v[164:165], v127, v[166:167]
	v_ffbh_u32_e32 v157, v169
	v_min_u32_e32 v157, 32, v157
	v_min_u32_e32 v164, 1, v164
	v_lshlrev_b64 v[166:167], v157, v[168:169]
	v_or_b32_e32 v164, v165, v164
	v_min_u32_e32 v165, 1, v166
	v_cvt_f32_u32_e32 v164, v164
	v_or_b32_e32 v165, v167, v165
	v_cvt_f32_u32_e32 v165, v165
	v_sub_u32_e32 v127, 32, v127
	v_ldexp_f32 v127, v164, v127
	v_sub_u32_e32 v157, 32, v157
	v_fmamk_f32 v127, v127, 0x30800000, v160
	v_ldexp_f32 v157, v165, v157
	v_fmamk_f32 v157, v157, 0x30800000, v160
	v_rsq_f32_e32 v127, v127
	v_rsq_f32_e32 v157, v157
	v_lshl_add_u64 v[164:165], v[196:197], 0, v[116:117]
	v_mul_f32_e32 v166, 0xbfb8aa3b, v127
	v_pk_mul_f32 v[112:113], v[112:113], v[166:167] op_sel_hi:[1,0]
	v_pk_mul_f32 v[114:115], v[114:115], v[166:167] op_sel_hi:[1,0]
	v_pk_mul_f32 v[108:109], v[108:109], v[166:167] op_sel_hi:[1,0]
	v_pk_mul_f32 v[110:111], v[110:111], v[166:167] op_sel_hi:[1,0]
	v_exp_f32_e32 v112, v112
	v_exp_f32_e32 v113, v113
	v_exp_f32_e32 v114, v114
	v_exp_f32_e32 v115, v115
	v_exp_f32_e32 v108, v108
	v_exp_f32_e32 v109, v109
	v_exp_f32_e32 v110, v110
	v_exp_f32_e32 v111, v111
	v_mul_f32_e32 v168, v127, v127
	v_mov_b32_e32 v127, v157
	v_mul_f32_e32 v166, 0xbfb8aa3b, v127
	v_pk_mul_f32 v[104:105], v[104:105], v[166:167] op_sel_hi:[1,0]
	v_pk_mul_f32 v[106:107], v[106:107], v[166:167] op_sel_hi:[1,0]
	v_exp_f32_e32 v104, v104
	v_exp_f32_e32 v105, v105
	v_exp_f32_e32 v200, v106
	v_exp_f32_e32 v201, v107
	v_pk_add_f32 v[106:107], v[112:113], 1.0 op_sel_hi:[1,0]
	v_pk_add_f32 v[112:113], v[114:115], 1.0 op_sel_hi:[1,0]
	v_pk_add_f32 v[108:109], v[108:109], 1.0 op_sel_hi:[1,0]
	v_pk_add_f32 v[110:111], v[110:111], 1.0 op_sel_hi:[1,0]
	v_rcp_f32_e32 v106, v106
	v_rcp_f32_e32 v107, v107
	v_rcp_f32_e32 v112, v112
	v_rcp_f32_e32 v113, v113
	v_rcp_f32_e32 v108, v108
	v_rcp_f32_e32 v109, v109
	v_rcp_f32_e32 v110, v110
	v_rcp_f32_e32 v111, v111
	v_pk_add_f32 v[104:105], v[104:105], 1.0 op_sel_hi:[1,0]
	v_pk_mul_f32 v[108:109], v[168:169], v[108:109] op_sel_hi:[0,1]
	v_rcp_f32_e32 v114, v104
	v_rcp_f32_e32 v115, v105
	v_pk_mul_f32 v[104:105], v[168:169], v[106:107] op_sel_hi:[0,1]
	v_pk_mul_f32 v[106:107], v[168:169], v[112:113] op_sel_hi:[0,1]
	v_pk_mul_f32 v[110:111], v[168:169], v[110:111] op_sel_hi:[0,1]
	v_pk_mul_f32 v[104:105], v[184:185], v[104:105]
	v_pk_mul_f32 v[106:107], v[180:181], v[106:107]
	v_pk_mul_f32 v[108:109], v[188:189], v[108:109]
	v_pk_mul_f32 v[110:111], v[186:187], v[110:111]
	v_cvt_pk_bf16_f32 v104, v104, v105
	v_cvt_pk_bf16_f32 v105, v106, v107
	v_cvt_pk_bf16_f32 v106, v108, v109
	v_cvt_pk_bf16_f32 v107, v110, v111
	global_store_dwordx4 v[164:165], v[104:107], off
	v_pk_mul_f32 v[108:109], v[100:101], v[166:167] op_sel_hi:[1,0]
	v_mul_f32_e32 v196, v127, v127
	v_pk_add_f32 v[106:107], v[200:201], 1.0 op_sel_hi:[1,0]
	v_exp_f32_e32 v108, v108
	v_rcp_f32_e32 v106, v106
	v_rcp_f32_e32 v107, v107
	v_exp_f32_e32 v109, v109
	v_pk_mul_f32 v[104:105], v[196:197], v[114:115] op_sel_hi:[0,1]
	v_pk_mul_f32 v[104:105], v[192:193], v[104:105]
	v_pk_mul_f32 v[106:107], v[196:197], v[106:107] op_sel_hi:[0,1]
	v_pk_mul_f32 v[106:107], v[190:191], v[106:107]
	v_cvt_pk_bf16_f32 v104, v104, v105
	v_cvt_pk_bf16_f32 v105, v106, v107
	v_pk_add_f32 v[106:107], v[108:109], 1.0 op_sel_hi:[1,0]
	v_pk_mul_f32 v[100:101], v[102:103], v[166:167] op_sel_hi:[1,0]
	v_rcp_f32_e32 v106, v106
	v_rcp_f32_e32 v107, v107
	v_exp_f32_e32 v100, v100
	v_exp_f32_e32 v101, v101
	v_pk_mul_f32 v[102:103], v[196:197], v[106:107] op_sel_hi:[0,1]
	v_pk_mul_f32 v[96:97], v[96:97], v[102:103]
	s_nop 0
	v_cvt_pk_bf16_f32 v106, v96, v97
	v_pk_add_f32 v[96:97], v[100:101], 1.0 op_sel_hi:[1,0]
	v_ffbh_u32_e32 v100, v199
	v_min_u32_e32 v102, 32, v100
	v_lshlrev_b64 v[100:101], v102, v[198:199]
	v_rcp_f32_e32 v96, v96
	v_rcp_f32_e32 v97, v97
	v_min_u32_e32 v100, 1, v100
	v_or_b32_e32 v100, v101, v100
	v_cvt_f32_u32_e32 v100, v100
	v_pk_mul_f32 v[96:97], v[196:197], v[96:97] op_sel_hi:[0,1]
	v_pk_mul_f32 v[96:97], v[98:99], v[96:97]
	v_sub_u32_e32 v98, 32, v102
	v_ldexp_f32 v98, v100, v98
	v_fmamk_f32 v98, v98, 0x30800000, v160
	v_cvt_pk_bf16_f32 v107, v96, v97
	v_mad_i64_i32 v[96:97], s[0:1], v138, s49, v[120:121]
	v_rsq_f32_e32 v98, v98
	v_lshl_add_u64 v[96:97], v[96:97], 0, v[116:117]
	global_store_dwordx4 v[96:97], v[104:107], off
	v_mov_b32_e32 v99, v98
	v_mul_f32_e32 v98, 0xbfb8aa3b, v99
	v_pk_mul_f32 v[100:101], v[92:93], v[98:99] op_sel_hi:[1,0]
	v_pk_mul_f32 v[92:93], v[94:95], v[98:99] op_sel_hi:[1,0]
	v_exp_f32_e32 v100, v100
	v_exp_f32_e32 v101, v101
	v_exp_f32_e32 v92, v92
	v_exp_f32_e32 v93, v93
	v_mul_f32_e32 v96, v99, v99
	v_pk_add_f32 v[100:101], v[100:101], 1.0 op_sel_hi:[1,0]
	v_pk_add_f32 v[92:93], v[92:93], 1.0 op_sel_hi:[1,0]
	v_rcp_f32_e32 v100, v100
	v_rcp_f32_e32 v101, v101
	v_rcp_f32_e32 v92, v92
	v_rcp_f32_e32 v93, v93
	v_pk_mul_f32 v[94:95], v[96:97], v[100:101] op_sel_hi:[0,1]
	v_pk_mul_f32 v[88:89], v[88:89], v[94:95]
	v_pk_mul_f32 v[94:95], v[84:85], v[98:99] op_sel_hi:[1,0]
	v_pk_mul_f32 v[92:93], v[96:97], v[92:93] op_sel_hi:[0,1]
	v_exp_f32_e32 v94, v94
	v_exp_f32_e32 v95, v95
	v_pk_mul_f32 v[90:91], v[90:91], v[92:93]
	v_cvt_pk_bf16_f32 v88, v88, v89
	v_cvt_pk_bf16_f32 v89, v90, v91
	v_pk_add_f32 v[90:91], v[94:95], 1.0 op_sel_hi:[1,0]
	v_pk_mul_f32 v[84:85], v[86:87], v[98:99] op_sel_hi:[1,0]
	v_rcp_f32_e32 v90, v90
	v_rcp_f32_e32 v91, v91
	v_exp_f32_e32 v84, v84
	v_exp_f32_e32 v85, v85
	v_pk_mul_f32 v[86:87], v[96:97], v[90:91] op_sel_hi:[0,1]
	v_pk_mul_f32 v[80:81], v[80:81], v[86:87]
	s_nop 0
	v_cvt_pk_bf16_f32 v90, v80, v81
	v_pk_add_f32 v[80:81], v[84:85], 1.0 op_sel_hi:[1,0]
	v_ffbh_u32_e32 v84, v179
	v_min_u32_e32 v86, 32, v84
	v_lshlrev_b64 v[84:85], v86, v[178:179]
	v_rcp_f32_e32 v80, v80
	v_rcp_f32_e32 v81, v81
	v_min_u32_e32 v84, 1, v84
	v_or_b32_e32 v84, v85, v84
	v_cvt_f32_u32_e32 v84, v84
	v_pk_mul_f32 v[80:81], v[96:97], v[80:81] op_sel_hi:[0,1]
	v_pk_mul_f32 v[80:81], v[82:83], v[80:81]
	v_sub_u32_e32 v82, 32, v86
	v_ldexp_f32 v82, v84, v82
	v_fmamk_f32 v82, v82, 0x30800000, v160
	v_cvt_pk_bf16_f32 v91, v80, v81
	v_mad_i64_i32 v[80:81], s[0:1], v156, s49, v[120:121]
	v_rsq_f32_e32 v82, v82
	v_lshl_add_u64 v[80:81], v[80:81], 0, v[116:117]
	global_store_dwordx4 v[80:81], v[88:91], off
	v_mov_b32_e32 v83, v82
	v_mul_f32_e32 v82, 0xbfb8aa3b, v83
	v_pk_mul_f32 v[84:85], v[76:77], v[82:83] op_sel_hi:[1,0]
	v_pk_mul_f32 v[76:77], v[78:79], v[82:83] op_sel_hi:[1,0]
	v_exp_f32_e32 v84, v84
	v_exp_f32_e32 v85, v85
	v_exp_f32_e32 v76, v76
	v_exp_f32_e32 v77, v77
	v_mul_f32_e32 v80, v83, v83
	v_pk_add_f32 v[84:85], v[84:85], 1.0 op_sel_hi:[1,0]
	v_pk_add_f32 v[76:77], v[76:77], 1.0 op_sel_hi:[1,0]
	v_rcp_f32_e32 v84, v84
	v_rcp_f32_e32 v85, v85
	v_rcp_f32_e32 v76, v76
	v_rcp_f32_e32 v77, v77
	v_pk_mul_f32 v[78:79], v[80:81], v[84:85] op_sel_hi:[0,1]
	v_pk_mul_f32 v[72:73], v[72:73], v[78:79]
	v_pk_mul_f32 v[78:79], v[68:69], v[82:83] op_sel_hi:[1,0]
	v_pk_mul_f32 v[76:77], v[80:81], v[76:77] op_sel_hi:[0,1]
	v_exp_f32_e32 v78, v78
	v_exp_f32_e32 v79, v79
	v_pk_mul_f32 v[74:75], v[74:75], v[76:77]
	v_cvt_pk_bf16_f32 v72, v72, v73
	v_cvt_pk_bf16_f32 v73, v74, v75
	v_pk_add_f32 v[74:75], v[78:79], 1.0 op_sel_hi:[1,0]
	v_pk_mul_f32 v[68:69], v[70:71], v[82:83] op_sel_hi:[1,0]
	v_rcp_f32_e32 v74, v74
	v_rcp_f32_e32 v75, v75
	v_exp_f32_e32 v68, v68
	v_exp_f32_e32 v69, v69
	v_pk_mul_f32 v[70:71], v[80:81], v[74:75] op_sel_hi:[0,1]
	v_pk_mul_f32 v[64:65], v[64:65], v[70:71]
	s_nop 0
	v_cvt_pk_bf16_f32 v74, v64, v65
	v_pk_add_f32 v[64:65], v[68:69], 1.0 op_sel_hi:[1,0]
	v_ffbh_u32_e32 v68, v137
	v_min_u32_e32 v70, 32, v68
	v_lshlrev_b64 v[68:69], v70, v[136:137]
	v_rcp_f32_e32 v64, v64
	v_rcp_f32_e32 v65, v65
	v_min_u32_e32 v68, 1, v68
	v_or_b32_e32 v68, v69, v68
	v_cvt_f32_u32_e32 v68, v68
	v_pk_mul_f32 v[64:65], v[80:81], v[64:65] op_sel_hi:[0,1]
	v_pk_mul_f32 v[64:65], v[66:67], v[64:65]
	v_sub_u32_e32 v66, 32, v70
	v_ldexp_f32 v66, v68, v66
	v_fmamk_f32 v66, v66, 0x30800000, v160
	v_cvt_pk_bf16_f32 v75, v64, v65
	v_mad_i64_i32 v[64:65], s[0:1], v126, s49, v[120:121]
	v_rsq_f32_e32 v66, v66
	v_lshl_add_u64 v[64:65], v[64:65], 0, v[116:117]
	global_store_dwordx4 v[64:65], v[72:75], off
	v_mov_b32_e32 v67, v66
	v_mul_f32_e32 v66, 0xbfb8aa3b, v67
	v_pk_mul_f32 v[68:69], v[60:61], v[66:67] op_sel_hi:[1,0]
	v_pk_mul_f32 v[60:61], v[62:63], v[66:67] op_sel_hi:[1,0]
	v_exp_f32_e32 v68, v68
	v_exp_f32_e32 v69, v69
	v_exp_f32_e32 v60, v60
	v_exp_f32_e32 v61, v61
	v_mul_f32_e32 v64, v67, v67
	v_pk_add_f32 v[68:69], v[68:69], 1.0 op_sel_hi:[1,0]
	v_pk_add_f32 v[60:61], v[60:61], 1.0 op_sel_hi:[1,0]
	v_rcp_f32_e32 v68, v68
	v_rcp_f32_e32 v69, v69
	v_rcp_f32_e32 v60, v60
	v_rcp_f32_e32 v61, v61
	v_pk_mul_f32 v[62:63], v[64:65], v[68:69] op_sel_hi:[0,1]
	v_pk_mul_f32 v[56:57], v[56:57], v[62:63]
	v_pk_mul_f32 v[62:63], v[52:53], v[66:67] op_sel_hi:[1,0]
	v_pk_mul_f32 v[60:61], v[64:65], v[60:61] op_sel_hi:[0,1]
	v_exp_f32_e32 v62, v62
	v_exp_f32_e32 v63, v63
	v_pk_mul_f32 v[58:59], v[58:59], v[60:61]
	v_cvt_pk_bf16_f32 v56, v56, v57
	v_cvt_pk_bf16_f32 v57, v58, v59
	v_pk_add_f32 v[58:59], v[62:63], 1.0 op_sel_hi:[1,0]
	v_pk_mul_f32 v[52:53], v[54:55], v[66:67] op_sel_hi:[1,0]
	v_rcp_f32_e32 v58, v58
	v_rcp_f32_e32 v59, v59
	v_exp_f32_e32 v52, v52
	v_exp_f32_e32 v53, v53
	v_pk_mul_f32 v[54:55], v[64:65], v[58:59] op_sel_hi:[0,1]
	v_pk_mul_f32 v[48:49], v[48:49], v[54:55]
	s_nop 0
	v_cvt_pk_bf16_f32 v58, v48, v49
	v_pk_add_f32 v[48:49], v[52:53], 1.0 op_sel_hi:[1,0]
	v_ffbh_u32_e32 v52, v125
	v_min_u32_e32 v54, 32, v52
	v_lshlrev_b64 v[52:53], v54, v[124:125]
	v_rcp_f32_e32 v48, v48
	v_rcp_f32_e32 v49, v49
	v_min_u32_e32 v52, 1, v52
	v_or_b32_e32 v52, v53, v52
	v_cvt_f32_u32_e32 v52, v52
	v_pk_mul_f32 v[48:49], v[64:65], v[48:49] op_sel_hi:[0,1]
	v_pk_mul_f32 v[48:49], v[50:51], v[48:49]
	v_sub_u32_e32 v50, 32, v54
	v_ldexp_f32 v50, v52, v50
	v_fmamk_f32 v50, v50, 0x30800000, v160
	v_cvt_pk_bf16_f32 v59, v48, v49
	v_mad_i64_i32 v[48:49], s[0:1], v163, s49, v[120:121]
	v_rsq_f32_e32 v50, v50
	v_lshl_add_u64 v[48:49], v[48:49], 0, v[116:117]
	global_store_dwordx4 v[48:49], v[56:59], off
	v_mov_b32_e32 v51, v50
	v_mul_f32_e32 v50, 0xbfb8aa3b, v51
	v_pk_mul_f32 v[52:53], v[44:45], v[50:51] op_sel_hi:[1,0]
	v_pk_mul_f32 v[44:45], v[46:47], v[50:51] op_sel_hi:[1,0]
	v_exp_f32_e32 v52, v52
	v_exp_f32_e32 v53, v53
	v_exp_f32_e32 v44, v44
	v_exp_f32_e32 v45, v45
	v_mul_f32_e32 v48, v51, v51
	v_pk_add_f32 v[52:53], v[52:53], 1.0 op_sel_hi:[1,0]
	v_pk_add_f32 v[44:45], v[44:45], 1.0 op_sel_hi:[1,0]
	v_rcp_f32_e32 v52, v52
	v_rcp_f32_e32 v53, v53
	v_rcp_f32_e32 v44, v44
	v_rcp_f32_e32 v45, v45
	v_pk_mul_f32 v[46:47], v[48:49], v[52:53] op_sel_hi:[0,1]
	v_pk_mul_f32 v[40:41], v[40:41], v[46:47]
	v_pk_mul_f32 v[46:47], v[36:37], v[50:51] op_sel_hi:[1,0]
	v_pk_mul_f32 v[44:45], v[48:49], v[44:45] op_sel_hi:[0,1]
	v_exp_f32_e32 v46, v46
	v_exp_f32_e32 v47, v47
	v_pk_mul_f32 v[42:43], v[42:43], v[44:45]
	v_cvt_pk_bf16_f32 v40, v40, v41
	v_cvt_pk_bf16_f32 v41, v42, v43
	v_pk_add_f32 v[42:43], v[46:47], 1.0 op_sel_hi:[1,0]
	v_pk_mul_f32 v[36:37], v[38:39], v[50:51] op_sel_hi:[1,0]
	v_rcp_f32_e32 v42, v42
	v_rcp_f32_e32 v43, v43
	v_exp_f32_e32 v36, v36
	v_exp_f32_e32 v37, v37
	v_pk_mul_f32 v[38:39], v[48:49], v[42:43] op_sel_hi:[0,1]
	v_pk_mul_f32 v[32:33], v[32:33], v[38:39]
	s_nop 0
	v_cvt_pk_bf16_f32 v42, v32, v33
	v_pk_add_f32 v[32:33], v[36:37], 1.0 op_sel_hi:[1,0]
	v_ffbh_u32_e32 v36, v123
	v_min_u32_e32 v38, 32, v36
	v_lshlrev_b64 v[36:37], v38, v[122:123]
	v_rcp_f32_e32 v32, v32
	v_rcp_f32_e32 v33, v33
	v_min_u32_e32 v36, 1, v36
	v_or_b32_e32 v36, v37, v36
	v_cvt_f32_u32_e32 v36, v36
	v_pk_mul_f32 v[32:33], v[48:49], v[32:33] op_sel_hi:[0,1]
	v_pk_mul_f32 v[32:33], v[34:35], v[32:33]
	v_sub_u32_e32 v34, 32, v38
	v_ldexp_f32 v34, v36, v34
	v_fmamk_f32 v34, v34, 0x30800000, v160
	v_cvt_pk_bf16_f32 v43, v32, v33
	v_mad_i64_i32 v[32:33], s[0:1], v162, s49, v[120:121]
	v_rsq_f32_e32 v34, v34
	v_lshl_add_u64 v[32:33], v[32:33], 0, v[116:117]
	global_store_dwordx4 v[32:33], v[40:43], off
	v_mov_b32_e32 v35, v34
	v_mul_f32_e32 v34, 0xbfb8aa3b, v35
	v_pk_mul_f32 v[36:37], v[28:29], v[34:35] op_sel_hi:[1,0]
	v_pk_mul_f32 v[28:29], v[30:31], v[34:35] op_sel_hi:[1,0]
	v_exp_f32_e32 v36, v36
	v_exp_f32_e32 v37, v37
	v_exp_f32_e32 v28, v28
	v_exp_f32_e32 v29, v29
	v_mul_f32_e32 v32, v35, v35
	v_pk_add_f32 v[36:37], v[36:37], 1.0 op_sel_hi:[1,0]
	v_pk_add_f32 v[28:29], v[28:29], 1.0 op_sel_hi:[1,0]
	v_rcp_f32_e32 v36, v36
	v_rcp_f32_e32 v37, v37
	v_rcp_f32_e32 v28, v28
	v_rcp_f32_e32 v29, v29
	v_pk_mul_f32 v[30:31], v[32:33], v[36:37] op_sel_hi:[0,1]
	v_pk_mul_f32 v[24:25], v[24:25], v[30:31]
	v_pk_mul_f32 v[30:31], v[20:21], v[34:35] op_sel_hi:[1,0]
	v_pk_mul_f32 v[28:29], v[32:33], v[28:29] op_sel_hi:[0,1]
	v_exp_f32_e32 v30, v30
	v_exp_f32_e32 v31, v31
	v_pk_mul_f32 v[26:27], v[26:27], v[28:29]
	v_cvt_pk_bf16_f32 v24, v24, v25
	v_cvt_pk_bf16_f32 v25, v26, v27
	v_pk_add_f32 v[26:27], v[30:31], 1.0 op_sel_hi:[1,0]
	v_pk_mul_f32 v[20:21], v[22:23], v[34:35] op_sel_hi:[1,0]
	v_rcp_f32_e32 v26, v26
	v_rcp_f32_e32 v27, v27
	v_exp_f32_e32 v20, v20
	v_exp_f32_e32 v21, v21
	v_pk_mul_f32 v[22:23], v[32:33], v[26:27] op_sel_hi:[0,1]
	v_pk_mul_f32 v[16:17], v[16:17], v[22:23]
	s_nop 0
	v_cvt_pk_bf16_f32 v26, v16, v17
	v_pk_add_f32 v[16:17], v[20:21], 1.0 op_sel_hi:[1,0]
	v_ffbh_u32_e32 v20, v119
	v_min_u32_e32 v22, 32, v20
	v_lshlrev_b64 v[20:21], v22, v[118:119]
	v_rcp_f32_e32 v16, v16
	v_rcp_f32_e32 v17, v17
	v_min_u32_e32 v20, 1, v20
	v_or_b32_e32 v20, v21, v20
	v_cvt_f32_u32_e32 v20, v20
	v_pk_mul_f32 v[16:17], v[32:33], v[16:17] op_sel_hi:[0,1]
	v_pk_mul_f32 v[16:17], v[18:19], v[16:17]
	v_sub_u32_e32 v18, 32, v22
	v_ldexp_f32 v18, v20, v18
	v_fmamk_f32 v18, v18, 0x30800000, v160
	v_cvt_pk_bf16_f32 v27, v16, v17
	v_mad_i64_i32 v[16:17], s[0:1], v161, s49, v[120:121]
	v_rsq_f32_e32 v18, v18
	v_lshl_add_u64 v[16:17], v[16:17], 0, v[116:117]
	global_store_dwordx4 v[16:17], v[24:27], off
	v_mov_b32_e32 v19, v18
	v_mul_f32_e32 v18, 0xbfb8aa3b, v19
	v_pk_mul_f32 v[20:21], v[12:13], v[18:19] op_sel_hi:[1,0]
	v_pk_mul_f32 v[12:13], v[14:15], v[18:19] op_sel_hi:[1,0]
	v_exp_f32_e32 v20, v20
	v_exp_f32_e32 v21, v21
	v_exp_f32_e32 v12, v12
	v_exp_f32_e32 v13, v13
	v_mul_f32_e32 v16, v19, v19
	v_pk_add_f32 v[20:21], v[20:21], 1.0 op_sel_hi:[1,0]
	s_andn2_b64 vcc, exec, s[4:5]
	v_rcp_f32_e32 v20, v20
	v_rcp_f32_e32 v21, v21
	v_pk_add_f32 v[12:13], v[12:13], 1.0 op_sel_hi:[1,0]
	v_pk_mul_f32 v[14:15], v[16:17], v[20:21] op_sel_hi:[0,1]
	v_rcp_f32_e32 v12, v12
	v_rcp_f32_e32 v13, v13
	v_pk_mul_f32 v[8:9], v[8:9], v[14:15]
	v_pk_mul_f32 v[14:15], v[4:5], v[18:19] op_sel_hi:[1,0]
	v_cvt_pk_bf16_f32 v8, v8, v9
	v_exp_f32_e32 v14, v14
	v_exp_f32_e32 v15, v15
	v_pk_mul_f32 v[12:13], v[16:17], v[12:13] op_sel_hi:[0,1]
	v_pk_mul_f32 v[10:11], v[10:11], v[12:13]
	v_pk_mul_f32 v[12:13], v[6:7], v[18:19] op_sel_hi:[1,0]
	v_cvt_pk_bf16_f32 v9, v10, v11
	v_exp_f32_e32 v12, v12
	v_exp_f32_e32 v13, v13
	v_pk_add_f32 v[10:11], v[14:15], 1.0 op_sel_hi:[1,0]
	v_pk_add_f32 v[4:5], v[12:13], 1.0 op_sel_hi:[1,0]
	v_rcp_f32_e32 v10, v10
	v_rcp_f32_e32 v11, v11
	v_rcp_f32_e32 v4, v4
	v_rcp_f32_e32 v5, v5
	v_pk_mul_f32 v[6:7], v[16:17], v[10:11] op_sel_hi:[0,1]
	v_pk_mul_f32 v[0:1], v[0:1], v[6:7]
	s_nop 0
	v_cvt_pk_bf16_f32 v10, v0, v1
	v_pk_mul_f32 v[0:1], v[16:17], v[4:5] op_sel_hi:[0,1]
	v_pk_mul_f32 v[0:1], v[2:3], v[0:1]
	s_nop 0
	v_cvt_pk_bf16_f32 v11, v0, v1
	v_mad_i64_i32 v[0:1], s[0:1], v139, s49, v[120:121]
	v_lshl_add_u64 v[0:1], v[0:1], 0, v[116:117]
	s_mov_b64 s[0:1], -1
	global_store_dwordx4 v[0:1], v[8:11], off
	s_cbranch_vccnz .LBB0_805
	s_andn2_b64 vcc, exec, s[6:7]
	s_cbranch_vccnz .LBB0_804
	s_barrier
	s_branch .LBB0_804

.LBB0_890:
	s_add_u32 s14, s14, 0xb0080
	s_addc_u32 s15, s15, 0
	s_add_u32 s53, s2, 0x100
	s_addc_u32 s54, s3, 0
	s_mov_b32 s55, -2
	s_waitcnt lgkmcnt(0)
	s_waitcnt vmcnt(0)
	ds_read_b128 v[128:131], v165
	ds_read_b128 v[132:135], v165 offset:1024
	ds_read_b128 v[136:139], v165 offset:2048
	ds_read_b128 v[156:159], v165 offset:3072
	ds_read_b128 v[172:175], v166
	ds_read_b128 v[176:179], v166 offset:1024
	ds_read_b128 v[180:183], v166 offset:2048
	ds_read_b128 v[184:187], v166 offset:3072
	s_add_u32 s2, s14, 0xfff50080
	s_addc_u32 s3, s15, -1
	s_cmp_eq_u32 s55, 40
	s_cselect_b32 s23, s1, s3
	s_cselect_b32 s22, s0, s2
	s_cselect_b32 s3, s21, s54
	s_cselect_b32 s2, s20, s53
	v_lshl_add_u64 v[160:161], s[14:15], 0, v[140:141]
	s_add_i32 m0, s27, 0xc000
	ds_read_b128 v[188:191], v167
	ds_read_b128 v[196:199], v167 offset:1024
	ds_read_b128 v[200:203], v167 offset:2048
	ds_read_b128 v[204:207], v167 offset:3072
	ds_read_b128 v[208:211], v167 offset:4096
	ds_read_b128 v[212:215], v167 offset:5120
	ds_read_b128 v[216:219], v167 offset:6144
	ds_read_b128 v[220:223], v167 offset:7168
	global_load_lds_dwordx4 v[160:161], off
	v_lshl_add_u64 v[160:161], s[14:15], 0, v[142:143]
	s_add_i32 m0, s27, 0xe000
	s_nop 0
	global_load_lds_dwordx4 v[160:161], off
	s_waitcnt vmcnt(8)
	s_waitcnt lgkmcnt(0)
	s_barrier
	s_setprio 1
	s_waitcnt lgkmcnt(0)
	v_mfma_f32_16x16x32_bf16 v[124:127], v[128:131], v[188:191], 0
	v_mfma_f32_16x16x32_bf16 v[120:123], v[136:139], v[188:191], 0
	v_mfma_f32_16x16x32_bf16 v[108:111], v[128:131], v[200:203], 0
	v_mfma_f32_16x16x32_bf16 v[104:107], v[136:139], v[200:203], 0
	v_mfma_f32_16x16x32_bf16 v[92:95], v[128:131], v[208:211], 0
	v_mfma_f32_16x16x32_bf16 v[88:91], v[136:139], v[208:211], 0
	v_mfma_f32_16x16x32_bf16 v[76:79], v[128:131], v[216:219], 0
	v_mfma_f32_16x16x32_bf16 v[72:75], v[136:139], v[216:219], 0
	v_mfma_f32_16x16x32_bf16 v[124:127], v[132:135], v[196:199], v[124:127]
	v_mfma_f32_16x16x32_bf16 v[120:123], v[156:159], v[196:199], v[120:123]
	v_mfma_f32_16x16x32_bf16 v[108:111], v[132:135], v[204:207], v[108:111]
	v_mfma_f32_16x16x32_bf16 v[104:107], v[156:159], v[204:207], v[104:107]
	v_mfma_f32_16x16x32_bf16 v[92:95], v[132:135], v[212:215], v[92:95]
	v_mfma_f32_16x16x32_bf16 v[88:91], v[156:159], v[212:215], v[88:91]
	v_mfma_f32_16x16x32_bf16 v[76:79], v[132:135], v[220:223], v[76:79]
	v_mfma_f32_16x16x32_bf16 v[72:75], v[156:159], v[220:223], v[72:75]
	s_setprio 0
	s_setprio 1
	v_mfma_f32_16x16x32_bf16 v[116:119], v[172:175], v[188:191], 0
	v_mfma_f32_16x16x32_bf16 v[112:115], v[180:183], v[188:191], 0
	v_mfma_f32_16x16x32_bf16 v[100:103], v[172:175], v[200:203], 0
	v_mfma_f32_16x16x32_bf16 v[96:99], v[180:183], v[200:203], 0
	v_mfma_f32_16x16x32_bf16 v[84:87], v[172:175], v[208:211], 0
	v_mfma_f32_16x16x32_bf16 v[80:83], v[180:183], v[208:211], 0
	v_mfma_f32_16x16x32_bf16 v[68:71], v[172:175], v[216:219], 0
	v_mfma_f32_16x16x32_bf16 v[64:67], v[180:183], v[216:219], 0
	v_mfma_f32_16x16x32_bf16 v[116:119], v[176:179], v[196:199], v[116:119]
	v_mfma_f32_16x16x32_bf16 v[112:115], v[184:187], v[196:199], v[112:115]
	v_mfma_f32_16x16x32_bf16 v[100:103], v[176:179], v[204:207], v[100:103]
	v_mfma_f32_16x16x32_bf16 v[96:99], v[184:187], v[204:207], v[96:99]
	v_mfma_f32_16x16x32_bf16 v[84:87], v[176:179], v[212:215], v[84:87]
	v_mfma_f32_16x16x32_bf16 v[80:83], v[184:187], v[212:215], v[80:83]
	v_mfma_f32_16x16x32_bf16 v[68:71], v[176:179], v[220:223], v[68:71]
	v_mfma_f32_16x16x32_bf16 v[64:67], v[184:187], v[220:223], v[64:67]
	s_setprio 0
	s_barrier
	s_add_i32 s56, s43, s26
	v_lshl_add_u64 v[160:161], s[2:3], 0, v[150:151]
	s_mov_b32 m0, s56
	ds_read_b128 v[188:191], v167 offset:16384
	ds_read_b128 v[196:199], v167 offset:17408
	ds_read_b128 v[200:203], v167 offset:18432
	ds_read_b128 v[204:207], v167 offset:19456
	ds_read_b128 v[208:211], v167 offset:20480
	ds_read_b128 v[212:215], v167 offset:21504
	ds_read_b128 v[216:219], v167 offset:22528
	ds_read_b128 v[220:223], v167 offset:23552
	global_load_lds_dwordx4 v[160:161], off
	s_add_i32 m0, s56, 0x2000
	s_add_u32 s56, s2, 0xb0000
	v_lshl_add_u64 v[192:193], s[2:3], 0, v[154:155]
	s_addc_u32 s57, s3, 0
	s_add_i32 s58, s44, s26
	global_load_lds_dwordx4 v[192:193], off
	v_lshl_add_u64 v[224:225], s[56:57], 0, v[150:151]
	s_mov_b32 m0, s58
	v_lshl_add_u64 v[226:227], s[22:23], 0, v[152:153]
	global_load_lds_dwordx4 v[224:225], off
	v_lshl_add_u64 v[224:225], s[56:57], 0, v[154:155]
	s_add_i32 m0, s58, 0x2000
	s_nop 0
	global_load_lds_dwordx4 v[224:225], off
	v_lshl_add_u64 v[224:225], s[22:23], 0, v[148:149]
	s_mov_b32 m0, s27
	s_nop 0
	global_load_lds_dwordx4 v[224:225], off
	s_mov_b32 m0, s28
	s_nop 0
	global_load_lds_dwordx4 v[226:227], off
	s_waitcnt vmcnt(8)
	s_waitcnt lgkmcnt(0)
	s_barrier
	s_setprio 1
	s_waitcnt lgkmcnt(0)
	v_mfma_f32_16x16x32_bf16 v[60:63], v[128:131], v[188:191], 0
	v_mfma_f32_16x16x32_bf16 v[56:59], v[136:139], v[188:191], 0
	v_mfma_f32_16x16x32_bf16 v[44:47], v[128:131], v[200:203], 0
	v_mfma_f32_16x16x32_bf16 v[40:43], v[136:139], v[200:203], 0
	v_mfma_f32_16x16x32_bf16 v[28:31], v[128:131], v[208:211], 0
	v_mfma_f32_16x16x32_bf16 v[24:27], v[136:139], v[208:211], 0
	v_mfma_f32_16x16x32_bf16 v[12:15], v[128:131], v[216:219], 0
	v_mfma_f32_16x16x32_bf16 v[8:11], v[136:139], v[216:219], 0
	v_mfma_f32_16x16x32_bf16 v[60:63], v[132:135], v[196:199], v[60:63]
	v_mfma_f32_16x16x32_bf16 v[56:59], v[156:159], v[196:199], v[56:59]
	v_mfma_f32_16x16x32_bf16 v[44:47], v[132:135], v[204:207], v[44:47]
	v_mfma_f32_16x16x32_bf16 v[40:43], v[156:159], v[204:207], v[40:43]
	v_mfma_f32_16x16x32_bf16 v[28:31], v[132:135], v[212:215], v[28:31]
	v_mfma_f32_16x16x32_bf16 v[24:27], v[156:159], v[212:215], v[24:27]
	v_mfma_f32_16x16x32_bf16 v[12:15], v[132:135], v[220:223], v[12:15]
	v_mfma_f32_16x16x32_bf16 v[8:11], v[156:159], v[220:223], v[8:11]
	s_setprio 0
	s_setprio 1
	v_mfma_f32_16x16x32_bf16 v[52:55], v[172:175], v[188:191], 0
	v_mfma_f32_16x16x32_bf16 v[48:51], v[180:183], v[188:191], 0
	v_mfma_f32_16x16x32_bf16 v[36:39], v[172:175], v[200:203], 0
	v_mfma_f32_16x16x32_bf16 v[32:35], v[180:183], v[200:203], 0
	v_mfma_f32_16x16x32_bf16 v[20:23], v[172:175], v[208:211], 0
	v_mfma_f32_16x16x32_bf16 v[16:19], v[180:183], v[208:211], 0
	v_mfma_f32_16x16x32_bf16 v[4:7], v[172:175], v[216:219], 0
	v_mfma_f32_16x16x32_bf16 v[0:3], v[180:183], v[216:219], 0
	v_mfma_f32_16x16x32_bf16 v[52:55], v[176:179], v[196:199], v[52:55]
	v_mfma_f32_16x16x32_bf16 v[48:51], v[184:187], v[196:199], v[48:51]
	v_mfma_f32_16x16x32_bf16 v[36:39], v[176:179], v[204:207], v[36:39]
	v_mfma_f32_16x16x32_bf16 v[32:35], v[184:187], v[204:207], v[32:35]
	v_mfma_f32_16x16x32_bf16 v[20:23], v[176:179], v[212:215], v[20:23]
	v_mfma_f32_16x16x32_bf16 v[16:19], v[184:187], v[212:215], v[16:19]
	v_mfma_f32_16x16x32_bf16 v[4:7], v[176:179], v[220:223], v[4:7]
	v_mfma_f32_16x16x32_bf16 v[0:3], v[184:187], v[220:223], v[0:3]
	s_setprio 0
	s_barrier
	s_add_i32 s56, 0, 0x18000
	s_add_i32 s57, 0, 0x1c000
	v_add_u32_e32 v156, s56, v162
	v_add_u32_e32 v169, s57, v162
	ds_read_b128 v[128:131], v156
	ds_read_b128 v[132:135], v156 offset:1024
	ds_read_b128 v[136:139], v156 offset:2048
	ds_read_b128 v[156:159], v156 offset:3072
	ds_read_b128 v[172:175], v169
	ds_read_b128 v[176:179], v169 offset:1024
	ds_read_b128 v[180:183], v169 offset:2048
	ds_read_b128 v[184:187], v169 offset:3072
	s_add_u32 s22, s22, 0xb0000
	s_addc_u32 s23, s23, 0
	s_mov_b32 m0, s29
	v_lshl_add_u64 v[228:229], s[22:23], 0, v[148:149]
	ds_read_b128 v[188:191], v167 offset:32768
	ds_read_b128 v[196:199], v167 offset:33792
	ds_read_b128 v[200:203], v167 offset:34816
	ds_read_b128 v[204:207], v167 offset:35840
	ds_read_b128 v[208:211], v167 offset:36864
	ds_read_b128 v[212:215], v167 offset:37888
	ds_read_b128 v[216:219], v167 offset:38912
	ds_read_b128 v[220:223], v167 offset:39936
	global_load_lds_dwordx4 v[228:229], off
	v_lshl_add_u64 v[228:229], s[22:23], 0, v[152:153]
	s_mov_b32 m0, s30
	s_nop 0
	global_load_lds_dwordx4 v[228:229], off
	s_waitcnt vmcnt(8)
	s_waitcnt lgkmcnt(0)
	s_barrier
	s_setprio 1
	s_waitcnt lgkmcnt(0)
	v_mfma_f32_16x16x32_bf16 v[124:127], v[128:131], v[188:191], v[124:127]
	v_mfma_f32_16x16x32_bf16 v[120:123], v[136:139], v[188:191], v[120:123]
	v_mfma_f32_16x16x32_bf16 v[108:111], v[128:131], v[200:203], v[108:111]
	v_mfma_f32_16x16x32_bf16 v[104:107], v[136:139], v[200:203], v[104:107]
	v_mfma_f32_16x16x32_bf16 v[92:95], v[128:131], v[208:211], v[92:95]
	v_mfma_f32_16x16x32_bf16 v[88:91], v[136:139], v[208:211], v[88:91]
	v_mfma_f32_16x16x32_bf16 v[76:79], v[128:131], v[216:219], v[76:79]
	v_mfma_f32_16x16x32_bf16 v[72:75], v[136:139], v[216:219], v[72:75]
	v_mfma_f32_16x16x32_bf16 v[124:127], v[132:135], v[196:199], v[124:127]
	v_mfma_f32_16x16x32_bf16 v[120:123], v[156:159], v[196:199], v[120:123]
	v_mfma_f32_16x16x32_bf16 v[108:111], v[132:135], v[204:207], v[108:111]
	v_mfma_f32_16x16x32_bf16 v[104:107], v[156:159], v[204:207], v[104:107]
	v_mfma_f32_16x16x32_bf16 v[92:95], v[132:135], v[212:215], v[92:95]
	v_mfma_f32_16x16x32_bf16 v[88:91], v[156:159], v[212:215], v[88:91]
	v_mfma_f32_16x16x32_bf16 v[76:79], v[132:135], v[220:223], v[76:79]
	v_mfma_f32_16x16x32_bf16 v[72:75], v[156:159], v[220:223], v[72:75]
	s_setprio 0
	s_setprio 1
	v_mfma_f32_16x16x32_bf16 v[116:119], v[172:175], v[188:191], v[116:119]
	v_mfma_f32_16x16x32_bf16 v[112:115], v[180:183], v[188:191], v[112:115]
	v_mfma_f32_16x16x32_bf16 v[100:103], v[172:175], v[200:203], v[100:103]
	v_mfma_f32_16x16x32_bf16 v[96:99], v[180:183], v[200:203], v[96:99]
	v_mfma_f32_16x16x32_bf16 v[84:87], v[172:175], v[208:211], v[84:87]
	v_mfma_f32_16x16x32_bf16 v[80:83], v[180:183], v[208:211], v[80:83]
	v_mfma_f32_16x16x32_bf16 v[68:71], v[172:175], v[216:219], v[68:71]
	v_mfma_f32_16x16x32_bf16 v[64:67], v[180:183], v[216:219], v[64:67]
	v_mfma_f32_16x16x32_bf16 v[116:119], v[176:179], v[196:199], v[116:119]
	v_mfma_f32_16x16x32_bf16 v[112:115], v[184:187], v[196:199], v[112:115]
	v_mfma_f32_16x16x32_bf16 v[100:103], v[176:179], v[204:207], v[100:103]
	v_mfma_f32_16x16x32_bf16 v[96:99], v[184:187], v[204:207], v[96:99]
	v_mfma_f32_16x16x32_bf16 v[84:87], v[176:179], v[212:215], v[84:87]
	v_mfma_f32_16x16x32_bf16 v[80:83], v[184:187], v[212:215], v[80:83]
	v_mfma_f32_16x16x32_bf16 v[68:71], v[176:179], v[220:223], v[68:71]
	v_mfma_f32_16x16x32_bf16 v[64:67], v[184:187], v[220:223], v[64:67]
	s_setprio 0
	s_barrier
	s_add_i32 s22, s56, s26
	v_lshl_add_u64 v[160:161], v[160:161], 0, s[12:13]
	s_mov_b32 m0, s22
	ds_read_b128 v[188:191], v167 offset:49152
	ds_read_b128 v[196:199], v167 offset:50176
	ds_read_b128 v[200:203], v167 offset:51200
	ds_read_b128 v[204:207], v167 offset:52224
	ds_read_b128 v[208:211], v167 offset:53248
	ds_read_b128 v[212:215], v167 offset:54272
	ds_read_b128 v[216:219], v167 offset:55296
	ds_read_b128 v[220:223], v167 offset:56320
	global_load_lds_dwordx4 v[160:161], off
	s_add_i32 m0, s22, 0x2000
	s_add_u32 s2, s2, 0xb0080
	v_lshl_add_u64 v[160:161], v[192:193], 0, s[12:13]
	s_addc_u32 s3, s3, 0
	s_add_i32 s22, s57, s26
	global_load_lds_dwordx4 v[160:161], off
	v_lshl_add_u64 v[160:161], s[2:3], 0, v[150:151]
	s_mov_b32 m0, s22
	s_nop 0
	global_load_lds_dwordx4 v[160:161], off
	v_lshl_add_u64 v[160:161], s[2:3], 0, v[154:155]
	s_add_i32 m0, s22, 0x2000
	s_nop 0
	global_load_lds_dwordx4 v[160:161], off
	v_lshl_add_u64 v[160:161], v[224:225], 0, s[12:13]
	s_mov_b32 m0, s36
	s_nop 0
	global_load_lds_dwordx4 v[160:161], off
	v_lshl_add_u64 v[160:161], v[226:227], 0, s[12:13]
	s_mov_b32 m0, s37
	s_nop 0
	global_load_lds_dwordx4 v[160:161], off
	s_waitcnt vmcnt(8)
	s_waitcnt lgkmcnt(0)
	s_barrier
	s_setprio 1
	s_waitcnt lgkmcnt(0)
	v_mfma_f32_16x16x32_bf16 v[60:63], v[128:131], v[188:191], v[60:63]
	v_mfma_f32_16x16x32_bf16 v[56:59], v[136:139], v[188:191], v[56:59]
	v_mfma_f32_16x16x32_bf16 v[44:47], v[128:131], v[200:203], v[44:47]
	v_mfma_f32_16x16x32_bf16 v[40:43], v[136:139], v[200:203], v[40:43]
	v_mfma_f32_16x16x32_bf16 v[28:31], v[128:131], v[208:211], v[28:31]
	v_mfma_f32_16x16x32_bf16 v[24:27], v[136:139], v[208:211], v[24:27]
	v_mfma_f32_16x16x32_bf16 v[12:15], v[128:131], v[216:219], v[12:15]
	v_mfma_f32_16x16x32_bf16 v[8:11], v[136:139], v[216:219], v[8:11]
	v_mfma_f32_16x16x32_bf16 v[60:63], v[132:135], v[196:199], v[60:63]
	v_mfma_f32_16x16x32_bf16 v[56:59], v[156:159], v[196:199], v[56:59]
	v_mfma_f32_16x16x32_bf16 v[44:47], v[132:135], v[204:207], v[44:47]
	v_mfma_f32_16x16x32_bf16 v[40:43], v[156:159], v[204:207], v[40:43]
	v_mfma_f32_16x16x32_bf16 v[28:31], v[132:135], v[212:215], v[28:31]
	v_mfma_f32_16x16x32_bf16 v[24:27], v[156:159], v[212:215], v[24:27]
	v_mfma_f32_16x16x32_bf16 v[12:15], v[132:135], v[220:223], v[12:15]
	v_mfma_f32_16x16x32_bf16 v[8:11], v[156:159], v[220:223], v[8:11]
	s_setprio 0
	s_setprio 1
	v_mfma_f32_16x16x32_bf16 v[52:55], v[172:175], v[188:191], v[52:55]
	v_mfma_f32_16x16x32_bf16 v[48:51], v[180:183], v[188:191], v[48:51]
	v_mfma_f32_16x16x32_bf16 v[36:39], v[172:175], v[200:203], v[36:39]
	v_mfma_f32_16x16x32_bf16 v[32:35], v[180:183], v[200:203], v[32:35]
	v_mfma_f32_16x16x32_bf16 v[20:23], v[172:175], v[208:211], v[20:23]
	v_mfma_f32_16x16x32_bf16 v[16:19], v[180:183], v[208:211], v[16:19]
	v_mfma_f32_16x16x32_bf16 v[4:7], v[172:175], v[216:219], v[4:7]
	v_mfma_f32_16x16x32_bf16 v[0:3], v[180:183], v[216:219], v[0:3]
	v_mfma_f32_16x16x32_bf16 v[52:55], v[176:179], v[196:199], v[52:55]
	v_mfma_f32_16x16x32_bf16 v[48:51], v[184:187], v[196:199], v[48:51]
	v_mfma_f32_16x16x32_bf16 v[36:39], v[176:179], v[204:207], v[36:39]
	v_mfma_f32_16x16x32_bf16 v[32:35], v[184:187], v[204:207], v[32:35]
	v_mfma_f32_16x16x32_bf16 v[20:23], v[176:179], v[212:215], v[20:23]
	v_mfma_f32_16x16x32_bf16 v[16:19], v[184:187], v[212:215], v[16:19]
	v_mfma_f32_16x16x32_bf16 v[4:7], v[176:179], v[220:223], v[4:7]
	v_mfma_f32_16x16x32_bf16 v[0:3], v[184:187], v[220:223], v[0:3]
	s_setprio 0
	s_barrier
	s_add_i32 s55, s55, 2
	s_add_u32 s14, s14, 0x100
	s_addc_u32 s15, s15, 0
	s_add_u32 s53, s53, 0x100
	s_addc_u32 s54, s54, 0
	s_cmp_gt_u32 s55, 41
	s_cbranch_scc1 .Lgemm_kdone_6
